# top-k selection: the quad shuffles are fused into the max (v_max_u32_dpp), 94 VALU off the dependent chain per item
# speedup vs baseline: 1.0033x; 1.0011x over previous
.LBB0_729:
	s_waitcnt vmcnt(0)
	s_barrier
	ds_write_b128 v98, v[48:51]
	ds_write_b128 v98, v[44:47] offset:4352
	ds_write_b128 v98, v[36:39] offset:8704
	ds_write_b128 v98, v[40:43] offset:13056
	ds_write_b128 v98, v[28:31] offset:17408
	ds_write_b128 v98, v[32:35] offset:21760
	ds_write_b128 v98, v[20:23] offset:26112
	ds_write_b128 v98, v[24:27] offset:30464
	s_waitcnt lgkmcnt(0)
	s_barrier
	ds_read_b128 v[20:23], v99
	ds_read_b128 v[24:27], v99 offset:4352
	ds_read_b128 v[28:31], v99 offset:8704
	ds_read_b128 v[32:35], v99 offset:13056
	ds_read_b128 v[36:39], v99 offset:17408
	ds_read_b128 v[40:43], v99 offset:21760
	ds_read_b128 v[44:47], v99 offset:26112
	ds_read_b128 v[48:51], v99 offset:30464
	s_waitcnt lgkmcnt(7)
	v_mfma_f32_16x16x32_bf16 v[20:23], v[16:19], v[20:23], 0
	s_and_b32 s24, s59, 7
	s_lshl_b32 s26, s24, 16
	s_add_u32 s26, s18, s26
	s_waitcnt lgkmcnt(6)
	v_mfma_f32_16x16x32_bf16 v[24:27], v[16:19], v[24:27], 0
	s_addc_u32 s27, s19, 0
	s_and_b32 s34, s3, 0xffffffc0
	s_lshl_b32 s24, s24, 9
	s_waitcnt lgkmcnt(5)
	v_mfma_f32_16x16x32_bf16 v[28:31], v[16:19], v[28:31], 0
	s_waitcnt lgkmcnt(4)
	v_mfma_f32_16x16x32_bf16 v[32:35], v[16:19], v[32:35], 0
	s_waitcnt lgkmcnt(3)
	v_mfma_f32_16x16x32_bf16 v[36:39], v[16:19], v[36:39], 0
	s_waitcnt lgkmcnt(2)
	v_mfma_f32_16x16x32_bf16 v[40:43], v[16:19], v[40:43], 0
	s_waitcnt lgkmcnt(1)
	v_mfma_f32_16x16x32_bf16 v[44:47], v[16:19], v[44:47], 0
	s_waitcnt lgkmcnt(0)
	v_mfma_f32_16x16x32_bf16 v[16:19], v[16:19], v[48:51], 0
	ds_read_b128 v[48:51], v88 offset:64
	ds_read_b128 v[62:65], v88 offset:128
	s_waitcnt lgkmcnt(1)
	v_mfma_f32_16x16x32_bf16 v[20:23], v[12:15], v[48:51], v[20:23]
	ds_read_b128 v[48:51], v89 offset:64
	ds_read_b128 v[66:69], v88 offset:192
	s_waitcnt lgkmcnt(2)
	v_mfma_f32_16x16x32_bf16 v[20:23], v[8:11], v[62:65], v[20:23]
	s_waitcnt lgkmcnt(1)
	v_mfma_f32_16x16x32_bf16 v[24:27], v[12:15], v[48:51], v[24:27]
	ds_read_b128 v[48:51], v90 offset:64
	ds_read_b128 v[72:75], v91 offset:64
	ds_read_b128 v[76:79], v90 offset:128
	s_waitcnt lgkmcnt(2)
	v_mfma_f32_16x16x32_bf16 v[28:31], v[12:15], v[48:51], v[28:31]
	ds_read_b128 v[48:51], v92 offset:64
	ds_read_b128 v[102:105], v92 offset:128
	ds_read_b128 v[106:109], v90 offset:192
	v_mfma_f32_16x16x32_bf16 v[20:23], v[4:7], v[66:69], v[20:23]
	s_waitcnt lgkmcnt(4)
	v_mfma_f32_16x16x32_bf16 v[32:35], v[12:15], v[72:75], v[32:35]
	ds_read_b128 v[72:75], v94 offset:64
	ds_read_b128 v[110:113], v94 offset:128
	ds_read_b128 v[114:117], v89 offset:128
	ds_read_b128 v[118:121], v89 offset:192
	s_nop 1
	v_not_b32_e32 v59, v20
	v_or_b32_e32 v61, 0x80000000, v20
	s_waitcnt lgkmcnt(6)
	v_mfma_f32_16x16x32_bf16 v[36:39], v[12:15], v[48:51], v[36:39]
	ds_read_b128 v[48:51], v91 offset:128
	ds_read_b128 v[122:125], v91 offset:192
	ds_read_b128 v[126:129], v93 offset:64
	ds_read_b128 v[130:133], v92 offset:192
	ds_read_b128 v[62:65], v93 offset:128
	ds_read_b128 v[134:137], v93 offset:192
	ds_read_b128 v[138:141], v95 offset:64
	ds_read_b128 v[146:149], v94 offset:192
	v_cmp_gt_i32_e32 vcc, 0, v20
	s_waitcnt lgkmcnt(5)
	v_mfma_f32_16x16x32_bf16 v[40:43], v[12:15], v[126:129], v[40:43]
	v_cndmask_b32_e32 v20, v61, v59, vcc
	v_and_b32_e32 v20, 0xffffff80, v20
	v_bitop3_b32 v59, v71, s44, v20 bitop3:0x36
	v_mfma_f32_16x16x32_bf16 v[44:47], v[12:15], v[72:75], v[44:47]
	v_not_b32_e32 v20, v21
	v_cmp_gt_i32_e32 vcc, 0, v21
	ds_read_b128 v[66:69], v95 offset:128
	ds_read_b128 v[150:153], v95 offset:192
	s_waitcnt lgkmcnt(3)
	v_mfma_f32_16x16x32_bf16 v[12:15], v[12:15], v[138:141], v[16:19]
	s_nop 2
	v_or_b32_e32 v16, 0x80000000, v21
	v_cndmask_b32_e32 v20, v16, v20, vcc
	v_mfma_f32_16x16x32_bf16 v[16:19], v[8:11], v[114:117], v[24:27]
	v_and_b32_e32 v20, 0xffffff80, v20
	v_bitop3_b32 v61, v71, s44, v20 bitop3:0x36
	v_not_b32_e32 v20, v22
	v_or_b32_e32 v21, 0x80000000, v22
	v_cmp_gt_i32_e32 vcc, 0, v22
	v_mfma_f32_16x16x32_bf16 v[16:19], v[4:7], v[118:121], v[16:19]
	s_nop 0
	v_cndmask_b32_e32 v20, v21, v20, vcc
	v_and_b32_e32 v20, 0xffffff80, v20
	v_mfma_f32_16x16x32_bf16 v[24:27], v[8:11], v[76:79], v[28:31]
	v_or_b32_e32 v21, 0x80000000, v23
	v_cmp_gt_i32_e32 vcc, 0, v23
	v_add_u32_e32 v77, 0x8800, v100
	v_mfma_f32_16x16x32_bf16 v[28:31], v[8:11], v[48:51], v[32:35]
	v_bitop3_b32 v48, v71, s44, v20 bitop3:0x36
	v_not_b32_e32 v20, v23
	v_cndmask_b32_e32 v20, v21, v20, vcc
	v_mfma_f32_16x16x32_bf16 v[32:35], v[8:11], v[102:105], v[36:39]
	v_cmp_gt_i32_e32 vcc, 0, v16
	v_and_b32_e32 v20, 0xffffff80, v20
	v_bitop3_b32 v49, v71, s44, v20 bitop3:0x36
	v_not_b32_e32 v36, v16
	v_or_b32_e32 v37, 0x80000000, v16
	v_cndmask_b32_e32 v16, v37, v36, vcc
	v_and_b32_e32 v16, 0xffffff80, v16
	v_bitop3_b32 v16, v71, s45, v16 bitop3:0x36
	v_mfma_f32_16x16x32_bf16 v[20:23], v[8:11], v[62:65], v[40:43]
	ds_write2_b32 v77, v59, v16 offset1:16
	v_not_b32_e32 v16, v17
	v_cmp_gt_i32_e32 vcc, 0, v17
	v_or_b32_e32 v40, 0x80000000, v17
	v_or_b32_e32 v17, 0x80000000, v18
	v_cndmask_b32_e32 v16, v40, v16, vcc
	v_and_b32_e32 v16, 0xffffff80, v16
	v_bitop3_b32 v16, v71, s45, v16 bitop3:0x36
	ds_write2_b32 v77, v61, v16 offset0:132 offset1:148
	v_not_b32_e32 v16, v18
	v_cmp_gt_i32_e32 vcc, 0, v18
	v_mfma_f32_16x16x32_bf16 v[36:39], v[8:11], v[110:113], v[44:47]
	v_add_u32_e32 v78, 0x8c00, v100
	v_cndmask_b32_e32 v16, v17, v16, vcc
	v_and_b32_e32 v16, 0xffffff80, v16
	s_waitcnt lgkmcnt(3)
	v_mfma_f32_16x16x32_bf16 v[8:11], v[8:11], v[66:69], v[12:15]
	v_bitop3_b32 v16, v71, s45, v16 bitop3:0x36
	ds_write2_b32 v78, v48, v16 offset0:8 offset1:24
	v_not_b32_e32 v16, v19
	v_mfma_f32_16x16x32_bf16 v[12:15], v[4:7], v[106:109], v[24:27]
	v_or_b32_e32 v17, 0x80000000, v19
	v_cmp_gt_i32_e32 vcc, 0, v19
	v_mov_b32_e32 v59, v53
	v_mfma_f32_16x16x32_bf16 v[24:27], v[4:7], v[122:125], v[28:31]
	v_mov_b32_e32 v61, v53
	v_mfma_f32_16x16x32_bf16 v[28:31], v[4:7], v[130:133], v[32:35]
	v_mfma_f32_16x16x32_bf16 v[20:23], v[4:7], v[134:137], v[20:23]
	v_mfma_f32_16x16x32_bf16 v[32:35], v[4:7], v[146:149], v[36:39]
	s_waitcnt lgkmcnt(3)
	v_mfma_f32_16x16x32_bf16 v[4:7], v[4:7], v[150:153], v[8:11]
	s_nop 2
	v_cndmask_b32_e32 v8, v17, v16, vcc
	v_and_b32_e32 v8, 0xffffff80, v8
	v_bitop3_b32 v8, v71, s45, v8 bitop3:0x36
	ds_write2_b32 v78, v49, v8 offset0:140 offset1:156
	v_not_b32_e32 v8, v12
	v_or_b32_e32 v9, 0x80000000, v12
	v_cmp_gt_i32_e32 vcc, 0, v12
	v_or_b32_e32 v10, 0x80000000, v13
	v_or_b32_e32 v11, 0x80000000, v14
	v_cndmask_b32_e32 v8, v9, v8, vcc
	v_not_b32_e32 v9, v13
	v_cmp_gt_i32_e32 vcc, 0, v13
	v_or_b32_e32 v12, 0x80000000, v15
	v_or_b32_e32 v13, 0x80000000, v24
	v_cndmask_b32_e32 v9, v10, v9, vcc
	v_not_b32_e32 v10, v14
	v_cmp_gt_i32_e32 vcc, 0, v14
	v_and_b32_e32 v8, 0xffffff80, v8
	v_bitop3_b32 v8, v71, s48, v8 bitop3:0x36
	v_cndmask_b32_e32 v10, v11, v10, vcc
	v_not_b32_e32 v11, v15
	v_cmp_gt_i32_e32 vcc, 0, v15
	v_and_b32_e32 v9, 0xffffff80, v9
	v_bitop3_b32 v9, v71, s48, v9 bitop3:0x36
	v_cndmask_b32_e32 v11, v12, v11, vcc
	v_not_b32_e32 v12, v24
	v_cmp_gt_i32_e32 vcc, 0, v24
	v_and_b32_e32 v10, 0xffffff80, v10
	v_bitop3_b32 v10, v71, s48, v10 bitop3:0x36
	v_cndmask_b32_e32 v12, v13, v12, vcc
	v_and_b32_e32 v12, 0xffffff80, v12
	v_bitop3_b32 v12, v71, s49, v12 bitop3:0x36
	ds_write2_b32 v77, v8, v12 offset0:32 offset1:48
	v_not_b32_e32 v8, v25
	v_or_b32_e32 v12, 0x80000000, v25
	v_cmp_gt_i32_e32 vcc, 0, v25
	v_and_b32_e32 v11, 0xffffff80, v11
	v_bitop3_b32 v11, v71, s48, v11 bitop3:0x36
	v_cndmask_b32_e32 v8, v12, v8, vcc
	v_and_b32_e32 v8, 0xffffff80, v8
	v_bitop3_b32 v8, v71, s49, v8 bitop3:0x36
	ds_write2_b32 v77, v9, v8 offset0:164 offset1:180
	v_not_b32_e32 v8, v26
	v_or_b32_e32 v9, 0x80000000, v26
	v_cmp_gt_i32_e32 vcc, 0, v26
	v_or_b32_e32 v12, 0x80000000, v31
	v_or_b32_e32 v13, 0x80000000, v20
	v_cndmask_b32_e32 v8, v9, v8, vcc
	v_and_b32_e32 v8, 0xffffff80, v8
	v_bitop3_b32 v8, v71, s49, v8 bitop3:0x36
	ds_write2_b32 v78, v10, v8 offset0:40 offset1:56
	v_not_b32_e32 v8, v27
	v_or_b32_e32 v9, 0x80000000, v27
	v_cmp_gt_i32_e32 vcc, 0, v27
	v_or_b32_e32 v10, 0x80000000, v29
	s_nop 0
	v_cndmask_b32_e32 v8, v9, v8, vcc
	v_and_b32_e32 v8, 0xffffff80, v8
	v_bitop3_b32 v8, v71, s49, v8 bitop3:0x36
	ds_write2_b32 v78, v11, v8 offset0:172 offset1:188
	v_not_b32_e32 v8, v28
	v_or_b32_e32 v9, 0x80000000, v28
	v_cmp_gt_i32_e32 vcc, 0, v28
	v_or_b32_e32 v11, 0x80000000, v30
	s_nop 0
	v_cndmask_b32_e32 v8, v9, v8, vcc
	v_not_b32_e32 v9, v29
	v_cmp_gt_i32_e32 vcc, 0, v29
	v_and_b32_e32 v8, 0xffffff80, v8
	v_bitop3_b32 v8, v71, 63, v8 bitop3:0x36
	v_cndmask_b32_e32 v9, v10, v9, vcc
	v_not_b32_e32 v10, v30
	v_cmp_gt_i32_e32 vcc, 0, v30
	v_and_b32_e32 v9, 0xffffff80, v9
	v_bitop3_b32 v9, v71, 63, v9 bitop3:0x36
	v_cndmask_b32_e32 v10, v11, v10, vcc
	v_not_b32_e32 v11, v31
	v_cmp_gt_i32_e32 vcc, 0, v31
	v_and_b32_e32 v10, 0xffffff80, v10
	v_bitop3_b32 v10, v71, 63, v10 bitop3:0x36
	v_cndmask_b32_e32 v11, v12, v11, vcc
	v_not_b32_e32 v12, v20
	v_cmp_gt_i32_e32 vcc, 0, v20
	v_and_b32_e32 v11, 0xffffff80, v11
	v_bitop3_b32 v11, v71, 63, v11 bitop3:0x36
	v_cndmask_b32_e32 v12, v13, v12, vcc
	v_and_b32_e32 v12, 0xffffff80, v12
	v_bitop3_b32 v12, v71, 47, v12 bitop3:0x36
	ds_write2_b32 v77, v8, v12 offset0:64 offset1:80
	v_not_b32_e32 v8, v21
	v_or_b32_e32 v12, 0x80000000, v21
	v_cmp_gt_i32_e32 vcc, 0, v21
	v_or_b32_e32 v13, 0x80000000, v4
	s_nop 0
	v_cndmask_b32_e32 v8, v12, v8, vcc
	v_and_b32_e32 v8, 0xffffff80, v8
	v_bitop3_b32 v8, v71, 47, v8 bitop3:0x36
	ds_write2_b32 v77, v9, v8 offset0:196 offset1:212
	v_not_b32_e32 v8, v22
	v_or_b32_e32 v9, 0x80000000, v22
	v_cmp_gt_i32_e32 vcc, 0, v22
	v_or_b32_e32 v12, 0x80000000, v35
	s_nop 0
	v_cndmask_b32_e32 v8, v9, v8, vcc
	v_and_b32_e32 v8, 0xffffff80, v8
	v_bitop3_b32 v8, v71, 47, v8 bitop3:0x36
	ds_write2_b32 v78, v10, v8 offset0:72 offset1:88
	v_not_b32_e32 v8, v23
	v_or_b32_e32 v9, 0x80000000, v23
	v_cmp_gt_i32_e32 vcc, 0, v23
	v_or_b32_e32 v10, 0x80000000, v33
	s_nop 0
	v_cndmask_b32_e32 v8, v9, v8, vcc
	v_and_b32_e32 v8, 0xffffff80, v8
	v_bitop3_b32 v8, v71, 47, v8 bitop3:0x36
	ds_write2_b32 v78, v11, v8 offset0:204 offset1:220
	v_not_b32_e32 v8, v32
	v_or_b32_e32 v9, 0x80000000, v32
	v_cmp_gt_i32_e32 vcc, 0, v32
	v_or_b32_e32 v11, 0x80000000, v34
	s_nop 0
	v_cndmask_b32_e32 v8, v9, v8, vcc
	v_not_b32_e32 v9, v33
	v_cmp_gt_i32_e32 vcc, 0, v33
	v_and_b32_e32 v8, 0xffffff80, v8
	v_bitop3_b32 v8, v71, 31, v8 bitop3:0x36
	v_cndmask_b32_e32 v9, v10, v9, vcc
	v_not_b32_e32 v10, v34
	v_cmp_gt_i32_e32 vcc, 0, v34
	v_and_b32_e32 v9, 0xffffff80, v9
	v_bitop3_b32 v9, v71, 31, v9 bitop3:0x36
	v_cndmask_b32_e32 v10, v11, v10, vcc
	v_not_b32_e32 v11, v35
	v_cmp_gt_i32_e32 vcc, 0, v35
	v_and_b32_e32 v10, 0xffffff80, v10
	v_bitop3_b32 v10, v71, 31, v10 bitop3:0x36
	v_cndmask_b32_e32 v11, v12, v11, vcc
	v_not_b32_e32 v12, v4
	v_cmp_gt_i32_e32 vcc, 0, v4
	v_and_b32_e32 v11, 0xffffff80, v11
	v_bitop3_b32 v11, v71, 31, v11 bitop3:0x36
	v_cndmask_b32_e32 v4, v13, v12, vcc
	v_and_b32_e32 v4, 0xffffff80, v4
	v_bitop3_b32 v4, v71, 15, v4 bitop3:0x36
	ds_write2_b32 v77, v8, v4 offset0:96 offset1:112
	v_not_b32_e32 v4, v5
	v_or_b32_e32 v8, 0x80000000, v5
	v_cmp_gt_i32_e32 vcc, 0, v5
	v_or_b32_e32 v5, 0x80000000, v6
	s_nop 0
	v_cndmask_b32_e32 v4, v8, v4, vcc
	v_and_b32_e32 v4, 0xffffff80, v4
	v_bitop3_b32 v4, v71, 15, v4 bitop3:0x36
	ds_write2_b32 v77, v9, v4 offset0:228 offset1:244
	v_not_b32_e32 v4, v6
	v_cmp_gt_i32_e32 vcc, 0, v6
	s_nop 1
	v_cndmask_b32_e32 v4, v5, v4, vcc
	v_and_b32_e32 v4, 0xffffff80, v4
	v_bitop3_b32 v4, v71, 15, v4 bitop3:0x36
	ds_write2_b32 v78, v10, v4 offset0:104 offset1:120
	v_not_b32_e32 v4, v7
	v_or_b32_e32 v5, 0x80000000, v7
	v_cmp_gt_i32_e32 vcc, 0, v7
	s_nop 1
	v_cndmask_b32_e32 v4, v5, v4, vcc
	v_and_b32_e32 v4, 0xffffff80, v4
	v_bitop3_b32 v4, v71, 15, v4 bitop3:0x36
	ds_write2_b32 v78, v11, v4 offset0:236 offset1:252
	v_lshl_add_u64 v[4:5], s[26:27], 0, v[52:53]
	v_lshl_add_u64 v[4:5], v[4:5], 0, v[58:59]
	v_add_co_u32_e32 v6, vcc, s50, v4
	s_waitcnt lgkmcnt(0)
	s_nop 0
	v_addc_co_u32_e32 v7, vcc, 0, v5, vcc
	s_barrier
	global_load_dwordx4 v[16:19], v[6:7], off offset:-4096
	global_load_dwordx4 v[20:23], v[6:7], off
	v_add_co_u32_e32 v6, vcc, s51, v4
	s_nop 1
	v_addc_co_u32_e32 v7, vcc, 0, v5, vcc
	global_load_dwordx4 v[24:27], v[6:7], off offset:-4096
	global_load_dwordx4 v[28:31], v[6:7], off
	v_add_co_u32_e32 v6, vcc, s56, v4
	s_nop 1
	v_addc_co_u32_e32 v7, vcc, 0, v5, vcc
	v_add_co_u32_e32 v4, vcc, s57, v4
	global_load_dwordx4 v[36:39], v[6:7], off offset:-4096
	global_load_dwordx4 v[40:43], v[6:7], off
	v_addc_co_u32_e32 v5, vcc, 0, v5, vcc
	global_load_dwordx4 v[44:47], v[4:5], off offset:-4096
	global_load_dwordx4 v[48:51], v[4:5], off
	v_add_u32_e32 v4, s34, v84
	v_ashrrev_i32_e32 v5, 31, v4
	v_lshlrev_b64 v[4:5], 12, v[4:5]
	v_lshl_add_u64 v[4:5], s[16:17], 0, v[4:5]
	v_lshl_add_u64 v[4:5], v[4:5], 0, s[24:25]
	v_lshl_add_u64 v[4:5], v[4:5], 0, v[60:61]
	global_load_dwordx4 v[32:35], v[4:5], off offset:256
	global_load_dwordx4 v[12:15], v[4:5], off offset:320
	global_load_dwordx4 v[8:11], v[4:5], off offset:384
	s_nop 0
	global_load_dwordx4 v[4:7], v[4:5], off offset:448
	s_and_b32 s81, s80, 0x3ff
	s_lshl_b32 s81, s81, 16
	s_cmp_lt_u32 s80, 0x400
	s_cselect_b32 s82, s88, s96
	s_cselect_b32 s83, s89, s97
	s_mov_b32 s86, 0x42800000
	s_cselect_b32 s86, 0x43800000, s86
	s_cselect_b32 s87, 0, 0x400
	s_add_u32 s82, s82, s81
	s_addc_u32 s83, s83, 0
	s_lshr_b32 s81, s81, 1
	s_add_u32 s81, s81, s87
	s_add_u32 s84, s98, s81
	s_addc_u32 s85, s99, 0
	global_load_dwordx4 v[170:173], v234, s[82:83]
	s_add_u32 s82, s82, 0x1000
	s_addc_u32 s83, s83, 0
	global_load_dwordx4 v[174:177], v234, s[82:83]
	s_add_u32 s82, s82, 0x1000
	s_addc_u32 s83, s83, 0
	global_load_dwordx4 v[178:181], v234, s[82:83]
	s_add_u32 s82, s82, 0x1000
	s_addc_u32 s83, s83, 0
	global_load_dwordx4 v[182:185], v234, s[82:83]
	s_add_u32 s82, s82, 0x1000
	s_addc_u32 s83, s83, 0
	global_load_dwordx4 v[186:189], v234, s[82:83]
	s_add_u32 s82, s82, 0x1000
	s_addc_u32 s83, s83, 0
	global_load_dwordx4 v[190:193], v234, s[82:83]
	s_add_u32 s82, s82, 0x1000
	s_addc_u32 s83, s83, 0
	global_load_dwordx4 v[194:197], v234, s[82:83]
	s_add_u32 s82, s82, 0x1000
	s_addc_u32 s83, s83, 0
	global_load_dwordx4 v[198:201], v234, s[82:83]
	s_add_u32 s82, s82, 0x1000
	s_addc_u32 s83, s83, 0
	global_load_dwordx4 v[202:205], v234, s[82:83]
	s_add_u32 s82, s82, 0x1000
	s_addc_u32 s83, s83, 0
	global_load_dwordx4 v[206:209], v234, s[82:83]
	s_add_u32 s82, s82, 0x1000
	s_addc_u32 s83, s83, 0
	global_load_dwordx4 v[210:213], v234, s[82:83]
	s_add_u32 s82, s82, 0x1000
	s_addc_u32 s83, s83, 0
	global_load_dwordx4 v[214:217], v234, s[82:83]
	s_add_u32 s82, s82, 0x1000
	s_addc_u32 s83, s83, 0
	global_load_dwordx4 v[218:221], v234, s[82:83]
	s_add_u32 s82, s82, 0x1000
	s_addc_u32 s83, s83, 0
	global_load_dwordx4 v[222:225], v234, s[82:83]
	s_add_u32 s82, s82, 0x1000
	s_addc_u32 s83, s83, 0
	global_load_dwordx4 v[226:229], v234, s[82:83]
	s_add_u32 s82, s82, 0x1000
	s_addc_u32 s83, s83, 0
	global_load_dwordx4 v[230:233], v234, s[82:83]
	ds_read_b128 v[62:65], v87 offset:34816
	ds_read_b128 v[66:69], v87 offset:34832
	ds_read_b128 v[72:75], v87 offset:34848
	ds_read_b128 v[102:105], v87 offset:34864
	s_waitcnt lgkmcnt(3)
	v_max_u32_e32 v59, v62, v63
	s_waitcnt lgkmcnt(2)
	v_max_u32_e32 v62, v68, v69
	v_max_u32_e32 v61, v64, v65
	v_max3_u32 v62, v66, v67, v62
	v_max3_u32 v59, v59, v61, v62
	ds_read_b128 v[62:65], v87 offset:34880
	s_waitcnt lgkmcnt(2)
	v_max_u32_e32 v61, v74, v75
	s_waitcnt lgkmcnt(1)
	v_max_u32_e32 v66, v104, v105
	v_max3_u32 v61, v72, v73, v61
	v_max3_u32 v70, v102, v103, v66
	ds_read_b128 v[66:69], v87 offset:34896
	v_max3_u32 v59, v59, v61, v70
	s_waitcnt lgkmcnt(1)
	v_max_u32_e32 v61, v64, v65
	v_max3_u32 v61, v62, v63, v61
	ds_read_b128 v[62:65], v87 offset:34912
	ds_read_b128 v[72:75], v87 offset:34928
	s_waitcnt lgkmcnt(2)
	v_max_u32_e32 v68, v68, v69
	v_max3_u32 v66, v66, v67, v68
	v_max3_u32 v59, v59, v61, v66
	s_waitcnt lgkmcnt(1)
	v_max_u32_e32 v61, v64, v65
	v_max3_u32 v61, v62, v63, v61
	s_waitcnt lgkmcnt(0)
	v_max_u32_e32 v62, v74, v75
	v_max3_u32 v62, v72, v73, v62
	v_max3_u32 v61, v59, v61, v62
	s_nop 1
	v_max_u32_dpp v59, v61, v61 quad_perm:[1,0,3,2] row_mask:0xf bank_mask:0xf
	s_waitcnt lgkmcnt(0)
	s_nop 1
	v_max_u32_dpp v64, v59, v59 quad_perm:[2,3,0,1] row_mask:0xf bank_mask:0xf
	s_waitcnt lgkmcnt(0)
	v_not_b32_e32 v59, v64
	v_bfe_u32 v59, v59, 5, 2
	v_cmp_eq_u32_e32 vcc, v59, v83
	s_and_saveexec_b64 s[26:27], vcc
	s_cbranch_execz .LBB0_731
	v_bitop3_b32 v59, v64, s44, v64 bitop3:0xc
	v_lshl_add_u32 v61, v59, 2, v85
	ds_write_b32 v61, v53 offset:34816
	ds_write_b8 v86, v59
	ds_read_b128 v[66:69], v87 offset:34816
	ds_read_b128 v[72:75], v87 offset:34832
	ds_read_b128 v[102:105], v87 offset:34848
	ds_read_b128 v[106:109], v87 offset:34864
	ds_read_b128 v[110:113], v87 offset:34880
	ds_read_b128 v[114:117], v87 offset:34896
	ds_read_b128 v[118:121], v87 offset:34912
	ds_read_b128 v[122:125], v87 offset:34928
	s_waitcnt lgkmcnt(6)
	v_max_u32_e32 v62, v74, v75
	v_max_u32_e32 v59, v66, v67
	v_max_u32_e32 v61, v68, v69
	v_max3_u32 v62, v72, v73, v62
	v_max3_u32 v59, v59, v61, v62
	s_waitcnt lgkmcnt(5)
	v_max_u32_e32 v61, v104, v105
	s_waitcnt lgkmcnt(4)
	v_max_u32_e32 v62, v108, v109
	v_max3_u32 v61, v102, v103, v61
	v_max3_u32 v62, v106, v107, v62
	v_max3_u32 v59, v59, v61, v62
	s_waitcnt lgkmcnt(3)
	v_max_u32_e32 v61, v112, v113
	s_waitcnt lgkmcnt(2)
	v_max_u32_e32 v62, v116, v117
	v_max3_u32 v61, v110, v111, v61
	v_max3_u32 v62, v114, v115, v62
	v_max3_u32 v59, v59, v61, v62
	s_waitcnt lgkmcnt(1)
	v_max_u32_e32 v61, v120, v121
	s_waitcnt lgkmcnt(0)
	v_max_u32_e32 v62, v124, v125
	v_max3_u32 v61, v118, v119, v61
	v_max3_u32 v62, v122, v123, v62
	v_max3_u32 v61, v59, v61, v62
.LBB0_731:
	s_or_b64 exec, exec, s[26:27]
	s_nop 1
	v_max_u32_dpp v59, v61, v61 quad_perm:[1,0,3,2] row_mask:0xf bank_mask:0xf
	s_waitcnt lgkmcnt(0)
	s_nop 1
	v_max_u32_dpp v62, v59, v59 quad_perm:[2,3,0,1] row_mask:0xf bank_mask:0xf
	s_waitcnt lgkmcnt(0)
	v_not_b32_e32 v59, v62
	v_bfe_u32 v59, v59, 5, 2
	v_cmp_eq_u32_e32 vcc, v59, v83
	s_and_saveexec_b64 s[26:27], vcc
	s_cbranch_execz .LBB0_733
	v_bitop3_b32 v59, v62, s44, v62 bitop3:0xc
	v_lshl_add_u32 v61, v59, 2, v85
	ds_write_b32 v61, v53 offset:34816
	ds_write_b8 v86, v59 offset:1
	ds_read_b128 v[66:69], v87 offset:34816
	ds_read_b128 v[72:75], v87 offset:34832
	ds_read_b128 v[102:105], v87 offset:34848
	ds_read_b128 v[106:109], v87 offset:34864
	ds_read_b128 v[110:113], v87 offset:34880
	ds_read_b128 v[114:117], v87 offset:34896
	ds_read_b128 v[118:121], v87 offset:34912
	ds_read_b128 v[122:125], v87 offset:34928
	s_waitcnt lgkmcnt(6)
	v_max_u32_e32 v63, v74, v75
	v_max_u32_e32 v59, v66, v67
	v_max_u32_e32 v61, v68, v69
	v_max3_u32 v63, v72, v73, v63
	v_max3_u32 v59, v59, v61, v63
	s_waitcnt lgkmcnt(5)
	v_max_u32_e32 v61, v104, v105
	s_waitcnt lgkmcnt(4)
	v_max_u32_e32 v63, v108, v109
	v_max3_u32 v61, v102, v103, v61
	v_max3_u32 v63, v106, v107, v63
	v_max3_u32 v59, v59, v61, v63
	s_waitcnt lgkmcnt(3)
	v_max_u32_e32 v61, v112, v113
	s_waitcnt lgkmcnt(2)
	v_max_u32_e32 v63, v116, v117
	v_max3_u32 v61, v110, v111, v61
	v_max3_u32 v63, v114, v115, v63
	v_max3_u32 v59, v59, v61, v63
	s_waitcnt lgkmcnt(1)
	v_max_u32_e32 v61, v120, v121
	s_waitcnt lgkmcnt(0)
	v_max_u32_e32 v63, v124, v125
	v_max3_u32 v61, v118, v119, v61
	v_max3_u32 v63, v122, v123, v63
	v_max3_u32 v61, v59, v61, v63
.LBB0_733:
	s_or_b64 exec, exec, s[26:27]
	s_nop 1
	v_max_u32_dpp v59, v61, v61 quad_perm:[1,0,3,2] row_mask:0xf bank_mask:0xf
	s_waitcnt lgkmcnt(0)
	s_nop 1
	v_max_u32_dpp v65, v59, v59 quad_perm:[2,3,0,1] row_mask:0xf bank_mask:0xf
	s_waitcnt lgkmcnt(0)
	v_not_b32_e32 v59, v65
	v_bfe_u32 v59, v59, 5, 2
	v_cmp_eq_u32_e32 vcc, v59, v83
	s_and_saveexec_b64 s[26:27], vcc
	s_cbranch_execz .LBB0_735
	v_bitop3_b32 v59, v65, s44, v65 bitop3:0xc
	v_lshl_add_u32 v61, v59, 2, v85
	ds_write_b32 v61, v53 offset:34816
	ds_write_b8 v86, v59 offset:2
	ds_read_b128 v[66:69], v87 offset:34816
	ds_read_b128 v[72:75], v87 offset:34832
	ds_read_b128 v[102:105], v87 offset:34848
	ds_read_b128 v[106:109], v87 offset:34864
	ds_read_b128 v[110:113], v87 offset:34880
	ds_read_b128 v[114:117], v87 offset:34896
	ds_read_b128 v[118:121], v87 offset:34912
	ds_read_b128 v[122:125], v87 offset:34928
	s_waitcnt lgkmcnt(6)
	v_max_u32_e32 v63, v74, v75
	v_max_u32_e32 v59, v66, v67
	v_max_u32_e32 v61, v68, v69
	v_max3_u32 v63, v72, v73, v63
	v_max3_u32 v59, v59, v61, v63
	s_waitcnt lgkmcnt(5)
	v_max_u32_e32 v61, v104, v105
	s_waitcnt lgkmcnt(4)
	v_max_u32_e32 v63, v108, v109
	v_max3_u32 v61, v102, v103, v61
	v_max3_u32 v63, v106, v107, v63
	v_max3_u32 v59, v59, v61, v63
	s_waitcnt lgkmcnt(3)
	v_max_u32_e32 v61, v112, v113
	s_waitcnt lgkmcnt(2)
	v_max_u32_e32 v63, v116, v117
	v_max3_u32 v61, v110, v111, v61
	v_max3_u32 v63, v114, v115, v63
	v_max3_u32 v59, v59, v61, v63
	s_waitcnt lgkmcnt(1)
	v_max_u32_e32 v61, v120, v121
	s_waitcnt lgkmcnt(0)
	v_max_u32_e32 v63, v124, v125
	v_max3_u32 v61, v118, v119, v61
	v_max3_u32 v63, v122, v123, v63
	v_max3_u32 v61, v59, v61, v63
.LBB0_735:
	s_or_b64 exec, exec, s[26:27]
	s_nop 1
	v_max_u32_dpp v59, v61, v61 quad_perm:[1,0,3,2] row_mask:0xf bank_mask:0xf
	s_waitcnt lgkmcnt(0)
	s_nop 1
	v_max_u32_dpp v66, v59, v59 quad_perm:[2,3,0,1] row_mask:0xf bank_mask:0xf
	s_waitcnt lgkmcnt(0)
	v_not_b32_e32 v59, v66
	v_bfe_u32 v59, v59, 5, 2
	v_cmp_eq_u32_e32 vcc, v59, v83
	s_and_saveexec_b64 s[26:27], vcc
	s_cbranch_execz .LBB0_737
	v_bitop3_b32 v59, v66, s44, v66 bitop3:0xc
	v_lshl_add_u32 v61, v59, 2, v85
	ds_write_b32 v61, v53 offset:34816
	ds_write_b8 v86, v59 offset:3
	ds_read_b128 v[72:75], v87 offset:34816
	ds_read_b128 v[102:105], v87 offset:34832
	ds_read_b128 v[106:109], v87 offset:34848
	ds_read_b128 v[110:113], v87 offset:34864
	ds_read_b128 v[114:117], v87 offset:34880
	ds_read_b128 v[118:121], v87 offset:34896
	ds_read_b128 v[122:125], v87 offset:34912
	ds_read_b128 v[126:129], v87 offset:34928
	s_waitcnt lgkmcnt(6)
	v_max_u32_e32 v63, v104, v105
	v_max_u32_e32 v59, v72, v73
	v_max_u32_e32 v61, v74, v75
	v_max3_u32 v63, v102, v103, v63
	v_max3_u32 v59, v59, v61, v63
	s_waitcnt lgkmcnt(5)
	v_max_u32_e32 v61, v108, v109
	s_waitcnt lgkmcnt(4)
	v_max_u32_e32 v63, v112, v113
	v_max3_u32 v61, v106, v107, v61
	v_max3_u32 v63, v110, v111, v63
	v_max3_u32 v59, v59, v61, v63
	s_waitcnt lgkmcnt(3)
	v_max_u32_e32 v61, v116, v117
	s_waitcnt lgkmcnt(2)
	v_max_u32_e32 v63, v120, v121
	v_max3_u32 v61, v114, v115, v61
	v_max3_u32 v63, v118, v119, v63
	v_max3_u32 v59, v59, v61, v63
	s_waitcnt lgkmcnt(1)
	v_max_u32_e32 v61, v124, v125
	s_waitcnt lgkmcnt(0)
	v_max_u32_e32 v63, v128, v129
	v_max3_u32 v61, v122, v123, v61
	v_max3_u32 v63, v126, v127, v63
	v_max3_u32 v61, v59, v61, v63
.LBB0_737:
	s_or_b64 exec, exec, s[26:27]
	s_nop 1
	v_max_u32_dpp v59, v61, v61 quad_perm:[1,0,3,2] row_mask:0xf bank_mask:0xf
	s_waitcnt lgkmcnt(0)
	s_nop 1
	v_max_u32_dpp v67, v59, v59 quad_perm:[2,3,0,1] row_mask:0xf bank_mask:0xf
	s_waitcnt lgkmcnt(0)
	v_not_b32_e32 v59, v67
	v_bfe_u32 v59, v59, 5, 2
	v_cmp_eq_u32_e32 vcc, v59, v83
	s_and_saveexec_b64 s[26:27], vcc
	s_cbranch_execz .LBB0_739
	v_bitop3_b32 v59, v67, s44, v67 bitop3:0xc
	v_lshl_add_u32 v61, v59, 2, v85
	ds_write_b32 v61, v53 offset:34816
	ds_write_b8 v86, v59 offset:4
	ds_read_b128 v[72:75], v87 offset:34816
	ds_read_b128 v[102:105], v87 offset:34832
	ds_read_b128 v[106:109], v87 offset:34848
	ds_read_b128 v[110:113], v87 offset:34864
	ds_read_b128 v[114:117], v87 offset:34880
	ds_read_b128 v[118:121], v87 offset:34896
	ds_read_b128 v[122:125], v87 offset:34912
	ds_read_b128 v[126:129], v87 offset:34928
	s_waitcnt lgkmcnt(6)
	v_max_u32_e32 v63, v104, v105
	v_max_u32_e32 v59, v72, v73
	v_max_u32_e32 v61, v74, v75
	v_max3_u32 v63, v102, v103, v63
	v_max3_u32 v59, v59, v61, v63
	s_waitcnt lgkmcnt(5)
	v_max_u32_e32 v61, v108, v109
	s_waitcnt lgkmcnt(4)
	v_max_u32_e32 v63, v112, v113
	v_max3_u32 v61, v106, v107, v61
	v_max3_u32 v63, v110, v111, v63
	v_max3_u32 v59, v59, v61, v63
	s_waitcnt lgkmcnt(3)
	v_max_u32_e32 v61, v116, v117
	s_waitcnt lgkmcnt(2)
	v_max_u32_e32 v63, v120, v121
	v_max3_u32 v61, v114, v115, v61
	v_max3_u32 v63, v118, v119, v63
	v_max3_u32 v59, v59, v61, v63
	s_waitcnt lgkmcnt(1)
	v_max_u32_e32 v61, v124, v125
	s_waitcnt lgkmcnt(0)
	v_max_u32_e32 v63, v128, v129
	v_max3_u32 v61, v122, v123, v61
	v_max3_u32 v63, v126, v127, v63
	v_max3_u32 v61, v59, v61, v63
.LBB0_739:
	s_or_b64 exec, exec, s[26:27]
	s_nop 1
	v_max_u32_dpp v59, v61, v61 quad_perm:[1,0,3,2] row_mask:0xf bank_mask:0xf
	s_waitcnt lgkmcnt(0)
	s_nop 1
	v_max_u32_dpp v59, v59, v59 quad_perm:[2,3,0,1] row_mask:0xf bank_mask:0xf
	s_waitcnt lgkmcnt(0)
	v_not_b32_e32 v63, v59
	v_bfe_u32 v63, v63, 5, 2
	v_cmp_eq_u32_e32 vcc, v63, v83
	s_and_saveexec_b64 s[26:27], vcc
	s_cbranch_execz .LBB0_741
	v_bitop3_b32 v61, v59, s44, v59 bitop3:0xc
	v_lshl_add_u32 v63, v61, 2, v85
	ds_write_b32 v63, v53 offset:34816
	ds_write_b8 v86, v61 offset:5
	ds_read_b128 v[72:75], v87 offset:34816
	ds_read_b128 v[102:105], v87 offset:34832
	ds_read_b128 v[106:109], v87 offset:34848
	ds_read_b128 v[110:113], v87 offset:34864
	ds_read_b128 v[114:117], v87 offset:34880
	ds_read_b128 v[118:121], v87 offset:34896
	ds_read_b128 v[122:125], v87 offset:34912
	ds_read_b128 v[126:129], v87 offset:34928
	s_waitcnt lgkmcnt(6)
	v_max_u32_e32 v68, v104, v105
	v_max_u32_e32 v61, v72, v73
	v_max_u32_e32 v63, v74, v75
	v_max3_u32 v68, v102, v103, v68
	v_max3_u32 v61, v61, v63, v68
	s_waitcnt lgkmcnt(5)
	v_max_u32_e32 v63, v108, v109
	s_waitcnt lgkmcnt(4)
	v_max_u32_e32 v68, v112, v113
	v_max3_u32 v63, v106, v107, v63
	v_max3_u32 v68, v110, v111, v68
	v_max3_u32 v61, v61, v63, v68
	s_waitcnt lgkmcnt(3)
	v_max_u32_e32 v63, v116, v117
	s_waitcnt lgkmcnt(2)
	v_max_u32_e32 v68, v120, v121
	v_max3_u32 v63, v114, v115, v63
	v_max3_u32 v68, v118, v119, v68
	v_max3_u32 v61, v61, v63, v68
	s_waitcnt lgkmcnt(1)
	v_max_u32_e32 v63, v124, v125
	s_waitcnt lgkmcnt(0)
	v_max_u32_e32 v68, v128, v129
	v_max3_u32 v63, v122, v123, v63
	v_max3_u32 v68, v126, v127, v68
	v_max3_u32 v61, v61, v63, v68
.LBB0_741:
	s_or_b64 exec, exec, s[26:27]
	s_nop 1
	v_max_u32_dpp v63, v61, v61 quad_perm:[1,0,3,2] row_mask:0xf bank_mask:0xf
	s_waitcnt lgkmcnt(0)
	s_nop 1
	v_max_u32_dpp v68, v63, v63 quad_perm:[2,3,0,1] row_mask:0xf bank_mask:0xf
	s_waitcnt lgkmcnt(0)
	v_not_b32_e32 v63, v68
	v_bfe_u32 v63, v63, 5, 2
	v_cmp_eq_u32_e32 vcc, v63, v83
	s_and_saveexec_b64 s[26:27], vcc
	s_cbranch_execz .LBB0_743
	v_bitop3_b32 v61, v68, s44, v68 bitop3:0xc
	v_lshl_add_u32 v63, v61, 2, v85
	ds_write_b32 v63, v53 offset:34816
	ds_write_b8 v86, v61 offset:6
	ds_read_b128 v[72:75], v87 offset:34816
	ds_read_b128 v[102:105], v87 offset:34832
	ds_read_b128 v[106:109], v87 offset:34848
	ds_read_b128 v[110:113], v87 offset:34864
	ds_read_b128 v[114:117], v87 offset:34880
	ds_read_b128 v[118:121], v87 offset:34896
	ds_read_b128 v[122:125], v87 offset:34912
	ds_read_b128 v[126:129], v87 offset:34928
	s_waitcnt lgkmcnt(6)
	v_max_u32_e32 v69, v104, v105
	v_max_u32_e32 v61, v72, v73
	v_max_u32_e32 v63, v74, v75
	v_max3_u32 v69, v102, v103, v69
	v_max3_u32 v61, v61, v63, v69
	s_waitcnt lgkmcnt(5)
	v_max_u32_e32 v63, v108, v109
	s_waitcnt lgkmcnt(4)
	v_max_u32_e32 v69, v112, v113
	v_max3_u32 v63, v106, v107, v63
	v_max3_u32 v69, v110, v111, v69
	v_max3_u32 v61, v61, v63, v69
	s_waitcnt lgkmcnt(3)
	v_max_u32_e32 v63, v116, v117
	s_waitcnt lgkmcnt(2)
	v_max_u32_e32 v69, v120, v121
	v_max3_u32 v63, v114, v115, v63
	v_max3_u32 v69, v118, v119, v69
	v_max3_u32 v61, v61, v63, v69
	s_waitcnt lgkmcnt(1)
	v_max_u32_e32 v63, v124, v125
	s_waitcnt lgkmcnt(0)
	v_max_u32_e32 v69, v128, v129
	v_max3_u32 v63, v122, v123, v63
	v_max3_u32 v69, v126, v127, v69
	v_max3_u32 v61, v61, v63, v69
.LBB0_743:
	s_or_b64 exec, exec, s[26:27]
	s_nop 1
	v_max_u32_dpp v63, v61, v61 quad_perm:[1,0,3,2] row_mask:0xf bank_mask:0xf
	s_waitcnt lgkmcnt(0)
	s_nop 1
	v_max_u32_dpp v70, v63, v63 quad_perm:[2,3,0,1] row_mask:0xf bank_mask:0xf
	s_waitcnt lgkmcnt(0)
	v_not_b32_e32 v63, v70
	v_bfe_u32 v63, v63, 5, 2
	v_cmp_eq_u32_e32 vcc, v63, v83
	s_and_saveexec_b64 s[26:27], vcc
	s_cbranch_execz .LBB0_745
	v_bitop3_b32 v61, v70, s44, v70 bitop3:0xc
	v_lshl_add_u32 v63, v61, 2, v85
	ds_write_b32 v63, v53 offset:34816
	ds_write_b8 v86, v61 offset:7
	ds_read_b128 v[72:75], v87 offset:34816
	ds_read_b128 v[102:105], v87 offset:34832
	ds_read_b128 v[106:109], v87 offset:34848
	ds_read_b128 v[110:113], v87 offset:34864
	ds_read_b128 v[114:117], v87 offset:34880
	ds_read_b128 v[118:121], v87 offset:34896
	ds_read_b128 v[122:125], v87 offset:34912
	ds_read_b128 v[126:129], v87 offset:34928
	s_waitcnt lgkmcnt(6)
	v_max_u32_e32 v69, v104, v105
	v_max_u32_e32 v61, v72, v73
	v_max_u32_e32 v63, v74, v75
	v_max3_u32 v69, v102, v103, v69
	v_max3_u32 v61, v61, v63, v69
	s_waitcnt lgkmcnt(5)
	v_max_u32_e32 v63, v108, v109
	s_waitcnt lgkmcnt(4)
	v_max_u32_e32 v69, v112, v113
	v_max3_u32 v63, v106, v107, v63
	v_max3_u32 v69, v110, v111, v69
	v_max3_u32 v61, v61, v63, v69
	s_waitcnt lgkmcnt(3)
	v_max_u32_e32 v63, v116, v117
	s_waitcnt lgkmcnt(2)
	v_max_u32_e32 v69, v120, v121
	v_max3_u32 v63, v114, v115, v63
	v_max3_u32 v69, v118, v119, v69
	v_max3_u32 v61, v61, v63, v69
	s_waitcnt lgkmcnt(1)
	v_max_u32_e32 v63, v124, v125
	s_waitcnt lgkmcnt(0)
	v_max_u32_e32 v69, v128, v129
	v_max3_u32 v63, v122, v123, v63
	v_max3_u32 v69, v126, v127, v69
	v_max3_u32 v61, v61, v63, v69
.LBB0_745:
	s_or_b64 exec, exec, s[26:27]
	s_nop 1
	v_max_u32_dpp v63, v61, v61 quad_perm:[1,0,3,2] row_mask:0xf bank_mask:0xf
	s_waitcnt lgkmcnt(0)
	s_nop 1
	v_max_u32_dpp v72, v63, v63 quad_perm:[2,3,0,1] row_mask:0xf bank_mask:0xf
	s_waitcnt lgkmcnt(0)
	v_not_b32_e32 v63, v72
	v_bfe_u32 v63, v63, 5, 2
	v_cmp_eq_u32_e32 vcc, v63, v83
	s_and_saveexec_b64 s[26:27], vcc
	s_cbranch_execz .LBB0_747
	v_bitop3_b32 v61, v72, s44, v72 bitop3:0xc
	v_lshl_add_u32 v63, v61, 2, v85
	ds_write_b32 v63, v53 offset:34816
	ds_write_b8 v86, v61 offset:8
	ds_read_b128 v[102:105], v87 offset:34816
	ds_read_b128 v[106:109], v87 offset:34832
	ds_read_b128 v[110:113], v87 offset:34848
	ds_read_b128 v[114:117], v87 offset:34864
	ds_read_b128 v[118:121], v87 offset:34880
	ds_read_b128 v[122:125], v87 offset:34896
	ds_read_b128 v[126:129], v87 offset:34912
	ds_read_b128 v[130:133], v87 offset:34928
	s_waitcnt lgkmcnt(6)
	v_max_u32_e32 v69, v108, v109
	v_max_u32_e32 v61, v102, v103
	v_max_u32_e32 v63, v104, v105
	v_max3_u32 v69, v106, v107, v69
	v_max3_u32 v61, v61, v63, v69
	s_waitcnt lgkmcnt(5)
	v_max_u32_e32 v63, v112, v113
	s_waitcnt lgkmcnt(4)
	v_max_u32_e32 v69, v116, v117
	v_max3_u32 v63, v110, v111, v63
	v_max3_u32 v69, v114, v115, v69
	v_max3_u32 v61, v61, v63, v69
	s_waitcnt lgkmcnt(3)
	v_max_u32_e32 v63, v120, v121
	s_waitcnt lgkmcnt(2)
	v_max_u32_e32 v69, v124, v125
	v_max3_u32 v63, v118, v119, v63
	v_max3_u32 v69, v122, v123, v69
	v_max3_u32 v61, v61, v63, v69
	s_waitcnt lgkmcnt(1)
	v_max_u32_e32 v63, v128, v129
	s_waitcnt lgkmcnt(0)
	v_max_u32_e32 v69, v132, v133
	v_max3_u32 v63, v126, v127, v63
	v_max3_u32 v69, v130, v131, v69
	v_max3_u32 v61, v61, v63, v69
.LBB0_747:
	s_or_b64 exec, exec, s[26:27]
	s_nop 1
	v_max_u32_dpp v63, v61, v61 quad_perm:[1,0,3,2] row_mask:0xf bank_mask:0xf
	s_waitcnt lgkmcnt(0)
	s_nop 1
	v_max_u32_dpp v63, v63, v63 quad_perm:[2,3,0,1] row_mask:0xf bank_mask:0xf
	s_waitcnt lgkmcnt(0)
	v_not_b32_e32 v69, v63
	v_bfe_u32 v69, v69, 5, 2
	v_cmp_eq_u32_e32 vcc, v69, v83
	s_and_saveexec_b64 s[26:27], vcc
	s_cbranch_execz .LBB0_749
	v_bitop3_b32 v61, v63, s44, v63 bitop3:0xc
	v_lshl_add_u32 v69, v61, 2, v85
	ds_write_b32 v69, v53 offset:34816
	ds_write_b8 v86, v61 offset:9
	ds_read_b128 v[102:105], v87 offset:34816
	ds_read_b128 v[106:109], v87 offset:34832
	ds_read_b128 v[110:113], v87 offset:34848
	ds_read_b128 v[114:117], v87 offset:34864
	ds_read_b128 v[118:121], v87 offset:34880
	ds_read_b128 v[122:125], v87 offset:34896
	ds_read_b128 v[126:129], v87 offset:34912
	ds_read_b128 v[130:133], v87 offset:34928
	s_waitcnt lgkmcnt(6)
	v_max_u32_e32 v73, v108, v109
	v_max_u32_e32 v61, v102, v103
	v_max_u32_e32 v69, v104, v105
	v_max3_u32 v73, v106, v107, v73
	v_max3_u32 v61, v61, v69, v73
	s_waitcnt lgkmcnt(5)
	v_max_u32_e32 v69, v112, v113
	s_waitcnt lgkmcnt(4)
	v_max_u32_e32 v73, v116, v117
	v_max3_u32 v69, v110, v111, v69
	v_max3_u32 v73, v114, v115, v73
	v_max3_u32 v61, v61, v69, v73
	s_waitcnt lgkmcnt(3)
	v_max_u32_e32 v69, v120, v121
	s_waitcnt lgkmcnt(2)
	v_max_u32_e32 v73, v124, v125
	v_max3_u32 v69, v118, v119, v69
	v_max3_u32 v73, v122, v123, v73
	v_max3_u32 v61, v61, v69, v73
	s_waitcnt lgkmcnt(1)
	v_max_u32_e32 v69, v128, v129
	s_waitcnt lgkmcnt(0)
	v_max_u32_e32 v73, v132, v133
	v_max3_u32 v69, v126, v127, v69
	v_max3_u32 v73, v130, v131, v73
	v_max3_u32 v61, v61, v69, v73
.LBB0_749:
	s_or_b64 exec, exec, s[26:27]
	s_nop 1
	v_max_u32_dpp v69, v61, v61 quad_perm:[1,0,3,2] row_mask:0xf bank_mask:0xf
	s_waitcnt lgkmcnt(0)
	s_nop 1
	v_max_u32_dpp v73, v69, v69 quad_perm:[2,3,0,1] row_mask:0xf bank_mask:0xf
	s_waitcnt lgkmcnt(0)
	v_not_b32_e32 v69, v73
	v_bfe_u32 v69, v69, 5, 2
	v_cmp_eq_u32_e32 vcc, v69, v83
	s_and_saveexec_b64 s[26:27], vcc
	s_cbranch_execz .LBB0_751
	v_bitop3_b32 v61, v73, s44, v73 bitop3:0xc
	v_lshl_add_u32 v69, v61, 2, v85
	ds_write_b32 v69, v53 offset:34816
	ds_write_b8 v86, v61 offset:10
	ds_read_b128 v[102:105], v87 offset:34816
	ds_read_b128 v[106:109], v87 offset:34832
	ds_read_b128 v[110:113], v87 offset:34848
	ds_read_b128 v[114:117], v87 offset:34864
	ds_read_b128 v[118:121], v87 offset:34880
	ds_read_b128 v[122:125], v87 offset:34896
	ds_read_b128 v[126:129], v87 offset:34912
	ds_read_b128 v[130:133], v87 offset:34928
	s_waitcnt lgkmcnt(6)
	v_max_u32_e32 v74, v108, v109
	v_max_u32_e32 v61, v102, v103
	v_max_u32_e32 v69, v104, v105
	v_max3_u32 v74, v106, v107, v74
	v_max3_u32 v61, v61, v69, v74
	s_waitcnt lgkmcnt(5)
	v_max_u32_e32 v69, v112, v113
	s_waitcnt lgkmcnt(4)
	v_max_u32_e32 v74, v116, v117
	v_max3_u32 v69, v110, v111, v69
	v_max3_u32 v74, v114, v115, v74
	v_max3_u32 v61, v61, v69, v74
	s_waitcnt lgkmcnt(3)
	v_max_u32_e32 v69, v120, v121
	s_waitcnt lgkmcnt(2)
	v_max_u32_e32 v74, v124, v125
	v_max3_u32 v69, v118, v119, v69
	v_max3_u32 v74, v122, v123, v74
	v_max3_u32 v61, v61, v69, v74
	s_waitcnt lgkmcnt(1)
	v_max_u32_e32 v69, v128, v129
	s_waitcnt lgkmcnt(0)
	v_max_u32_e32 v74, v132, v133
	v_max3_u32 v69, v126, v127, v69
	v_max3_u32 v74, v130, v131, v74
	v_max3_u32 v61, v61, v69, v74
.LBB0_751:
	s_or_b64 exec, exec, s[26:27]
	s_nop 1
	v_max_u32_dpp v69, v61, v61 quad_perm:[1,0,3,2] row_mask:0xf bank_mask:0xf
	s_waitcnt lgkmcnt(0)
	s_nop 1
	v_max_u32_dpp v74, v69, v69 quad_perm:[2,3,0,1] row_mask:0xf bank_mask:0xf
	s_waitcnt lgkmcnt(0)
	v_not_b32_e32 v69, v74
	v_bfe_u32 v69, v69, 5, 2
	v_cmp_eq_u32_e32 vcc, v69, v83
	s_and_saveexec_b64 s[26:27], vcc
	s_cbranch_execz .LBB0_753
	v_bitop3_b32 v61, v74, s44, v74 bitop3:0xc
	v_lshl_add_u32 v69, v61, 2, v85
	ds_write_b32 v69, v53 offset:34816
	ds_write_b8 v86, v61 offset:11
	ds_read_b128 v[102:105], v87 offset:34816
	ds_read_b128 v[106:109], v87 offset:34832
	ds_read_b128 v[110:113], v87 offset:34848
	ds_read_b128 v[114:117], v87 offset:34864
	ds_read_b128 v[118:121], v87 offset:34880
	ds_read_b128 v[122:125], v87 offset:34896
	ds_read_b128 v[126:129], v87 offset:34912
	ds_read_b128 v[130:133], v87 offset:34928
	s_waitcnt lgkmcnt(6)
	v_max_u32_e32 v75, v108, v109
	v_max_u32_e32 v61, v102, v103
	v_max_u32_e32 v69, v104, v105
	v_max3_u32 v75, v106, v107, v75
	v_max3_u32 v61, v61, v69, v75
	s_waitcnt lgkmcnt(5)
	v_max_u32_e32 v69, v112, v113
	s_waitcnt lgkmcnt(4)
	v_max_u32_e32 v75, v116, v117
	v_max3_u32 v69, v110, v111, v69
	v_max3_u32 v75, v114, v115, v75
	v_max3_u32 v61, v61, v69, v75
	s_waitcnt lgkmcnt(3)
	v_max_u32_e32 v69, v120, v121
	s_waitcnt lgkmcnt(2)
	v_max_u32_e32 v75, v124, v125
	v_max3_u32 v69, v118, v119, v69
	v_max3_u32 v75, v122, v123, v75
	v_max3_u32 v61, v61, v69, v75
	s_waitcnt lgkmcnt(1)
	v_max_u32_e32 v69, v128, v129
	s_waitcnt lgkmcnt(0)
	v_max_u32_e32 v75, v132, v133
	v_max3_u32 v69, v126, v127, v69
	v_max3_u32 v75, v130, v131, v75
	v_max3_u32 v61, v61, v69, v75
.LBB0_753:
	s_or_b64 exec, exec, s[26:27]
	s_nop 1
	v_max_u32_dpp v69, v61, v61 quad_perm:[1,0,3,2] row_mask:0xf bank_mask:0xf
	s_waitcnt lgkmcnt(0)
	s_nop 1
	v_max_u32_dpp v75, v69, v69 quad_perm:[2,3,0,1] row_mask:0xf bank_mask:0xf
	s_waitcnt lgkmcnt(0)
	v_not_b32_e32 v69, v75
	v_bfe_u32 v69, v69, 5, 2
	v_cmp_eq_u32_e32 vcc, v69, v83
	s_and_saveexec_b64 s[26:27], vcc
	s_cbranch_execz .LBB0_755
	v_bitop3_b32 v61, v75, s44, v75 bitop3:0xc
	v_lshl_add_u32 v69, v61, 2, v85
	ds_write_b32 v69, v53 offset:34816
	ds_write_b8 v86, v61 offset:12
	ds_read_b128 v[102:105], v87 offset:34816
	ds_read_b128 v[106:109], v87 offset:34832
	ds_read_b128 v[110:113], v87 offset:34848
	ds_read_b128 v[114:117], v87 offset:34864
	ds_read_b128 v[118:121], v87 offset:34880
	ds_read_b128 v[122:125], v87 offset:34896
	ds_read_b128 v[126:129], v87 offset:34912
	ds_read_b128 v[130:133], v87 offset:34928
	s_waitcnt lgkmcnt(6)
	v_max_u32_e32 v76, v108, v109
	v_max_u32_e32 v61, v102, v103
	v_max_u32_e32 v69, v104, v105
	v_max3_u32 v76, v106, v107, v76
	v_max3_u32 v61, v61, v69, v76
	s_waitcnt lgkmcnt(5)
	v_max_u32_e32 v69, v112, v113
	s_waitcnt lgkmcnt(4)
	v_max_u32_e32 v76, v116, v117
	v_max3_u32 v69, v110, v111, v69
	v_max3_u32 v76, v114, v115, v76
	v_max3_u32 v61, v61, v69, v76
	s_waitcnt lgkmcnt(3)
	v_max_u32_e32 v69, v120, v121
	s_waitcnt lgkmcnt(2)
	v_max_u32_e32 v76, v124, v125
	v_max3_u32 v69, v118, v119, v69
	v_max3_u32 v76, v122, v123, v76
	v_max3_u32 v61, v61, v69, v76
	s_waitcnt lgkmcnt(1)
	v_max_u32_e32 v69, v128, v129
	s_waitcnt lgkmcnt(0)
	v_max_u32_e32 v76, v132, v133
	v_max3_u32 v69, v126, v127, v69
	v_max3_u32 v76, v130, v131, v76
	v_max3_u32 v61, v61, v69, v76
.LBB0_755:
	s_or_b64 exec, exec, s[26:27]
	s_nop 1
	v_max_u32_dpp v69, v61, v61 quad_perm:[1,0,3,2] row_mask:0xf bank_mask:0xf
	s_waitcnt lgkmcnt(0)
	s_nop 1
	v_max_u32_dpp v69, v69, v69 quad_perm:[2,3,0,1] row_mask:0xf bank_mask:0xf
	s_waitcnt lgkmcnt(0)
	v_not_b32_e32 v76, v69
	v_bfe_u32 v76, v76, 5, 2
	v_cmp_eq_u32_e32 vcc, v76, v83
	s_and_saveexec_b64 s[26:27], vcc
	s_cbranch_execz .LBB0_757
	v_bitop3_b32 v61, v69, s44, v69 bitop3:0xc
	v_lshl_add_u32 v76, v61, 2, v85
	ds_write_b32 v76, v53 offset:34816
	ds_write_b8 v86, v61 offset:13
	ds_read_b128 v[102:105], v87 offset:34816
	ds_read_b128 v[106:109], v87 offset:34832
	ds_read_b128 v[110:113], v87 offset:34848
	ds_read_b128 v[114:117], v87 offset:34864
	ds_read_b128 v[118:121], v87 offset:34880
	ds_read_b128 v[122:125], v87 offset:34896
	ds_read_b128 v[126:129], v87 offset:34912
	ds_read_b128 v[130:133], v87 offset:34928
	s_waitcnt lgkmcnt(6)
	v_max_u32_e32 v79, v108, v109
	v_max_u32_e32 v61, v102, v103
	v_max_u32_e32 v76, v104, v105
	v_max3_u32 v79, v106, v107, v79
	v_max3_u32 v61, v61, v76, v79
	s_waitcnt lgkmcnt(5)
	v_max_u32_e32 v76, v112, v113
	s_waitcnt lgkmcnt(4)
	v_max_u32_e32 v79, v116, v117
	v_max3_u32 v76, v110, v111, v76
	v_max3_u32 v79, v114, v115, v79
	v_max3_u32 v61, v61, v76, v79
	s_waitcnt lgkmcnt(3)
	v_max_u32_e32 v76, v120, v121
	s_waitcnt lgkmcnt(2)
	v_max_u32_e32 v79, v124, v125
	v_max3_u32 v76, v118, v119, v76
	v_max3_u32 v79, v122, v123, v79
	v_max3_u32 v61, v61, v76, v79
	s_waitcnt lgkmcnt(1)
	v_max_u32_e32 v76, v128, v129
	s_waitcnt lgkmcnt(0)
	v_max_u32_e32 v79, v132, v133
	v_max3_u32 v76, v126, v127, v76
	v_max3_u32 v79, v130, v131, v79
	v_max3_u32 v61, v61, v76, v79
.LBB0_757:
	s_or_b64 exec, exec, s[26:27]
	s_nop 1
	v_max_u32_dpp v76, v61, v61 quad_perm:[1,0,3,2] row_mask:0xf bank_mask:0xf
	s_waitcnt lgkmcnt(0)
	s_nop 1
	v_max_u32_dpp v76, v76, v76 quad_perm:[2,3,0,1] row_mask:0xf bank_mask:0xf
	s_waitcnt lgkmcnt(0)
	v_not_b32_e32 v79, v76
	v_bfe_u32 v79, v79, 5, 2
	v_cmp_eq_u32_e32 vcc, v79, v83
	s_and_saveexec_b64 s[26:27], vcc
	s_cbranch_execz .LBB0_759
	v_bitop3_b32 v61, v76, s44, v76 bitop3:0xc
	v_lshl_add_u32 v79, v61, 2, v85
	ds_write_b32 v79, v53 offset:34816
	ds_write_b8 v86, v61 offset:14
	ds_read_b128 v[102:105], v87 offset:34816
	ds_read_b128 v[106:109], v87 offset:34832
	ds_read_b128 v[110:113], v87 offset:34848
	ds_read_b128 v[114:117], v87 offset:34864
	ds_read_b128 v[118:121], v87 offset:34880
	ds_read_b128 v[122:125], v87 offset:34896
	ds_read_b128 v[126:129], v87 offset:34912
	ds_read_b128 v[130:133], v87 offset:34928
	s_waitcnt lgkmcnt(6)
	v_max_u32_e32 v80, v108, v109
	v_max_u32_e32 v61, v102, v103
	v_max_u32_e32 v79, v104, v105
	v_max3_u32 v80, v106, v107, v80
	v_max3_u32 v61, v61, v79, v80
	s_waitcnt lgkmcnt(5)
	v_max_u32_e32 v79, v112, v113
	s_waitcnt lgkmcnt(4)
	v_max_u32_e32 v80, v116, v117
	v_max3_u32 v79, v110, v111, v79
	v_max3_u32 v80, v114, v115, v80
	v_max3_u32 v61, v61, v79, v80
	s_waitcnt lgkmcnt(3)
	v_max_u32_e32 v79, v120, v121
	s_waitcnt lgkmcnt(2)
	v_max_u32_e32 v80, v124, v125
	v_max3_u32 v79, v118, v119, v79
	v_max3_u32 v80, v122, v123, v80
	v_max3_u32 v61, v61, v79, v80
	s_waitcnt lgkmcnt(1)
	v_max_u32_e32 v79, v128, v129
	s_waitcnt lgkmcnt(0)
	v_max_u32_e32 v80, v132, v133
	v_max3_u32 v79, v126, v127, v79
	v_max3_u32 v80, v130, v131, v80
	v_max3_u32 v61, v61, v79, v80
.LBB0_759:
	s_or_b64 exec, exec, s[26:27]
	s_nop 1
	v_max_u32_dpp v61, v61, v61 quad_perm:[1,0,3,2] row_mask:0xf bank_mask:0xf
	s_waitcnt lgkmcnt(0)
	s_nop 1
	v_max_u32_dpp v79, v61, v61 quad_perm:[2,3,0,1] row_mask:0xf bank_mask:0xf
	s_waitcnt lgkmcnt(0)
	v_not_b32_e32 v61, v79
	v_bfe_u32 v61, v61, 5, 2
	v_cmp_eq_u32_e32 vcc, v61, v83
	s_and_saveexec_b64 s[26:27], vcc
	s_cbranch_execz .LBB0_761
	v_bitop3_b32 v61, v79, s44, v79 bitop3:0xc
	v_lshl_add_u32 v80, v61, 2, v85
	ds_write_b32 v80, v53 offset:34816
	ds_write_b8 v86, v61 offset:15
.LBB0_761:
	s_or_b64 exec, exec, s[26:27]
	s_waitcnt lgkmcnt(0)
	s_barrier
	s_waitcnt vmcnt(27)
	ds_write_b128 v98, v[16:19]
	s_waitcnt vmcnt(26)
	ds_write_b128 v98, v[20:23] offset:4352
	s_waitcnt vmcnt(25)
	ds_write_b128 v98, v[24:27] offset:8704
	s_waitcnt vmcnt(24)
	ds_write_b128 v98, v[28:31] offset:13056
	s_waitcnt vmcnt(23)
	ds_write_b128 v98, v[36:39] offset:17408
	s_waitcnt vmcnt(22)
	ds_write_b128 v98, v[40:43] offset:21760
	s_waitcnt vmcnt(21)
	ds_write_b128 v98, v[44:47] offset:26112
	s_waitcnt vmcnt(20)
	ds_write_b128 v98, v[48:51] offset:30464
	s_waitcnt lgkmcnt(0)
	s_barrier
	ds_read_b128 v[16:19], v99
	ds_read_b128 v[20:23], v99 offset:4352
	ds_read_b128 v[24:27], v99 offset:8704
	ds_read_b128 v[28:31], v99 offset:13056
	ds_read_b128 v[36:39], v99 offset:17408
	ds_read_b128 v[40:43], v99 offset:21760
	ds_read_b128 v[44:47], v99 offset:26112
	ds_read_b128 v[48:51], v99 offset:30464
	s_waitcnt vmcnt(19) lgkmcnt(7)
	v_mfma_f32_16x16x32_bf16 v[16:19], v[32:35], v[16:19], 0
	s_add_i32 s59, s59, s94
	s_cmp_ge_i32 s59, s101
	s_cselect_b64 s[26:27], -1, 0
	s_waitcnt lgkmcnt(6)
	v_mfma_f32_16x16x32_bf16 v[20:23], v[32:35], v[20:23], 0
	s_cmp_lt_i32 s59, s101
	s_cselect_b32 s28, s59, s100
	s_and_b32 s29, s28, 7
	s_waitcnt lgkmcnt(5)
	v_mfma_f32_16x16x32_bf16 v[24:27], v[32:35], v[24:27], 0
	s_lshl_b32 s24, s29, 16
	s_waitcnt lgkmcnt(4)
	v_mfma_f32_16x16x32_bf16 v[28:31], v[32:35], v[28:31], 0
	s_waitcnt lgkmcnt(3)
	v_mfma_f32_16x16x32_bf16 v[36:39], v[32:35], v[36:39], 0
	s_waitcnt lgkmcnt(2)
	v_mfma_f32_16x16x32_bf16 v[40:43], v[32:35], v[40:43], 0
	s_waitcnt lgkmcnt(1)
	v_mfma_f32_16x16x32_bf16 v[44:47], v[32:35], v[44:47], 0
	s_waitcnt lgkmcnt(0)
	v_mfma_f32_16x16x32_bf16 v[32:35], v[32:35], v[48:51], 0
	ds_read_b128 v[48:51], v88 offset:64
	ds_read_b128 v[102:105], v88 offset:128
	s_waitcnt vmcnt(18) lgkmcnt(1)
	v_mfma_f32_16x16x32_bf16 v[16:19], v[12:15], v[48:51], v[16:19]
	ds_read_b128 v[48:51], v89 offset:64
	ds_read_b128 v[106:109], v88 offset:192
	s_waitcnt lgkmcnt(1)
	v_mfma_f32_16x16x32_bf16 v[20:23], v[12:15], v[48:51], v[20:23]
	ds_read_b128 v[48:51], v90 offset:64
	ds_read_b128 v[110:113], v90 offset:128
	s_waitcnt lgkmcnt(1)
	v_mfma_f32_16x16x32_bf16 v[24:27], v[12:15], v[48:51], v[24:27]
	ds_read_b128 v[48:51], v91 offset:64
	ds_read_b128 v[114:117], v90 offset:192
	s_waitcnt vmcnt(17)
	v_mfma_f32_16x16x32_bf16 v[16:19], v[8:11], v[102:105], v[16:19]
	s_waitcnt lgkmcnt(1)
	v_mfma_f32_16x16x32_bf16 v[28:31], v[12:15], v[48:51], v[28:31]
	ds_read_b128 v[48:51], v92 offset:64
	ds_read_b128 v[118:121], v93 offset:64
	ds_read_b128 v[122:125], v92 offset:128
	s_waitcnt vmcnt(16)
	v_mfma_f32_16x16x32_bf16 v[16:19], v[4:7], v[106:109], v[16:19]
	s_waitcnt lgkmcnt(2)
	v_mfma_f32_16x16x32_bf16 v[36:39], v[12:15], v[48:51], v[36:39]
	ds_read_b128 v[48:51], v94 offset:64
	ds_read_b128 v[126:129], v94 offset:128
	ds_read_b128 v[130:133], v92 offset:192
	s_nop 2
	v_not_b32_e32 v61, v16
	v_or_b32_e32 v80, 0x80000000, v16
	s_waitcnt lgkmcnt(4)
	v_mfma_f32_16x16x32_bf16 v[40:43], v[12:15], v[118:121], v[40:43]
	ds_read_b128 v[118:121], v89 offset:128
	ds_read_b128 v[134:137], v89 offset:192
	ds_read_b128 v[138:141], v91 offset:128
	ds_read_b128 v[146:149], v91 offset:192
	ds_read_b128 v[102:105], v93 offset:128
	ds_read_b128 v[150:153], v93 offset:192
	ds_read_b128 v[154:157], v95 offset:64
	ds_read_b128 v[158:161], v94 offset:192
	v_cmp_gt_i32_e32 vcc, 0, v16
	s_waitcnt lgkmcnt(10)
	v_mfma_f32_16x16x32_bf16 v[44:47], v[12:15], v[48:51], v[44:47]
	ds_read_b128 v[106:109], v95 offset:128
	ds_read_b128 v[162:165], v95 offset:192
	v_cndmask_b32_e32 v16, v80, v61, vcc
	v_and_b32_e32 v16, 0xffffff80, v16
	s_waitcnt lgkmcnt(3)
	v_mfma_f32_16x16x32_bf16 v[12:15], v[12:15], v[154:157], v[32:35]
	v_bitop3_b32 v48, v71, s44, v16 bitop3:0x36
	v_not_b32_e32 v16, v17
	v_cmp_gt_i32_e32 vcc, 0, v17
	v_or_b32_e32 v32, 0x80000000, v17
	v_or_b32_e32 v17, 0x80000000, v18
	v_cndmask_b32_e32 v16, v32, v16, vcc
	v_and_b32_e32 v16, 0xffffff80, v16
	v_bitop3_b32 v49, v71, s44, v16 bitop3:0x36
	v_not_b32_e32 v16, v18
	v_cmp_gt_i32_e32 vcc, 0, v18
	v_mfma_f32_16x16x32_bf16 v[20:23], v[8:11], v[118:121], v[20:23]
	v_mov_b32_e32 v61, v53
	v_cndmask_b32_e32 v16, v17, v16, vcc
	v_and_b32_e32 v16, 0xffffff80, v16
	v_bitop3_b32 v50, v71, s44, v16 bitop3:0x36
	v_not_b32_e32 v16, v19
	v_or_b32_e32 v17, 0x80000000, v19
	v_cmp_gt_i32_e32 vcc, 0, v19
	v_mfma_f32_16x16x32_bf16 v[32:35], v[8:11], v[122:125], v[36:39]
	s_nop 0
	v_cndmask_b32_e32 v16, v17, v16, vcc
	v_mfma_f32_16x16x32_bf16 v[36:39], v[8:11], v[102:105], v[40:43]
	s_nop 2
	v_and_b32_e32 v40, 0xffffff80, v16
	v_mfma_f32_16x16x32_bf16 v[16:19], v[4:7], v[134:137], v[20:23]
	v_bitop3_b32 v40, v71, s44, v40 bitop3:0x36
	v_mfma_f32_16x16x32_bf16 v[24:27], v[8:11], v[110:113], v[24:27]
	v_mfma_f32_16x16x32_bf16 v[28:31], v[8:11], v[138:141], v[28:31]
	s_nop 4
	v_not_b32_e32 v41, v16
	v_or_b32_e32 v42, 0x80000000, v16
	v_cmp_gt_i32_e32 vcc, 0, v16
	v_mfma_f32_16x16x32_bf16 v[20:23], v[8:11], v[126:129], v[44:47]
	s_nop 0
	v_cndmask_b32_e32 v16, v42, v41, vcc
	v_and_b32_e32 v16, 0xffffff80, v16
	v_bitop3_b32 v16, v71, s45, v16 bitop3:0x36
	ds_write2_b32 v77, v48, v16 offset1:16
	v_not_b32_e32 v16, v17
	v_or_b32_e32 v41, 0x80000000, v17
	v_cmp_gt_i32_e32 vcc, 0, v17
	v_or_b32_e32 v17, 0x80000000, v18
	s_waitcnt lgkmcnt(2)
	v_mfma_f32_16x16x32_bf16 v[8:11], v[8:11], v[106:109], v[12:15]
	v_cndmask_b32_e32 v16, v41, v16, vcc
	v_and_b32_e32 v16, 0xffffff80, v16
	v_bitop3_b32 v16, v71, s45, v16 bitop3:0x36
	ds_write2_b32 v77, v49, v16 offset0:132 offset1:148
	v_not_b32_e32 v16, v18
	v_cmp_gt_i32_e32 vcc, 0, v18
	v_mfma_f32_16x16x32_bf16 v[12:15], v[4:7], v[114:117], v[24:27]
	s_nop 0
	v_cndmask_b32_e32 v16, v17, v16, vcc
	v_and_b32_e32 v16, 0xffffff80, v16
	v_bitop3_b32 v16, v71, s45, v16 bitop3:0x36
	ds_write2_b32 v78, v50, v16 offset0:8 offset1:24
	v_not_b32_e32 v16, v19
	v_or_b32_e32 v17, 0x80000000, v19
	v_cmp_gt_i32_e32 vcc, 0, v19
	v_mfma_f32_16x16x32_bf16 v[24:27], v[4:7], v[146:149], v[28:31]
	s_nop 0
	v_cndmask_b32_e32 v16, v17, v16, vcc
	v_cmp_gt_i32_e32 vcc, 0, v12
	v_mfma_f32_16x16x32_bf16 v[28:31], v[4:7], v[130:133], v[32:35]
	v_mfma_f32_16x16x32_bf16 v[32:35], v[4:7], v[150:153], v[36:39]
	v_mfma_f32_16x16x32_bf16 v[20:23], v[4:7], v[158:161], v[20:23]
	s_waitcnt lgkmcnt(3)
	v_mfma_f32_16x16x32_bf16 v[4:7], v[4:7], v[162:165], v[8:11]
	s_nop 2
	v_and_b32_e32 v8, 0xffffff80, v16
	v_bitop3_b32 v8, v71, s45, v8 bitop3:0x36
	ds_write2_b32 v78, v40, v8 offset0:140 offset1:156
	v_not_b32_e32 v8, v12
	v_or_b32_e32 v9, 0x80000000, v12
	v_cndmask_b32_e32 v8, v9, v8, vcc
	v_not_b32_e32 v9, v13
	v_or_b32_e32 v10, 0x80000000, v13
	v_cmp_gt_i32_e32 vcc, 0, v13
	v_or_b32_e32 v11, 0x80000000, v14
	v_or_b32_e32 v12, 0x80000000, v15
	v_cndmask_b32_e32 v9, v10, v9, vcc
	v_not_b32_e32 v10, v14
	v_cmp_gt_i32_e32 vcc, 0, v14
	v_or_b32_e32 v13, 0x80000000, v24
	v_and_b32_e32 v8, 0xffffff80, v8
	v_cndmask_b32_e32 v10, v11, v10, vcc
	v_not_b32_e32 v11, v15
	v_cmp_gt_i32_e32 vcc, 0, v15
	v_bitop3_b32 v8, v71, s48, v8 bitop3:0x36
	v_and_b32_e32 v9, 0xffffff80, v9
	v_cndmask_b32_e32 v11, v12, v11, vcc
	v_not_b32_e32 v12, v24
	v_cmp_gt_i32_e32 vcc, 0, v24
	v_bitop3_b32 v9, v71, s48, v9 bitop3:0x36
	v_and_b32_e32 v10, 0xffffff80, v10
	v_cndmask_b32_e32 v12, v13, v12, vcc
	v_and_b32_e32 v12, 0xffffff80, v12
	v_bitop3_b32 v12, v71, s49, v12 bitop3:0x36
	ds_write2_b32 v77, v8, v12 offset0:32 offset1:48
	v_not_b32_e32 v8, v25
	v_or_b32_e32 v12, 0x80000000, v25
	v_cmp_gt_i32_e32 vcc, 0, v25
	v_bitop3_b32 v10, v71, s48, v10 bitop3:0x36
	v_and_b32_e32 v11, 0xffffff80, v11
	v_cndmask_b32_e32 v8, v12, v8, vcc
	v_and_b32_e32 v8, 0xffffff80, v8
	v_bitop3_b32 v8, v71, s49, v8 bitop3:0x36
	ds_write2_b32 v77, v9, v8 offset0:164 offset1:180
	v_not_b32_e32 v8, v26
	v_or_b32_e32 v9, 0x80000000, v26
	v_cmp_gt_i32_e32 vcc, 0, v26
	v_bitop3_b32 v11, v71, s48, v11 bitop3:0x36
	v_or_b32_e32 v12, 0x80000000, v31
	v_cndmask_b32_e32 v8, v9, v8, vcc
	v_and_b32_e32 v8, 0xffffff80, v8
	v_bitop3_b32 v8, v71, s49, v8 bitop3:0x36
	ds_write2_b32 v78, v10, v8 offset0:40 offset1:56
	v_not_b32_e32 v8, v27
	v_or_b32_e32 v9, 0x80000000, v27
	v_cmp_gt_i32_e32 vcc, 0, v27
	v_or_b32_e32 v10, 0x80000000, v29
	v_or_b32_e32 v13, 0x80000000, v32
	v_cndmask_b32_e32 v8, v9, v8, vcc
	v_and_b32_e32 v8, 0xffffff80, v8
	v_bitop3_b32 v8, v71, s49, v8 bitop3:0x36
	ds_write2_b32 v78, v11, v8 offset0:172 offset1:188
	v_not_b32_e32 v8, v28
	v_or_b32_e32 v9, 0x80000000, v28
	v_cmp_gt_i32_e32 vcc, 0, v28
	v_or_b32_e32 v11, 0x80000000, v30
	s_nop 0
	v_cndmask_b32_e32 v8, v9, v8, vcc
	v_not_b32_e32 v9, v29
	v_cmp_gt_i32_e32 vcc, 0, v29
	v_and_b32_e32 v8, 0xffffff80, v8
	v_bitop3_b32 v8, v71, 63, v8 bitop3:0x36
	v_cndmask_b32_e32 v9, v10, v9, vcc
	v_not_b32_e32 v10, v30
	v_cmp_gt_i32_e32 vcc, 0, v30
	v_and_b32_e32 v9, 0xffffff80, v9
	v_bitop3_b32 v9, v71, 63, v9 bitop3:0x36
	v_cndmask_b32_e32 v10, v11, v10, vcc
	v_not_b32_e32 v11, v31
	v_cmp_gt_i32_e32 vcc, 0, v31
	v_and_b32_e32 v10, 0xffffff80, v10
	v_bitop3_b32 v10, v71, 63, v10 bitop3:0x36
	v_cndmask_b32_e32 v11, v12, v11, vcc
	v_not_b32_e32 v12, v32
	v_cmp_gt_i32_e32 vcc, 0, v32
	v_and_b32_e32 v11, 0xffffff80, v11
	v_bitop3_b32 v11, v71, 63, v11 bitop3:0x36
	v_cndmask_b32_e32 v12, v13, v12, vcc
	v_and_b32_e32 v12, 0xffffff80, v12
	v_bitop3_b32 v12, v71, 47, v12 bitop3:0x36
	ds_write2_b32 v77, v8, v12 offset0:64 offset1:80
	v_not_b32_e32 v8, v33
	v_or_b32_e32 v12, 0x80000000, v33
	v_cmp_gt_i32_e32 vcc, 0, v33
	v_or_b32_e32 v13, 0x80000000, v4
	s_nop 0
	v_cndmask_b32_e32 v8, v12, v8, vcc
	v_and_b32_e32 v8, 0xffffff80, v8
	v_bitop3_b32 v8, v71, 47, v8 bitop3:0x36
	ds_write2_b32 v77, v9, v8 offset0:196 offset1:212
	v_not_b32_e32 v8, v34
	v_or_b32_e32 v9, 0x80000000, v34
	v_cmp_gt_i32_e32 vcc, 0, v34
	v_or_b32_e32 v12, 0x80000000, v23
	s_nop 0
	v_cndmask_b32_e32 v8, v9, v8, vcc
	v_and_b32_e32 v8, 0xffffff80, v8
	v_bitop3_b32 v8, v71, 47, v8 bitop3:0x36
	ds_write2_b32 v78, v10, v8 offset0:72 offset1:88
	v_not_b32_e32 v8, v35
	v_or_b32_e32 v9, 0x80000000, v35
	v_cmp_gt_i32_e32 vcc, 0, v35
	v_or_b32_e32 v10, 0x80000000, v21
	s_nop 0
	v_cndmask_b32_e32 v8, v9, v8, vcc
	v_and_b32_e32 v8, 0xffffff80, v8
	v_bitop3_b32 v8, v71, 47, v8 bitop3:0x36
	ds_write2_b32 v78, v11, v8 offset0:204 offset1:220
	v_not_b32_e32 v8, v20
	v_or_b32_e32 v9, 0x80000000, v20
	v_cmp_gt_i32_e32 vcc, 0, v20
	v_or_b32_e32 v11, 0x80000000, v22
	s_nop 0
	v_cndmask_b32_e32 v8, v9, v8, vcc
	v_not_b32_e32 v9, v21
	v_cmp_gt_i32_e32 vcc, 0, v21
	v_and_b32_e32 v8, 0xffffff80, v8
	v_bitop3_b32 v8, v71, 31, v8 bitop3:0x36
	v_cndmask_b32_e32 v9, v10, v9, vcc
	v_not_b32_e32 v10, v22
	v_cmp_gt_i32_e32 vcc, 0, v22
	v_and_b32_e32 v9, 0xffffff80, v9
	v_bitop3_b32 v9, v71, 31, v9 bitop3:0x36
	v_cndmask_b32_e32 v10, v11, v10, vcc
	v_not_b32_e32 v11, v23
	v_cmp_gt_i32_e32 vcc, 0, v23
	v_and_b32_e32 v10, 0xffffff80, v10
	v_bitop3_b32 v10, v71, 31, v10 bitop3:0x36
	v_cndmask_b32_e32 v11, v12, v11, vcc
	v_not_b32_e32 v12, v4
	v_cmp_gt_i32_e32 vcc, 0, v4
	v_and_b32_e32 v11, 0xffffff80, v11
	v_bitop3_b32 v11, v71, 31, v11 bitop3:0x36
	v_cndmask_b32_e32 v4, v13, v12, vcc
	v_and_b32_e32 v4, 0xffffff80, v4
	v_bitop3_b32 v4, v71, 15, v4 bitop3:0x36
	ds_write2_b32 v77, v8, v4 offset0:96 offset1:112
	v_not_b32_e32 v4, v5
	v_or_b32_e32 v8, 0x80000000, v5
	v_cmp_gt_i32_e32 vcc, 0, v5
	v_or_b32_e32 v5, 0x80000000, v6
	s_nop 0
	v_cndmask_b32_e32 v4, v8, v4, vcc
	v_and_b32_e32 v4, 0xffffff80, v4
	v_bitop3_b32 v4, v71, 15, v4 bitop3:0x36
	ds_write2_b32 v77, v9, v4 offset0:228 offset1:244
	v_not_b32_e32 v4, v6
	v_cmp_gt_i32_e32 vcc, 0, v6
	s_nop 1
	v_cndmask_b32_e32 v4, v5, v4, vcc
	v_and_b32_e32 v4, 0xffffff80, v4
	v_bitop3_b32 v4, v71, 15, v4 bitop3:0x36
	ds_write2_b32 v78, v10, v4 offset0:104 offset1:120
	v_not_b32_e32 v4, v7
	v_or_b32_e32 v5, 0x80000000, v7
	v_cmp_gt_i32_e32 vcc, 0, v7
	s_nop 1
	v_cndmask_b32_e32 v4, v5, v4, vcc
	v_and_b32_e32 v4, 0xffffff80, v4
	v_bitop3_b32 v4, v71, 15, v4 bitop3:0x36
	ds_write2_b32 v78, v11, v4 offset0:236 offset1:252
	v_lshl_add_u64 v[4:5], v[54:55], 0, s[24:25]
	v_add_co_u32_e32 v6, vcc, s39, v4
	s_waitcnt lgkmcnt(0)
	s_nop 0
	v_addc_co_u32_e32 v7, vcc, 0, v5, vcc
	s_waitcnt vmcnt(0)
	v_mul_f32_e32 v170, s86, v170
	v_mul_f32_e32 v171, s86, v171
	v_mul_f32_e32 v172, s86, v172
	v_mul_f32_e32 v173, s86, v173
	v_mul_f32_e32 v174, s86, v174
	v_mul_f32_e32 v175, s86, v175
	v_mul_f32_e32 v176, s86, v176
	v_mul_f32_e32 v177, s86, v177
	v_mul_f32_e32 v178, s86, v178
	v_mul_f32_e32 v179, s86, v179
	v_mul_f32_e32 v180, s86, v180
	v_mul_f32_e32 v181, s86, v181
	v_mul_f32_e32 v182, s86, v182
	v_mul_f32_e32 v183, s86, v183
	v_mul_f32_e32 v184, s86, v184
	v_mul_f32_e32 v185, s86, v185
	v_mul_f32_e32 v186, s86, v186
	v_mul_f32_e32 v187, s86, v187
	v_mul_f32_e32 v188, s86, v188
	v_mul_f32_e32 v189, s86, v189
	v_mul_f32_e32 v190, s86, v190
	v_mul_f32_e32 v191, s86, v191
	v_mul_f32_e32 v192, s86, v192
	v_mul_f32_e32 v193, s86, v193
	v_mul_f32_e32 v194, s86, v194
	v_mul_f32_e32 v195, s86, v195
	v_mul_f32_e32 v196, s86, v196
	v_mul_f32_e32 v197, s86, v197
	v_mul_f32_e32 v198, s86, v198
	v_mul_f32_e32 v199, s86, v199
	v_mul_f32_e32 v200, s86, v200
	v_mul_f32_e32 v201, s86, v201
	v_mul_f32_e32 v202, s86, v202
	v_mul_f32_e32 v203, s86, v203
	v_mul_f32_e32 v204, s86, v204
	v_mul_f32_e32 v205, s86, v205
	v_mul_f32_e32 v206, s86, v206
	v_mul_f32_e32 v207, s86, v207
	v_mul_f32_e32 v208, s86, v208
	v_mul_f32_e32 v209, s86, v209
	v_mul_f32_e32 v210, s86, v210
	v_mul_f32_e32 v211, s86, v211
	v_mul_f32_e32 v212, s86, v212
	v_mul_f32_e32 v213, s86, v213
	v_mul_f32_e32 v214, s86, v214
	v_mul_f32_e32 v215, s86, v215
	v_mul_f32_e32 v216, s86, v216
	v_mul_f32_e32 v217, s86, v217
	v_mul_f32_e32 v218, s86, v218
	v_mul_f32_e32 v219, s86, v219
	v_mul_f32_e32 v220, s86, v220
	v_mul_f32_e32 v221, s86, v221
	v_mul_f32_e32 v222, s86, v222
	v_mul_f32_e32 v223, s86, v223
	v_mul_f32_e32 v224, s86, v224
	v_mul_f32_e32 v225, s86, v225
	v_mul_f32_e32 v226, s86, v226
	v_mul_f32_e32 v227, s86, v227
	v_mul_f32_e32 v228, s86, v228
	v_mul_f32_e32 v229, s86, v229
	v_mul_f32_e32 v230, s86, v230
	v_mul_f32_e32 v231, s86, v231
	v_mul_f32_e32 v232, s86, v232
	v_mul_f32_e32 v233, s86, v233
	v_cvt_pk_fp8_f32 v236, v170, v171
	v_cvt_pk_fp8_f32 v237, v174, v175
	v_cvt_pk_fp8_f32 v238, v178, v179
	v_cvt_pk_fp8_f32 v239, v182, v183
	v_cvt_pk_fp8_f32 v240, v186, v187
	v_cvt_pk_fp8_f32 v241, v190, v191
	v_cvt_pk_fp8_f32 v242, v194, v195
	v_cvt_pk_fp8_f32 v243, v198, v199
	v_cvt_pk_fp8_f32 v244, v202, v203
	v_cvt_pk_fp8_f32 v245, v206, v207
	v_cvt_pk_fp8_f32 v246, v210, v211
	v_cvt_pk_fp8_f32 v247, v214, v215
	v_cvt_pk_fp8_f32 v248, v218, v219
	v_cvt_pk_fp8_f32 v249, v222, v223
	v_cvt_pk_fp8_f32 v250, v226, v227
	v_cvt_pk_fp8_f32 v251, v230, v231
	v_cvt_pk_fp8_f32 v236, v172, v173 op_sel:[0,0,1]
	v_cvt_pk_fp8_f32 v237, v176, v177 op_sel:[0,0,1]
	v_cvt_pk_fp8_f32 v238, v180, v181 op_sel:[0,0,1]
	v_cvt_pk_fp8_f32 v239, v184, v185 op_sel:[0,0,1]
	v_cvt_pk_fp8_f32 v240, v188, v189 op_sel:[0,0,1]
	v_cvt_pk_fp8_f32 v241, v192, v193 op_sel:[0,0,1]
	v_cvt_pk_fp8_f32 v242, v196, v197 op_sel:[0,0,1]
	v_cvt_pk_fp8_f32 v243, v200, v201 op_sel:[0,0,1]
	v_cvt_pk_fp8_f32 v244, v204, v205 op_sel:[0,0,1]
	v_cvt_pk_fp8_f32 v245, v208, v209 op_sel:[0,0,1]
	v_cvt_pk_fp8_f32 v246, v212, v213 op_sel:[0,0,1]
	v_cvt_pk_fp8_f32 v247, v216, v217 op_sel:[0,0,1]
	v_cvt_pk_fp8_f32 v248, v220, v221 op_sel:[0,0,1]
	v_cvt_pk_fp8_f32 v249, v224, v225 op_sel:[0,0,1]
	v_cvt_pk_fp8_f32 v250, v228, v229 op_sel:[0,0,1]
	v_cvt_pk_fp8_f32 v251, v232, v233 op_sel:[0,0,1]
	s_nop 0
	global_store_dword v235, v236, s[84:85]
	s_add_u32 s84, s84, 0x800
	s_addc_u32 s85, s85, 0
	global_store_dword v235, v237, s[84:85]
	s_add_u32 s84, s84, 0x800
	s_addc_u32 s85, s85, 0
	global_store_dword v235, v238, s[84:85]
	s_add_u32 s84, s84, 0x800
	s_addc_u32 s85, s85, 0
	global_store_dword v235, v239, s[84:85]
	s_add_u32 s84, s84, 0x800
	s_addc_u32 s85, s85, 0
	global_store_dword v235, v240, s[84:85]
	s_add_u32 s84, s84, 0x800
	s_addc_u32 s85, s85, 0
	global_store_dword v235, v241, s[84:85]
	s_add_u32 s84, s84, 0x800
	s_addc_u32 s85, s85, 0
	global_store_dword v235, v242, s[84:85]
	s_add_u32 s84, s84, 0x800
	s_addc_u32 s85, s85, 0
	global_store_dword v235, v243, s[84:85]
	s_add_u32 s84, s84, 0x800
	s_addc_u32 s85, s85, 0
	global_store_dword v235, v244, s[84:85]
	s_add_u32 s84, s84, 0x800
	s_addc_u32 s85, s85, 0
	global_store_dword v235, v245, s[84:85]
	s_add_u32 s84, s84, 0x800
	s_addc_u32 s85, s85, 0
	global_store_dword v235, v246, s[84:85]
	s_add_u32 s84, s84, 0x800
	s_addc_u32 s85, s85, 0
	global_store_dword v235, v247, s[84:85]
	s_add_u32 s84, s84, 0x800
	s_addc_u32 s85, s85, 0
	global_store_dword v235, v248, s[84:85]
	s_add_u32 s84, s84, 0x800
	s_addc_u32 s85, s85, 0
	global_store_dword v235, v249, s[84:85]
	s_add_u32 s84, s84, 0x800
	s_addc_u32 s85, s85, 0
	global_store_dword v235, v250, s[84:85]
	s_add_u32 s84, s84, 0x800
	s_addc_u32 s85, s85, 0
	global_store_dword v235, v251, s[84:85]
	s_barrier
	global_load_dwordx4 v[44:47], v[6:7], off offset:-4096
	global_load_dwordx4 v[36:39], v[6:7], off
	v_add_co_u32_e32 v6, vcc, s38, v4
	s_lshl_b32 s24, s28, 3
	s_nop 0
	v_addc_co_u32_e32 v7, vcc, 0, v5, vcc
	global_load_dwordx4 v[40:43], v[6:7], off offset:-4096
	global_load_dwordx4 v[28:31], v[6:7], off
	v_add_co_u32_e32 v6, vcc, s37, v4
	s_andn2_b32 s24, s24, 63
	s_nop 0
	v_addc_co_u32_e32 v7, vcc, 0, v5, vcc
	global_load_dwordx4 v[32:35], v[6:7], off offset:-4096
	global_load_dwordx4 v[20:23], v[6:7], off
	v_add_co_u32_e32 v6, vcc, s36, v4
	s_nop 1
	v_addc_co_u32_e32 v7, vcc, 0, v5, vcc
	global_load_dwordx4 v[48:51], v[4:5], off
	global_load_dwordx4 v[24:27], v[6:7], off
	v_add_u32_e32 v4, s24, v84
	v_ashrrev_i32_e32 v5, 31, v4
	v_lshlrev_b64 v[4:5], 12, v[4:5]
	v_lshl_add_u64 v[4:5], s[16:17], 0, v[4:5]
	s_lshl_b32 s24, s29, 9
	v_lshl_add_u64 v[4:5], v[4:5], 0, s[24:25]
	v_lshl_add_u64 v[4:5], v[4:5], 0, v[60:61]
	global_load_dwordx4 v[16:19], v[4:5], off
	global_load_dwordx4 v[12:15], v[4:5], off offset:64
	global_load_dwordx4 v[8:11], v[4:5], off offset:128
	s_nop 0
	global_load_dwordx4 v[4:7], v[4:5], off offset:192
	ds_read_b128 v[102:105], v87 offset:34816
	ds_read_b128 v[106:109], v87 offset:34832
	ds_read_b128 v[110:113], v87 offset:34848
	ds_read_b128 v[114:117], v87 offset:34864
	s_waitcnt lgkmcnt(3)
	v_max_u32_e32 v61, v102, v103
	v_max_u32_e32 v77, v104, v105
	s_waitcnt lgkmcnt(2)
	v_max_u32_e32 v78, v108, v109
	ds_read_b128 v[102:105], v87 offset:34880
	v_max3_u32 v78, v106, v107, v78
	ds_read_b128 v[106:109], v87 offset:34896
	v_max3_u32 v61, v61, v77, v78
	s_waitcnt lgkmcnt(3)
	v_max_u32_e32 v77, v112, v113
	s_waitcnt lgkmcnt(2)
	v_max_u32_e32 v78, v116, v117
	v_max3_u32 v77, v110, v111, v77
	v_max3_u32 v78, v114, v115, v78
	v_max3_u32 v61, v61, v77, v78
	s_waitcnt lgkmcnt(1)
	v_max_u32_e32 v77, v104, v105
	v_max3_u32 v77, v102, v103, v77
	ds_read_b128 v[102:105], v87 offset:34912
	s_waitcnt lgkmcnt(1)
	v_max_u32_e32 v78, v108, v109
	ds_read_b128 v[108:111], v87 offset:34928
	v_max3_u32 v78, v106, v107, v78
	v_max3_u32 v61, v61, v77, v78
	s_waitcnt lgkmcnt(1)
	v_max_u32_e32 v77, v104, v105
	v_max3_u32 v77, v102, v103, v77
	s_waitcnt lgkmcnt(0)
	v_max_u32_e32 v78, v110, v111
	v_max3_u32 v78, v108, v109, v78
	v_max3_u32 v112, v61, v77, v78
	s_nop 1
	v_max_u32_dpp v61, v112, v112 quad_perm:[1,0,3,2] row_mask:0xf bank_mask:0xf
	s_waitcnt lgkmcnt(0)
	s_nop 1
	v_max_u32_dpp v61, v61, v61 quad_perm:[2,3,0,1] row_mask:0xf bank_mask:0xf
	s_waitcnt lgkmcnt(0)
	v_not_b32_e32 v77, v61
	v_bfe_u32 v77, v77, 5, 2
	v_cmp_eq_u32_e32 vcc, v77, v83
	s_and_saveexec_b64 s[28:29], vcc
	s_cbranch_execz .LBB0_763
	v_bitop3_b32 v77, v61, s44, v61 bitop3:0xc
	v_lshl_add_u32 v78, v77, 2, v85
	ds_write_b32 v78, v53 offset:34816
	ds_write_b8 v86, v77 offset:16
	ds_read_b128 v[102:105], v87 offset:34816
	ds_read_b128 v[106:109], v87 offset:34832
	ds_read_b128 v[110:113], v87 offset:34848
	ds_read_b128 v[114:117], v87 offset:34864
	ds_read_b128 v[118:121], v87 offset:34880
	ds_read_b128 v[122:125], v87 offset:34896
	ds_read_b128 v[126:129], v87 offset:34912
	ds_read_b128 v[130:133], v87 offset:34928
	s_waitcnt lgkmcnt(6)
	v_max_u32_e32 v80, v108, v109
	v_max_u32_e32 v77, v102, v103
	v_max_u32_e32 v78, v104, v105
	v_max3_u32 v80, v106, v107, v80
	v_max3_u32 v77, v77, v78, v80
	s_waitcnt lgkmcnt(5)
	v_max_u32_e32 v78, v112, v113
	s_waitcnt lgkmcnt(4)
	v_max_u32_e32 v80, v116, v117
	v_max3_u32 v78, v110, v111, v78
	v_max3_u32 v80, v114, v115, v80
	v_max3_u32 v77, v77, v78, v80
	s_waitcnt lgkmcnt(3)
	v_max_u32_e32 v78, v120, v121
	s_waitcnt lgkmcnt(2)
	v_max_u32_e32 v80, v124, v125
	v_max3_u32 v78, v118, v119, v78
	v_max3_u32 v80, v122, v123, v80
	v_max3_u32 v77, v77, v78, v80
	s_waitcnt lgkmcnt(1)
	v_max_u32_e32 v78, v128, v129
	s_waitcnt lgkmcnt(0)
	v_max_u32_e32 v80, v132, v133
	v_max3_u32 v78, v126, v127, v78
	v_max3_u32 v80, v130, v131, v80
	v_max3_u32 v112, v77, v78, v80
.LBB0_763:
	s_or_b64 exec, exec, s[28:29]
	s_nop 1
	v_max_u32_dpp v77, v112, v112 quad_perm:[1,0,3,2] row_mask:0xf bank_mask:0xf
	s_waitcnt lgkmcnt(0)
	s_nop 1
	v_max_u32_dpp v77, v77, v77 quad_perm:[2,3,0,1] row_mask:0xf bank_mask:0xf
	s_waitcnt lgkmcnt(0)
	v_not_b32_e32 v78, v77
	v_bfe_u32 v78, v78, 5, 2
	v_cmp_eq_u32_e32 vcc, v78, v83
	s_and_saveexec_b64 s[28:29], vcc
	s_cbranch_execz .LBB0_765
	v_bitop3_b32 v78, v77, s44, v77 bitop3:0xc
	v_lshl_add_u32 v80, v78, 2, v85
	ds_write_b32 v80, v53 offset:34816
	ds_write_b8 v86, v78 offset:17
	ds_read_b128 v[102:105], v87 offset:34816
	ds_read_b128 v[106:109], v87 offset:34832
	ds_read_b128 v[110:113], v87 offset:34848
	ds_read_b128 v[114:117], v87 offset:34864
	ds_read_b128 v[118:121], v87 offset:34880
	ds_read_b128 v[122:125], v87 offset:34896
	ds_read_b128 v[126:129], v87 offset:34912
	ds_read_b128 v[130:133], v87 offset:34928
	s_waitcnt lgkmcnt(6)
	v_max_u32_e32 v81, v108, v109
	v_max_u32_e32 v78, v102, v103
	v_max_u32_e32 v80, v104, v105
	v_max3_u32 v81, v106, v107, v81
	v_max3_u32 v78, v78, v80, v81
	s_waitcnt lgkmcnt(5)
	v_max_u32_e32 v80, v112, v113
	s_waitcnt lgkmcnt(4)
	v_max_u32_e32 v81, v116, v117
	v_max3_u32 v80, v110, v111, v80
	v_max3_u32 v81, v114, v115, v81
	v_max3_u32 v78, v78, v80, v81
	s_waitcnt lgkmcnt(3)
	v_max_u32_e32 v80, v120, v121
	s_waitcnt lgkmcnt(2)
	v_max_u32_e32 v81, v124, v125
	v_max3_u32 v80, v118, v119, v80
	v_max3_u32 v81, v122, v123, v81
	v_max3_u32 v78, v78, v80, v81
	s_waitcnt lgkmcnt(1)
	v_max_u32_e32 v80, v128, v129
	s_waitcnt lgkmcnt(0)
	v_max_u32_e32 v81, v132, v133
	v_max3_u32 v80, v126, v127, v80
	v_max3_u32 v81, v130, v131, v81
	v_max3_u32 v112, v78, v80, v81
.LBB0_765:
	s_or_b64 exec, exec, s[28:29]
	s_nop 1
	v_max_u32_dpp v78, v112, v112 quad_perm:[1,0,3,2] row_mask:0xf bank_mask:0xf
	s_waitcnt lgkmcnt(0)
	s_nop 1
	v_max_u32_dpp v78, v78, v78 quad_perm:[2,3,0,1] row_mask:0xf bank_mask:0xf
	s_waitcnt lgkmcnt(0)
	v_not_b32_e32 v80, v78
	v_bfe_u32 v80, v80, 5, 2
	v_cmp_eq_u32_e32 vcc, v80, v83
	s_and_saveexec_b64 s[28:29], vcc
	s_cbranch_execz .LBB0_767
	v_bitop3_b32 v80, v78, s44, v78 bitop3:0xc
	v_lshl_add_u32 v81, v80, 2, v85
	ds_write_b32 v81, v53 offset:34816
	ds_write_b8 v86, v80 offset:18
	ds_read_b128 v[102:105], v87 offset:34816
	ds_read_b128 v[106:109], v87 offset:34832
	ds_read_b128 v[110:113], v87 offset:34848
	ds_read_b128 v[114:117], v87 offset:34864
	ds_read_b128 v[118:121], v87 offset:34880
	ds_read_b128 v[122:125], v87 offset:34896
	ds_read_b128 v[126:129], v87 offset:34912
	ds_read_b128 v[130:133], v87 offset:34928
	s_waitcnt lgkmcnt(7)
	v_max_u32_e32 v80, v102, v103
	s_waitcnt lgkmcnt(6)
	v_max_u32_e32 v102, v108, v109
	v_max_u32_e32 v81, v104, v105
	v_max3_u32 v102, v106, v107, v102
	v_max3_u32 v80, v80, v81, v102
	s_waitcnt lgkmcnt(5)
	v_max_u32_e32 v81, v112, v113
	s_waitcnt lgkmcnt(4)
	v_max_u32_e32 v102, v116, v117
	v_max3_u32 v81, v110, v111, v81
	v_max3_u32 v102, v114, v115, v102
	v_max3_u32 v80, v80, v81, v102
	s_waitcnt lgkmcnt(3)
	v_max_u32_e32 v81, v120, v121
	s_waitcnt lgkmcnt(2)
	v_max_u32_e32 v102, v124, v125
	v_max3_u32 v81, v118, v119, v81
	v_max3_u32 v102, v122, v123, v102
	v_max3_u32 v80, v80, v81, v102
	s_waitcnt lgkmcnt(1)
	v_max_u32_e32 v81, v128, v129
	s_waitcnt lgkmcnt(0)
	v_max_u32_e32 v102, v132, v133
	v_max3_u32 v81, v126, v127, v81
	v_max3_u32 v102, v130, v131, v102
	v_max3_u32 v112, v80, v81, v102
.LBB0_767:
	s_or_b64 exec, exec, s[28:29]
	s_nop 1
	v_max_u32_dpp v80, v112, v112 quad_perm:[1,0,3,2] row_mask:0xf bank_mask:0xf
	s_waitcnt lgkmcnt(0)
	s_nop 1
	v_max_u32_dpp v80, v80, v80 quad_perm:[2,3,0,1] row_mask:0xf bank_mask:0xf
	s_waitcnt lgkmcnt(0)
	v_not_b32_e32 v81, v80
	v_bfe_u32 v81, v81, 5, 2
	v_cmp_eq_u32_e32 vcc, v81, v83
	s_and_saveexec_b64 s[28:29], vcc
	s_cbranch_execz .LBB0_769
	v_bitop3_b32 v81, v80, s44, v80 bitop3:0xc
	v_lshl_add_u32 v102, v81, 2, v85
	ds_write_b32 v102, v53 offset:34816
	ds_write_b8 v86, v81 offset:19
	ds_read_b128 v[102:105], v87 offset:34816
	ds_read_b128 v[106:109], v87 offset:34832
	ds_read_b128 v[110:113], v87 offset:34848
	ds_read_b128 v[114:117], v87 offset:34864
	ds_read_b128 v[118:121], v87 offset:34880
	ds_read_b128 v[122:125], v87 offset:34896
	ds_read_b128 v[126:129], v87 offset:34912
	ds_read_b128 v[130:133], v87 offset:34928
	s_waitcnt lgkmcnt(7)
	v_max_u32_e32 v81, v102, v103
	s_waitcnt lgkmcnt(6)
	v_max_u32_e32 v103, v108, v109
	v_max_u32_e32 v102, v104, v105
	v_max3_u32 v103, v106, v107, v103
	v_max3_u32 v81, v81, v102, v103
	s_waitcnt lgkmcnt(5)
	v_max_u32_e32 v102, v112, v113
	s_waitcnt lgkmcnt(4)
	v_max_u32_e32 v103, v116, v117
	v_max3_u32 v102, v110, v111, v102
	v_max3_u32 v103, v114, v115, v103
	v_max3_u32 v81, v81, v102, v103
	s_waitcnt lgkmcnt(3)
	v_max_u32_e32 v102, v120, v121
	s_waitcnt lgkmcnt(2)
	v_max_u32_e32 v103, v124, v125
	v_max3_u32 v102, v118, v119, v102
	v_max3_u32 v103, v122, v123, v103
	v_max3_u32 v81, v81, v102, v103
	s_waitcnt lgkmcnt(1)
	v_max_u32_e32 v102, v128, v129
	s_waitcnt lgkmcnt(0)
	v_max_u32_e32 v103, v132, v133
	v_max3_u32 v102, v126, v127, v102
	v_max3_u32 v103, v130, v131, v103
	v_max3_u32 v112, v81, v102, v103
.LBB0_769:
	s_or_b64 exec, exec, s[28:29]
	s_nop 1
	v_max_u32_dpp v81, v112, v112 quad_perm:[1,0,3,2] row_mask:0xf bank_mask:0xf
	s_waitcnt lgkmcnt(0)
	s_nop 1
	v_max_u32_dpp v81, v81, v81 quad_perm:[2,3,0,1] row_mask:0xf bank_mask:0xf
	s_waitcnt lgkmcnt(0)
	v_not_b32_e32 v102, v81
	v_bfe_u32 v102, v102, 5, 2
	v_cmp_eq_u32_e32 vcc, v102, v83
	s_and_saveexec_b64 s[28:29], vcc
	s_cbranch_execz .LBB0_771
	v_bitop3_b32 v102, v81, s44, v81 bitop3:0xc
	v_lshl_add_u32 v103, v102, 2, v85
	ds_write_b32 v103, v53 offset:34816
	ds_write_b8 v86, v102 offset:20
	ds_read_b128 v[102:105], v87 offset:34816
	ds_read_b128 v[106:109], v87 offset:34832
	ds_read_b128 v[110:113], v87 offset:34848
	ds_read_b128 v[114:117], v87 offset:34864
	ds_read_b128 v[118:121], v87 offset:34880
	ds_read_b128 v[122:125], v87 offset:34896
	ds_read_b128 v[126:129], v87 offset:34912
	ds_read_b128 v[130:133], v87 offset:34928
	s_waitcnt lgkmcnt(7)
	v_max_u32_e32 v102, v102, v103
	v_max_u32_e32 v103, v104, v105
	s_waitcnt lgkmcnt(6)
	v_max_u32_e32 v104, v108, v109
	v_max3_u32 v104, v106, v107, v104
	v_max3_u32 v102, v102, v103, v104
	s_waitcnt lgkmcnt(5)
	v_max_u32_e32 v103, v112, v113
	s_waitcnt lgkmcnt(4)
	v_max_u32_e32 v104, v116, v117
	v_max3_u32 v103, v110, v111, v103
	v_max3_u32 v104, v114, v115, v104
	v_max3_u32 v102, v102, v103, v104
	s_waitcnt lgkmcnt(3)
	v_max_u32_e32 v103, v120, v121
	s_waitcnt lgkmcnt(2)
	v_max_u32_e32 v104, v124, v125
	v_max3_u32 v103, v118, v119, v103
	v_max3_u32 v104, v122, v123, v104
	v_max3_u32 v102, v102, v103, v104
	s_waitcnt lgkmcnt(1)
	v_max_u32_e32 v103, v128, v129
	s_waitcnt lgkmcnt(0)
	v_max_u32_e32 v104, v132, v133
	v_max3_u32 v103, v126, v127, v103
	v_max3_u32 v104, v130, v131, v104
	v_max3_u32 v112, v102, v103, v104
.LBB0_771:
	s_or_b64 exec, exec, s[28:29]
	s_nop 1
	v_max_u32_dpp v102, v112, v112 quad_perm:[1,0,3,2] row_mask:0xf bank_mask:0xf
	s_waitcnt lgkmcnt(0)
	s_nop 1
	v_max_u32_dpp v102, v102, v102 quad_perm:[2,3,0,1] row_mask:0xf bank_mask:0xf
	s_waitcnt lgkmcnt(0)
	v_not_b32_e32 v103, v102
	v_bfe_u32 v103, v103, 5, 2
	v_cmp_eq_u32_e32 vcc, v103, v83
	s_and_saveexec_b64 s[28:29], vcc
	s_cbranch_execz .LBB0_773
	v_bitop3_b32 v103, v102, s44, v102 bitop3:0xc
	v_lshl_add_u32 v104, v103, 2, v85
	ds_write_b32 v104, v53 offset:34816
	ds_write_b8 v86, v103 offset:21
	ds_read_b128 v[104:107], v87 offset:34816
	ds_read_b128 v[108:111], v87 offset:34832
	ds_read_b128 v[112:115], v87 offset:34848
	ds_read_b128 v[116:119], v87 offset:34864
	ds_read_b128 v[120:123], v87 offset:34880
	ds_read_b128 v[124:127], v87 offset:34896
	ds_read_b128 v[128:131], v87 offset:34912
	ds_read_b128 v[132:135], v87 offset:34928
	s_waitcnt lgkmcnt(7)
	v_max_u32_e32 v103, v104, v105
	s_waitcnt lgkmcnt(6)
	v_max_u32_e32 v105, v110, v111
	v_max_u32_e32 v104, v106, v107
	v_max3_u32 v105, v108, v109, v105
	v_max3_u32 v103, v103, v104, v105
	s_waitcnt lgkmcnt(5)
	v_max_u32_e32 v104, v114, v115
	s_waitcnt lgkmcnt(4)
	v_max_u32_e32 v105, v118, v119
	v_max3_u32 v104, v112, v113, v104
	v_max3_u32 v105, v116, v117, v105
	v_max3_u32 v103, v103, v104, v105
	s_waitcnt lgkmcnt(3)
	v_max_u32_e32 v104, v122, v123
	s_waitcnt lgkmcnt(2)
	v_max_u32_e32 v105, v126, v127
	v_max3_u32 v104, v120, v121, v104
	v_max3_u32 v105, v124, v125, v105
	v_max3_u32 v103, v103, v104, v105
	s_waitcnt lgkmcnt(1)
	v_max_u32_e32 v104, v130, v131
	s_waitcnt lgkmcnt(0)
	v_max_u32_e32 v105, v134, v135
	v_max3_u32 v104, v128, v129, v104
	v_max3_u32 v105, v132, v133, v105
	v_max3_u32 v112, v103, v104, v105
.LBB0_773:
	s_or_b64 exec, exec, s[28:29]
	s_nop 1
	v_max_u32_dpp v103, v112, v112 quad_perm:[1,0,3,2] row_mask:0xf bank_mask:0xf
	s_waitcnt lgkmcnt(0)
	s_nop 1
	v_max_u32_dpp v103, v103, v103 quad_perm:[2,3,0,1] row_mask:0xf bank_mask:0xf
	s_waitcnt lgkmcnt(0)
	v_not_b32_e32 v104, v103
	v_bfe_u32 v104, v104, 5, 2
	v_cmp_eq_u32_e32 vcc, v104, v83
	s_and_saveexec_b64 s[28:29], vcc
	s_cbranch_execz .LBB0_775
	v_bitop3_b32 v104, v103, s44, v103 bitop3:0xc
	v_lshl_add_u32 v105, v104, 2, v85
	ds_write_b32 v105, v53 offset:34816
	ds_write_b8 v86, v104 offset:22
	ds_read_b128 v[104:107], v87 offset:34816
	ds_read_b128 v[108:111], v87 offset:34832
	ds_read_b128 v[112:115], v87 offset:34848
	ds_read_b128 v[116:119], v87 offset:34864
	ds_read_b128 v[120:123], v87 offset:34880
	ds_read_b128 v[124:127], v87 offset:34896
	ds_read_b128 v[128:131], v87 offset:34912
	ds_read_b128 v[132:135], v87 offset:34928
	s_waitcnt lgkmcnt(7)
	v_max_u32_e32 v104, v104, v105
	v_max_u32_e32 v105, v106, v107
	s_waitcnt lgkmcnt(6)
	v_max_u32_e32 v106, v110, v111
	v_max3_u32 v106, v108, v109, v106
	v_max3_u32 v104, v104, v105, v106
	s_waitcnt lgkmcnt(5)
	v_max_u32_e32 v105, v114, v115
	s_waitcnt lgkmcnt(4)
	v_max_u32_e32 v106, v118, v119
	v_max3_u32 v105, v112, v113, v105
	v_max3_u32 v106, v116, v117, v106
	v_max3_u32 v104, v104, v105, v106
	s_waitcnt lgkmcnt(3)
	v_max_u32_e32 v105, v122, v123
	s_waitcnt lgkmcnt(2)
	v_max_u32_e32 v106, v126, v127
	v_max3_u32 v105, v120, v121, v105
	v_max3_u32 v106, v124, v125, v106
	v_max3_u32 v104, v104, v105, v106
	s_waitcnt lgkmcnt(1)
	v_max_u32_e32 v105, v130, v131
	s_waitcnt lgkmcnt(0)
	v_max_u32_e32 v106, v134, v135
	v_max3_u32 v105, v128, v129, v105
	v_max3_u32 v106, v132, v133, v106
	v_max3_u32 v112, v104, v105, v106
.LBB0_775:
	s_or_b64 exec, exec, s[28:29]
	s_nop 1
	v_max_u32_dpp v104, v112, v112 quad_perm:[1,0,3,2] row_mask:0xf bank_mask:0xf
	s_waitcnt lgkmcnt(0)
	s_nop 1
	v_max_u32_dpp v104, v104, v104 quad_perm:[2,3,0,1] row_mask:0xf bank_mask:0xf
	s_waitcnt lgkmcnt(0)
	v_not_b32_e32 v105, v104
	v_bfe_u32 v105, v105, 5, 2
	v_cmp_eq_u32_e32 vcc, v105, v83
	s_and_saveexec_b64 s[28:29], vcc
	s_cbranch_execz .LBB0_777
	v_bitop3_b32 v105, v104, s44, v104 bitop3:0xc
	v_lshl_add_u32 v106, v105, 2, v85
	ds_write_b32 v106, v53 offset:34816
	ds_write_b8 v86, v105 offset:23
	ds_read_b128 v[106:109], v87 offset:34816
	ds_read_b128 v[110:113], v87 offset:34832
	ds_read_b128 v[114:117], v87 offset:34848
	ds_read_b128 v[118:121], v87 offset:34864
	ds_read_b128 v[122:125], v87 offset:34880
	ds_read_b128 v[126:129], v87 offset:34896
	ds_read_b128 v[130:133], v87 offset:34912
	ds_read_b128 v[134:137], v87 offset:34928
	s_waitcnt lgkmcnt(7)
	v_max_u32_e32 v105, v106, v107
	s_waitcnt lgkmcnt(6)
	v_max_u32_e32 v107, v112, v113
	v_max_u32_e32 v106, v108, v109
	v_max3_u32 v107, v110, v111, v107
	v_max3_u32 v105, v105, v106, v107
	s_waitcnt lgkmcnt(5)
	v_max_u32_e32 v106, v116, v117
	s_waitcnt lgkmcnt(4)
	v_max_u32_e32 v107, v120, v121
	v_max3_u32 v106, v114, v115, v106
	v_max3_u32 v107, v118, v119, v107
	v_max3_u32 v105, v105, v106, v107
	s_waitcnt lgkmcnt(3)
	v_max_u32_e32 v106, v124, v125
	s_waitcnt lgkmcnt(2)
	v_max_u32_e32 v107, v128, v129
	v_max3_u32 v106, v122, v123, v106
	v_max3_u32 v107, v126, v127, v107
	v_max3_u32 v105, v105, v106, v107
	s_waitcnt lgkmcnt(1)
	v_max_u32_e32 v106, v132, v133
	s_waitcnt lgkmcnt(0)
	v_max_u32_e32 v107, v136, v137
	v_max3_u32 v106, v130, v131, v106
	v_max3_u32 v107, v134, v135, v107
	v_max3_u32 v112, v105, v106, v107
.LBB0_777:
	s_or_b64 exec, exec, s[28:29]
	s_nop 1
	v_max_u32_dpp v105, v112, v112 quad_perm:[1,0,3,2] row_mask:0xf bank_mask:0xf
	s_waitcnt lgkmcnt(0)
	s_nop 1
	v_max_u32_dpp v105, v105, v105 quad_perm:[2,3,0,1] row_mask:0xf bank_mask:0xf
	s_waitcnt lgkmcnt(0)
	v_not_b32_e32 v106, v105
	v_bfe_u32 v106, v106, 5, 2
	v_cmp_eq_u32_e32 vcc, v106, v83
	s_and_saveexec_b64 s[28:29], vcc
	s_cbranch_execz .LBB0_779
	v_bitop3_b32 v106, v105, s44, v105 bitop3:0xc
	v_lshl_add_u32 v107, v106, 2, v85
	ds_write_b32 v107, v53 offset:34816
	ds_write_b8 v86, v106 offset:24
	ds_read_b128 v[106:109], v87 offset:34816
	ds_read_b128 v[110:113], v87 offset:34832
	ds_read_b128 v[114:117], v87 offset:34848
	ds_read_b128 v[118:121], v87 offset:34864
	ds_read_b128 v[122:125], v87 offset:34880
	ds_read_b128 v[126:129], v87 offset:34896
	ds_read_b128 v[130:133], v87 offset:34912
	ds_read_b128 v[134:137], v87 offset:34928
	s_waitcnt lgkmcnt(7)
	v_max_u32_e32 v106, v106, v107
	v_max_u32_e32 v107, v108, v109
	s_waitcnt lgkmcnt(6)
	v_max_u32_e32 v108, v112, v113
	v_max3_u32 v108, v110, v111, v108
	v_max3_u32 v106, v106, v107, v108
	s_waitcnt lgkmcnt(5)
	v_max_u32_e32 v107, v116, v117
	s_waitcnt lgkmcnt(4)
	v_max_u32_e32 v108, v120, v121
	v_max3_u32 v107, v114, v115, v107
	v_max3_u32 v108, v118, v119, v108
	v_max3_u32 v106, v106, v107, v108
	s_waitcnt lgkmcnt(3)
	v_max_u32_e32 v107, v124, v125
	s_waitcnt lgkmcnt(2)
	v_max_u32_e32 v108, v128, v129
	v_max3_u32 v107, v122, v123, v107
	v_max3_u32 v108, v126, v127, v108
	v_max3_u32 v106, v106, v107, v108
	s_waitcnt lgkmcnt(1)
	v_max_u32_e32 v107, v132, v133
	s_waitcnt lgkmcnt(0)
	v_max_u32_e32 v108, v136, v137
	v_max3_u32 v107, v130, v131, v107
	v_max3_u32 v108, v134, v135, v108
	v_max3_u32 v112, v106, v107, v108
.LBB0_779:
	s_or_b64 exec, exec, s[28:29]
	s_nop 1
	v_max_u32_dpp v106, v112, v112 quad_perm:[1,0,3,2] row_mask:0xf bank_mask:0xf
	s_waitcnt lgkmcnt(0)
	s_nop 1
	v_max_u32_dpp v106, v106, v106 quad_perm:[2,3,0,1] row_mask:0xf bank_mask:0xf
	s_waitcnt lgkmcnt(0)
	v_not_b32_e32 v107, v106
	v_bfe_u32 v107, v107, 5, 2
	v_cmp_eq_u32_e32 vcc, v107, v83
	s_and_saveexec_b64 s[28:29], vcc
	s_cbranch_execz .LBB0_781
	v_bitop3_b32 v107, v106, s44, v106 bitop3:0xc
	v_lshl_add_u32 v108, v107, 2, v85
	ds_write_b32 v108, v53 offset:34816
	ds_write_b8 v86, v107 offset:25
	ds_read_b128 v[108:111], v87 offset:34816
	ds_read_b128 v[112:115], v87 offset:34832
	ds_read_b128 v[116:119], v87 offset:34848
	ds_read_b128 v[120:123], v87 offset:34864
	ds_read_b128 v[124:127], v87 offset:34880
	ds_read_b128 v[128:131], v87 offset:34896
	ds_read_b128 v[132:135], v87 offset:34912
	ds_read_b128 v[136:139], v87 offset:34928
	s_waitcnt lgkmcnt(7)
	v_max_u32_e32 v107, v108, v109
	s_waitcnt lgkmcnt(6)
	v_max_u32_e32 v109, v114, v115
	v_max_u32_e32 v108, v110, v111
	v_max3_u32 v109, v112, v113, v109
	v_max3_u32 v107, v107, v108, v109
	s_waitcnt lgkmcnt(5)
	v_max_u32_e32 v108, v118, v119
	s_waitcnt lgkmcnt(4)
	v_max_u32_e32 v109, v122, v123
	v_max3_u32 v108, v116, v117, v108
	v_max3_u32 v109, v120, v121, v109
	v_max3_u32 v107, v107, v108, v109
	s_waitcnt lgkmcnt(3)
	v_max_u32_e32 v108, v126, v127
	s_waitcnt lgkmcnt(2)
	v_max_u32_e32 v109, v130, v131
	v_max3_u32 v108, v124, v125, v108
	v_max3_u32 v109, v128, v129, v109
	v_max3_u32 v107, v107, v108, v109
	s_waitcnt lgkmcnt(1)
	v_max_u32_e32 v108, v134, v135
	s_waitcnt lgkmcnt(0)
	v_max_u32_e32 v109, v138, v139
	v_max3_u32 v108, v132, v133, v108
	v_max3_u32 v109, v136, v137, v109
	v_max3_u32 v112, v107, v108, v109
.LBB0_781:
	s_or_b64 exec, exec, s[28:29]
	s_nop 1
	v_max_u32_dpp v107, v112, v112 quad_perm:[1,0,3,2] row_mask:0xf bank_mask:0xf
	s_waitcnt lgkmcnt(0)
	s_nop 1
	v_max_u32_dpp v107, v107, v107 quad_perm:[2,3,0,1] row_mask:0xf bank_mask:0xf
	s_waitcnt lgkmcnt(0)
	v_not_b32_e32 v108, v107
	v_bfe_u32 v108, v108, 5, 2
	v_cmp_eq_u32_e32 vcc, v108, v83
	s_and_saveexec_b64 s[28:29], vcc
	s_cbranch_execz .LBB0_783
	v_bitop3_b32 v108, v107, s44, v107 bitop3:0xc
	v_lshl_add_u32 v109, v108, 2, v85
	ds_write_b32 v109, v53 offset:34816
	ds_write_b8 v86, v108 offset:26
	ds_read_b128 v[108:111], v87 offset:34816
	ds_read_b128 v[112:115], v87 offset:34832
	ds_read_b128 v[116:119], v87 offset:34848
	ds_read_b128 v[120:123], v87 offset:34864
	ds_read_b128 v[124:127], v87 offset:34880
	ds_read_b128 v[128:131], v87 offset:34896
	ds_read_b128 v[132:135], v87 offset:34912
	ds_read_b128 v[136:139], v87 offset:34928
	s_waitcnt lgkmcnt(7)
	v_max_u32_e32 v108, v108, v109
	v_max_u32_e32 v109, v110, v111
	s_waitcnt lgkmcnt(6)
	v_max_u32_e32 v110, v114, v115
	v_max3_u32 v110, v112, v113, v110
	v_max3_u32 v108, v108, v109, v110
	s_waitcnt lgkmcnt(5)
	v_max_u32_e32 v109, v118, v119
	s_waitcnt lgkmcnt(4)
	v_max_u32_e32 v110, v122, v123
	v_max3_u32 v109, v116, v117, v109
	v_max3_u32 v110, v120, v121, v110
	v_max3_u32 v108, v108, v109, v110
	s_waitcnt lgkmcnt(3)
	v_max_u32_e32 v109, v126, v127
	s_waitcnt lgkmcnt(2)
	v_max_u32_e32 v110, v130, v131
	v_max3_u32 v109, v124, v125, v109
	v_max3_u32 v110, v128, v129, v110
	v_max3_u32 v108, v108, v109, v110
	s_waitcnt lgkmcnt(1)
	v_max_u32_e32 v109, v134, v135
	s_waitcnt lgkmcnt(0)
	v_max_u32_e32 v110, v138, v139
	v_max3_u32 v109, v132, v133, v109
	v_max3_u32 v110, v136, v137, v110
	v_max3_u32 v112, v108, v109, v110
.LBB0_783:
	s_or_b64 exec, exec, s[28:29]
	s_nop 1
	v_max_u32_dpp v108, v112, v112 quad_perm:[1,0,3,2] row_mask:0xf bank_mask:0xf
	s_waitcnt lgkmcnt(0)
	s_nop 1
	v_max_u32_dpp v108, v108, v108 quad_perm:[2,3,0,1] row_mask:0xf bank_mask:0xf
	s_waitcnt lgkmcnt(0)
	v_not_b32_e32 v109, v108
	v_bfe_u32 v109, v109, 5, 2
	v_cmp_eq_u32_e32 vcc, v109, v83
	s_and_saveexec_b64 s[28:29], vcc
	s_cbranch_execz .LBB0_785
	v_bitop3_b32 v109, v108, s44, v108 bitop3:0xc
	v_lshl_add_u32 v110, v109, 2, v85
	ds_write_b32 v110, v53 offset:34816
	ds_write_b8 v86, v109 offset:27
	ds_read_b128 v[110:113], v87 offset:34816
	ds_read_b128 v[114:117], v87 offset:34832
	ds_read_b128 v[118:121], v87 offset:34848
	ds_read_b128 v[122:125], v87 offset:34864
	ds_read_b128 v[126:129], v87 offset:34880
	ds_read_b128 v[130:133], v87 offset:34896
	ds_read_b128 v[134:137], v87 offset:34912
	ds_read_b128 v[138:141], v87 offset:34928
	s_waitcnt lgkmcnt(7)
	v_max_u32_e32 v109, v110, v111
	s_waitcnt lgkmcnt(6)
	v_max_u32_e32 v111, v116, v117
	v_max_u32_e32 v110, v112, v113
	v_max3_u32 v111, v114, v115, v111
	v_max3_u32 v109, v109, v110, v111
	s_waitcnt lgkmcnt(5)
	v_max_u32_e32 v110, v120, v121
	s_waitcnt lgkmcnt(4)
	v_max_u32_e32 v111, v124, v125
	v_max3_u32 v110, v118, v119, v110
	v_max3_u32 v111, v122, v123, v111
	v_max3_u32 v109, v109, v110, v111
	s_waitcnt lgkmcnt(3)
	v_max_u32_e32 v110, v128, v129
	s_waitcnt lgkmcnt(2)
	v_max_u32_e32 v111, v132, v133
	v_max3_u32 v110, v126, v127, v110
	v_max3_u32 v111, v130, v131, v111
	v_max3_u32 v109, v109, v110, v111
	s_waitcnt lgkmcnt(1)
	v_max_u32_e32 v110, v136, v137
	s_waitcnt lgkmcnt(0)
	v_max_u32_e32 v111, v140, v141
	v_max3_u32 v110, v134, v135, v110
	v_max3_u32 v111, v138, v139, v111
	v_max3_u32 v112, v109, v110, v111
.LBB0_785:
	s_or_b64 exec, exec, s[28:29]
	s_nop 1
	v_max_u32_dpp v109, v112, v112 quad_perm:[1,0,3,2] row_mask:0xf bank_mask:0xf
	s_waitcnt lgkmcnt(0)
	s_nop 1
	v_max_u32_dpp v109, v109, v109 quad_perm:[2,3,0,1] row_mask:0xf bank_mask:0xf
	s_waitcnt lgkmcnt(0)
	v_not_b32_e32 v110, v109
	v_bfe_u32 v110, v110, 5, 2
	v_cmp_eq_u32_e32 vcc, v110, v83
	s_and_saveexec_b64 s[28:29], vcc
	s_cbranch_execz .LBB0_787
	v_bitop3_b32 v110, v109, s44, v109 bitop3:0xc
	v_lshl_add_u32 v111, v110, 2, v85
	ds_write_b32 v111, v53 offset:34816
	ds_write_b8 v86, v110 offset:28
	ds_read_b128 v[110:113], v87 offset:34816
	ds_read_b128 v[114:117], v87 offset:34832
	ds_read_b128 v[118:121], v87 offset:34848
	ds_read_b128 v[122:125], v87 offset:34864
	ds_read_b128 v[126:129], v87 offset:34880
	ds_read_b128 v[130:133], v87 offset:34896
	ds_read_b128 v[134:137], v87 offset:34912
	ds_read_b128 v[138:141], v87 offset:34928
	s_waitcnt lgkmcnt(7)
	v_max_u32_e32 v110, v110, v111
	v_max_u32_e32 v111, v112, v113
	s_waitcnt lgkmcnt(6)
	v_max_u32_e32 v112, v116, v117
	v_max3_u32 v112, v114, v115, v112
	v_max3_u32 v110, v110, v111, v112
	s_waitcnt lgkmcnt(5)
	v_max_u32_e32 v111, v120, v121
	s_waitcnt lgkmcnt(4)
	v_max_u32_e32 v112, v124, v125
	v_max3_u32 v111, v118, v119, v111
	v_max3_u32 v112, v122, v123, v112
	v_max3_u32 v110, v110, v111, v112
	s_waitcnt lgkmcnt(3)
	v_max_u32_e32 v111, v128, v129
	s_waitcnt lgkmcnt(2)
	v_max_u32_e32 v112, v132, v133
	v_max3_u32 v111, v126, v127, v111
	v_max3_u32 v112, v130, v131, v112
	v_max3_u32 v110, v110, v111, v112
	s_waitcnt lgkmcnt(1)
	v_max_u32_e32 v111, v136, v137
	s_waitcnt lgkmcnt(0)
	v_max_u32_e32 v112, v140, v141
	v_max3_u32 v111, v134, v135, v111
	v_max3_u32 v112, v138, v139, v112
	v_max3_u32 v112, v110, v111, v112
.LBB0_787:
	s_or_b64 exec, exec, s[28:29]
	s_nop 1
	v_max_u32_dpp v110, v112, v112 quad_perm:[1,0,3,2] row_mask:0xf bank_mask:0xf
	s_waitcnt lgkmcnt(0)
	s_nop 1
	v_max_u32_dpp v110, v110, v110 quad_perm:[2,3,0,1] row_mask:0xf bank_mask:0xf
	s_waitcnt lgkmcnt(0)
	v_not_b32_e32 v111, v110
	v_bfe_u32 v111, v111, 5, 2
	v_cmp_eq_u32_e32 vcc, v111, v83
	s_and_saveexec_b64 s[28:29], vcc
	s_cbranch_execz .LBB0_789
	v_bitop3_b32 v111, v110, s44, v110 bitop3:0xc
	v_lshl_add_u32 v112, v111, 2, v85
	ds_write_b32 v112, v53 offset:34816
	ds_write_b8 v86, v111 offset:29
	ds_read_b128 v[112:115], v87 offset:34816
	ds_read_b128 v[116:119], v87 offset:34832
	ds_read_b128 v[120:123], v87 offset:34848
	ds_read_b128 v[124:127], v87 offset:34864
	ds_read_b128 v[128:131], v87 offset:34880
	ds_read_b128 v[132:135], v87 offset:34896
	ds_read_b128 v[136:139], v87 offset:34912
	ds_read_b128 v[140:143], v87 offset:34928
	s_waitcnt lgkmcnt(7)
	v_max_u32_e32 v111, v112, v113
	s_waitcnt lgkmcnt(6)
	v_max_u32_e32 v113, v118, v119
	v_max_u32_e32 v112, v114, v115
	v_max3_u32 v113, v116, v117, v113
	v_max3_u32 v111, v111, v112, v113
	s_waitcnt lgkmcnt(5)
	v_max_u32_e32 v112, v122, v123
	s_waitcnt lgkmcnt(4)
	v_max_u32_e32 v113, v126, v127
	v_max3_u32 v112, v120, v121, v112
	v_max3_u32 v113, v124, v125, v113
	v_max3_u32 v111, v111, v112, v113
	s_waitcnt lgkmcnt(3)
	v_max_u32_e32 v112, v130, v131
	s_waitcnt lgkmcnt(2)
	v_max_u32_e32 v113, v134, v135
	v_max3_u32 v112, v128, v129, v112
	v_max3_u32 v113, v132, v133, v113
	v_max3_u32 v111, v111, v112, v113
	s_waitcnt lgkmcnt(1)
	v_max_u32_e32 v112, v138, v139
	s_waitcnt lgkmcnt(0)
	v_max_u32_e32 v113, v142, v143
	v_max3_u32 v112, v136, v137, v112
	v_max3_u32 v113, v140, v141, v113
	v_max3_u32 v112, v111, v112, v113
.LBB0_789:
	s_or_b64 exec, exec, s[28:29]
	s_nop 1
	v_max_u32_dpp v111, v112, v112 quad_perm:[1,0,3,2] row_mask:0xf bank_mask:0xf
	s_waitcnt lgkmcnt(0)
	s_nop 1
	v_max_u32_dpp v111, v111, v111 quad_perm:[2,3,0,1] row_mask:0xf bank_mask:0xf
	s_waitcnt lgkmcnt(0)
	v_not_b32_e32 v113, v111
	v_bfe_u32 v113, v113, 5, 2
	v_cmp_eq_u32_e32 vcc, v113, v83
	s_and_saveexec_b64 s[28:29], vcc
	s_cbranch_execz .LBB0_791
	v_bitop3_b32 v112, v111, s44, v111 bitop3:0xc
	v_lshl_add_u32 v113, v112, 2, v85
	ds_write_b32 v113, v53 offset:34816
	ds_write_b8 v86, v112 offset:30
	ds_read_b128 v[112:115], v87 offset:34816
	ds_read_b128 v[116:119], v87 offset:34832
	ds_read_b128 v[120:123], v87 offset:34848
	ds_read_b128 v[124:127], v87 offset:34864
	ds_read_b128 v[128:131], v87 offset:34880
	ds_read_b128 v[132:135], v87 offset:34896
	ds_read_b128 v[136:139], v87 offset:34912
	ds_read_b128 v[140:143], v87 offset:34928
	s_waitcnt lgkmcnt(7)
	v_max_u32_e32 v112, v112, v113
	v_max_u32_e32 v113, v114, v115
	s_waitcnt lgkmcnt(6)
	v_max_u32_e32 v114, v118, v119
	v_max3_u32 v114, v116, v117, v114
	v_max3_u32 v112, v112, v113, v114
	s_waitcnt lgkmcnt(5)
	v_max_u32_e32 v113, v122, v123
	s_waitcnt lgkmcnt(4)
	v_max_u32_e32 v114, v126, v127
	v_max3_u32 v113, v120, v121, v113
	v_max3_u32 v114, v124, v125, v114
	v_max3_u32 v112, v112, v113, v114
	s_waitcnt lgkmcnt(3)
	v_max_u32_e32 v113, v130, v131
	s_waitcnt lgkmcnt(2)
	v_max_u32_e32 v114, v134, v135
	v_max3_u32 v113, v128, v129, v113
	v_max3_u32 v114, v132, v133, v114
	v_max3_u32 v112, v112, v113, v114
	s_waitcnt lgkmcnt(1)
	v_max_u32_e32 v113, v138, v139
	s_waitcnt lgkmcnt(0)
	v_max_u32_e32 v114, v142, v143
	v_max3_u32 v113, v136, v137, v113
	v_max3_u32 v114, v140, v141, v114
	v_max3_u32 v112, v112, v113, v114
.LBB0_791:
	s_or_b64 exec, exec, s[28:29]
	s_nop 1
	v_max_u32_dpp v112, v112, v112 quad_perm:[1,0,3,2] row_mask:0xf bank_mask:0xf
	s_waitcnt lgkmcnt(0)
	s_nop 1
	v_max_u32_dpp v112, v112, v112 quad_perm:[2,3,0,1] row_mask:0xf bank_mask:0xf
	s_waitcnt lgkmcnt(0)
	v_not_b32_e32 v113, v112
	v_bfe_u32 v113, v113, 5, 2
	v_cmp_eq_u32_e32 vcc, v113, v83
	s_and_saveexec_b64 s[28:29], vcc
	s_cbranch_execz .LBB0_793
	v_bitop3_b32 v113, v112, s44, v112 bitop3:0xc
	v_lshl_add_u32 v114, v113, 2, v85
	ds_write_b32 v114, v53 offset:34816
	ds_write_b8 v86, v113 offset:31

.LBB0_841:
	s_or_b64 exec, exec, s[28:29]
	v_cmp_gt_i32_e32 vcc, 0, v61
	v_mov_b32_e32 v106, 0
	s_nop 0
	v_cndmask_b32_e32 v64, -1, v101, vcc
	v_cmp_gt_i32_e32 vcc, 0, v77
	v_bitop3_b32 v64, v64, v61, s43 bitop3:0x78
	s_nop 0
	v_cndmask_b32_e32 v65, -1, v101, vcc
	v_cmp_lt_i32_e32 vcc, -1, v78
	v_bitop3_b32 v65, v65, v77, s43 bitop3:0x78
	s_nop 0
	v_cndmask_b32_e64 v66, v101, -1, vcc
	v_cmp_lt_i32_e32 vcc, -1, v80
	v_bitop3_b32 v66, v66, v78, s43 bitop3:0x78
	s_nop 0
	v_cndmask_b32_e64 v67, v101, -1, vcc
	v_cmp_lt_i32_e32 vcc, -1, v59
	v_bitop3_b32 v67, v67, v80, s43 bitop3:0x78
	s_nop 0
	v_cndmask_b32_e64 v61, v101, -1, vcc
	v_bitop3_b32 v68, v61, v59, s43 bitop3:0x78
	s_and_saveexec_b64 s[28:29], s[14:15]
	v_add_f32_e32 v59, v66, v68
	v_not_b32_e32 v61, v59
	v_or_b32_e32 v77, 0x80000000, v59
	v_cmp_gt_i32_e32 vcc, 0, v59
	s_nop 1
	v_cndmask_b32_e32 v59, v77, v61, vcc
	v_and_b32_e32 v59, 0xffffff00, v59
	v_or_b32_e32 v106, 0xbd, v59
	s_or_b64 exec, exec, s[28:29]
	v_pk_add_f32 v[108:109], v[64:65], v[68:69] op_sel_hi:[1,0]
	v_pk_add_f32 v[66:67], v[62:63], v[66:67] op_sel_hi:[0,1]
	v_and_b32_e32 v111, 0x7fffffff, v109
	v_and_b32_e32 v110, 0x7fffffff, v108
	v_xor_b32_e32 v59, -1, v109
	v_pk_add_f32 v[110:111], v[110:111], 0 neg_lo:[1,1] neg_hi:[1,1]
	v_cmp_gt_i32_e32 vcc, 0, v109
	v_xor_b32_e32 v61, -1, v108
	v_or_b32_e32 v107, 0x80000000, v67
	v_cndmask_b32_e32 v59, v111, v59, vcc
	v_cmp_gt_i32_e32 vcc, 0, v108
	v_and_b32_e32 v59, 0xffffff00, v59
	v_sub_u32_e32 v59, v59, v57
	v_cndmask_b32_e32 v61, v110, v61, vcc
	v_cmp_lt_i32_e32 vcc, -1, v69
	v_add_u32_e32 v77, 0xbe, v59
	v_pk_add_f32 v[108:109], v[62:63], v[64:65] op_sel_hi:[0,1]
	v_cndmask_b32_e64 v59, v101, -1, vcc
	v_not_b32_e32 v62, v67
	v_cmp_gt_i32_e32 vcc, 0, v67
	v_bitop3_b32 v68, v59, v69, s43 bitop3:0x78
	v_not_b32_e32 v59, v66
	v_or_b32_e32 v80, 0x80000000, v66
	v_cndmask_b32_e32 v62, v107, v62, vcc
	v_cmp_gt_i32_e32 vcc, 0, v66
	v_not_b32_e32 v78, v109
	v_or_b32_e32 v111, 0x80000000, v109
	v_cndmask_b32_e32 v59, v80, v59, vcc
	v_cmp_gt_i32_e32 vcc, 0, v109
	v_not_b32_e32 v69, v108
	v_or_b32_e32 v110, 0x80000000, v108
	v_cndmask_b32_e32 v66, v111, v78, vcc
	v_cmp_gt_i32_e32 vcc, 0, v108
	v_and_b32_e32 v59, 0xffffff00, v59
	v_sub_u32_e32 v59, v59, v2
	v_cndmask_b32_e32 v67, v110, v69, vcc
	v_cmp_lt_i32_e32 vcc, -1, v63
	v_and_b32_e32 v62, 0xffffff00, v62
	v_add_u32_e32 v78, 0xfd, v59
	v_cndmask_b32_e64 v59, v101, -1, vcc
	v_sub_u32_e32 v62, v62, v3
	v_bitop3_b32 v69, v59, v63, s43 bitop3:0x78
	v_add_u32_e32 v80, 0xfc, v62
	v_pk_add_f32 v[62:63], v[64:65], v[68:69] op_sel_hi:[0,1]
	v_not_b32_e32 v59, v63
	v_or_b32_e32 v64, 0x80000000, v63
	v_cmp_gt_i32_e32 vcc, 0, v63
	v_and_b32_e32 v67, 0xffffff00, v67
	v_and_b32_e32 v66, 0xffffff00, v66
	v_cndmask_b32_e32 v59, v64, v59, vcc
	v_and_b32_e32 v59, 0xffffff00, v59
	v_bitop3_b32 v63, v0, s44, v59 bitop3:0x36
	v_not_b32_e32 v59, v62
	v_or_b32_e32 v64, 0x80000000, v62
	v_cmp_gt_i32_e32 vcc, 0, v62
	v_and_b32_e32 v61, 0xffffff00, v61
	v_sub_u32_e32 v66, v66, v1
	v_sub_u32_e32 v67, v67, v0
	v_cndmask_b32_e32 v59, v64, v59, vcc
	v_sub_u32_e32 v61, v61, v56
	v_add_u32_e32 v67, 0xff, v67
	v_add_u32_e32 v66, 0xfe, v66
	v_and_b32_e32 v59, 0xffffff00, v59
	v_add_u32_e32 v61, 0xbf, v61
	v_bitop3_b32 v62, v0, 63, v59 bitop3:0x36
	v_max_u32_e32 v59, v66, v80
	v_max_u32_e32 v64, v67, v78
	v_max_u32_e32 v65, v104, v105
	v_max_u32_e32 v107, v73, v74
	v_max3_u32 v59, v64, v59, v63
	v_max_u32_e32 v64, v62, v61
	v_max_u32_e32 v68, v102, v103
	v_max_u32_e32 v69, v79, v81
	v_max3_u32 v65, v77, v106, v65
	v_max3_u32 v107, v75, v76, v107
	v_max_u32_e32 v108, v70, v72
	v_max3_u32 v59, v59, v64, v65
	v_max3_u32 v64, v68, v69, v107
	v_max3_u32 v59, v59, v64, v108
	s_nop 1
	v_mov_b32_dpp v64, v59 quad_perm:[1,0,3,2] row_mask:0xf bank_mask:0xf
	s_and_b32 s24, s40, 0x70
	s_lshl_b32 s24, s24, 2
	s_waitcnt lgkmcnt(0)
	v_max_u32_e32 v59, v59, v64
	s_nop 1
	v_max_u32_dpp v59, v59, v59 quad_perm:[2,3,0,1] row_mask:0xf bank_mask:0xf
	s_waitcnt lgkmcnt(0)
	v_cmp_ne_u32_e32 vcc, v67, v59
	s_nop 1
	v_cndmask_b32_e32 v64, 0, v67, vcc
	v_cmp_ne_u32_e32 vcc, v66, v59
	s_nop 1
	v_cndmask_b32_e32 v65, 0, v66, vcc
	v_cmp_ne_u32_e32 vcc, v78, v59
	s_nop 1
	v_cndmask_b32_e32 v66, 0, v78, vcc
	v_cmp_ne_u32_e32 vcc, v80, v59
	s_nop 1
	v_cndmask_b32_e32 v67, 0, v80, vcc
	v_cmp_ne_u32_e32 vcc, v72, v59
	s_nop 1
	v_cndmask_b32_e32 v68, 0, v72, vcc
	v_cmp_ne_u32_e32 vcc, v70, v59
	s_nop 1
	v_cndmask_b32_e32 v69, 0, v70, vcc
	v_cmp_ne_u32_e32 vcc, v74, v59
	s_nop 1
	v_cndmask_b32_e32 v70, 0, v74, vcc
	v_cmp_ne_u32_e32 vcc, v73, v59
	s_nop 1
	v_cndmask_b32_e32 v72, 0, v73, vcc
	v_cmp_ne_u32_e32 vcc, v76, v59
	s_nop 1
	v_cndmask_b32_e32 v73, 0, v76, vcc
	v_cmp_ne_u32_e32 vcc, v75, v59
	s_nop 1
	v_cndmask_b32_e32 v74, 0, v75, vcc
	v_cmp_ne_u32_e32 vcc, v81, v59
	s_nop 1
	v_cndmask_b32_e32 v75, 0, v81, vcc
	v_cmp_ne_u32_e32 vcc, v79, v59
	s_nop 1
	v_cndmask_b32_e32 v76, 0, v79, vcc
	v_cmp_ne_u32_e32 vcc, v103, v59
	s_nop 1
	v_cndmask_b32_e32 v78, 0, v103, vcc
	v_cmp_ne_u32_e32 vcc, v102, v59
	s_nop 1
	v_cndmask_b32_e32 v79, 0, v102, vcc
	v_cmp_ne_u32_e32 vcc, v105, v59
	s_nop 1
	v_cndmask_b32_e32 v80, 0, v105, vcc
	v_cmp_ne_u32_e32 vcc, v104, v59
	s_nop 1
	v_cndmask_b32_e32 v81, 0, v104, vcc
	v_cmp_ne_u32_e32 vcc, v61, v59
	s_nop 1
	v_cndmask_b32_e32 v102, 0, v61, vcc
	v_max3_u32 v61, v64, v65, v66
	v_max3_u32 v61, v61, v67, v68
	v_max3_u32 v61, v61, v69, v70
	v_max3_u32 v61, v61, v72, v73
	v_cmp_ne_u32_e32 vcc, v77, v59
	v_max3_u32 v61, v61, v74, v75
	v_max3_u32 v61, v61, v76, v78
	v_cndmask_b32_e32 v77, 0, v77, vcc
	v_cmp_ne_u32_e32 vcc, v106, v59
	v_max3_u32 v61, v61, v79, v80
	v_max3_u32 v61, v61, v81, v102
	v_cndmask_b32_e32 v103, 0, v106, vcc
	v_cmp_ne_u32_e32 vcc, v63, v59
	v_max3_u32 v61, v61, v77, v103
	s_nop 0
	v_cndmask_b32_e32 v63, 0, v63, vcc
	v_cmp_ne_u32_e32 vcc, v62, v59
	s_nop 1
	v_cndmask_b32_e32 v62, 0, v62, vcc
	v_max3_u32 v61, v61, v63, v62
	s_nop 1
	v_max_u32_dpp v61, v61, v61 quad_perm:[1,0,3,2] row_mask:0xf bank_mask:0xf
	s_waitcnt lgkmcnt(0)
	s_nop 1
	v_max_u32_dpp v61, v61, v61 quad_perm:[2,3,0,1] row_mask:0xf bank_mask:0xf
	s_waitcnt lgkmcnt(0)
	v_cmp_ne_u32_e32 vcc, v64, v61
	s_nop 1
	v_cndmask_b32_e32 v64, 0, v64, vcc
	v_cmp_ne_u32_e32 vcc, v65, v61
	s_nop 1
	v_cndmask_b32_e32 v65, 0, v65, vcc
	v_cmp_ne_u32_e32 vcc, v66, v61
	s_nop 1
	v_cndmask_b32_e32 v66, 0, v66, vcc
	v_cmp_ne_u32_e32 vcc, v67, v61
	s_nop 1
	v_cndmask_b32_e32 v67, 0, v67, vcc
	v_cmp_ne_u32_e32 vcc, v68, v61
	s_nop 1
	v_cndmask_b32_e32 v68, 0, v68, vcc
	v_cmp_ne_u32_e32 vcc, v69, v61
	s_nop 1
	v_cndmask_b32_e32 v69, 0, v69, vcc
	v_cmp_ne_u32_e32 vcc, v70, v61
	s_nop 1
	v_cndmask_b32_e32 v70, 0, v70, vcc
	v_cmp_ne_u32_e32 vcc, v72, v61
	s_nop 1
	v_cndmask_b32_e32 v72, 0, v72, vcc
	v_cmp_ne_u32_e32 vcc, v73, v61
	s_nop 1
	v_cndmask_b32_e32 v73, 0, v73, vcc
	v_cmp_ne_u32_e32 vcc, v74, v61
	s_nop 1
	v_cndmask_b32_e32 v74, 0, v74, vcc
	v_cmp_ne_u32_e32 vcc, v75, v61
	s_nop 1
	v_cndmask_b32_e32 v75, 0, v75, vcc
	v_cmp_ne_u32_e32 vcc, v76, v61
	s_nop 1
	v_cndmask_b32_e32 v76, 0, v76, vcc
	v_cmp_ne_u32_e32 vcc, v78, v61
	s_nop 1
	v_cndmask_b32_e32 v78, 0, v78, vcc
	v_cmp_ne_u32_e32 vcc, v79, v61
	s_nop 1
	v_cndmask_b32_e32 v79, 0, v79, vcc
	v_cmp_ne_u32_e32 vcc, v80, v61
	s_nop 1
	v_cndmask_b32_e32 v80, 0, v80, vcc
	v_cmp_ne_u32_e32 vcc, v81, v61
	s_nop 1
	v_cndmask_b32_e32 v81, 0, v81, vcc
	v_cmp_ne_u32_e32 vcc, v102, v61
	s_nop 1
	v_cndmask_b32_e32 v104, 0, v102, vcc
	v_max3_u32 v102, v64, v65, v66
	v_max3_u32 v102, v102, v67, v68
	v_max3_u32 v102, v102, v69, v70
	v_max3_u32 v102, v102, v72, v73
	v_cmp_ne_u32_e32 vcc, v77, v61
	v_max3_u32 v102, v102, v74, v75
	v_max3_u32 v102, v102, v76, v78
	v_cndmask_b32_e32 v77, 0, v77, vcc
	v_cmp_ne_u32_e32 vcc, v103, v61
	v_max3_u32 v102, v102, v79, v80
	v_max3_u32 v102, v102, v81, v104
	v_cndmask_b32_e32 v103, 0, v103, vcc
	v_cmp_ne_u32_e32 vcc, v63, v61
	v_max3_u32 v102, v102, v77, v103
	s_nop 0
	v_cndmask_b32_e32 v63, 0, v63, vcc
	v_cmp_ne_u32_e32 vcc, v62, v61
	s_nop 1
	v_cndmask_b32_e32 v62, 0, v62, vcc
	v_max3_u32 v102, v102, v63, v62
	s_nop 1
	v_max_u32_dpp v102, v102, v102 quad_perm:[1,0,3,2] row_mask:0xf bank_mask:0xf
	s_waitcnt lgkmcnt(0)
	s_nop 1
	v_max_u32_dpp v102, v102, v102 quad_perm:[2,3,0,1] row_mask:0xf bank_mask:0xf
	s_waitcnt lgkmcnt(0)
	v_cmp_ne_u32_e32 vcc, v64, v102
	s_nop 1
	v_cndmask_b32_e32 v64, 0, v64, vcc
	v_cmp_ne_u32_e32 vcc, v65, v102
	s_nop 1
	v_cndmask_b32_e32 v65, 0, v65, vcc
	v_cmp_ne_u32_e32 vcc, v66, v102
	s_nop 1
	v_cndmask_b32_e32 v66, 0, v66, vcc
	v_cmp_ne_u32_e32 vcc, v67, v102
	s_nop 1
	v_cndmask_b32_e32 v67, 0, v67, vcc
	v_cmp_ne_u32_e32 vcc, v68, v102
	s_nop 1
	v_cndmask_b32_e32 v68, 0, v68, vcc
	v_cmp_ne_u32_e32 vcc, v69, v102
	s_nop 1
	v_cndmask_b32_e32 v69, 0, v69, vcc
	v_cmp_ne_u32_e32 vcc, v70, v102
	s_nop 1
	v_cndmask_b32_e32 v70, 0, v70, vcc
	v_cmp_ne_u32_e32 vcc, v72, v102
	s_nop 1
	v_cndmask_b32_e32 v72, 0, v72, vcc
	v_cmp_ne_u32_e32 vcc, v73, v102
	s_nop 1
	v_cndmask_b32_e32 v73, 0, v73, vcc
	v_cmp_ne_u32_e32 vcc, v74, v102
	s_nop 1
	v_cndmask_b32_e32 v74, 0, v74, vcc
	v_cmp_ne_u32_e32 vcc, v75, v102
	s_nop 1
	v_cndmask_b32_e32 v75, 0, v75, vcc
	v_cmp_ne_u32_e32 vcc, v76, v102
	s_nop 1
	v_cndmask_b32_e32 v76, 0, v76, vcc
	v_cmp_ne_u32_e32 vcc, v78, v102
	s_nop 1
	v_cndmask_b32_e32 v78, 0, v78, vcc
	v_cmp_ne_u32_e32 vcc, v79, v102
	s_nop 1
	v_cndmask_b32_e32 v79, 0, v79, vcc
	v_cmp_ne_u32_e32 vcc, v80, v102
	s_nop 1
	v_cndmask_b32_e32 v80, 0, v80, vcc
	v_cmp_ne_u32_e32 vcc, v81, v102
	s_nop 1
	v_cndmask_b32_e32 v81, 0, v81, vcc
	v_cmp_ne_u32_e32 vcc, v104, v102
	s_nop 1
	v_cndmask_b32_e32 v104, 0, v104, vcc
	v_cmp_ne_u32_e32 vcc, v77, v102
	s_nop 1
	v_cndmask_b32_e32 v77, 0, v77, vcc
	v_cmp_ne_u32_e32 vcc, v103, v102
	s_nop 1
	v_cndmask_b32_e32 v105, 0, v103, vcc
	v_max3_u32 v103, v64, v65, v66
	v_max3_u32 v103, v103, v67, v68
	v_max3_u32 v103, v103, v69, v70
	v_max3_u32 v103, v103, v72, v73
	v_max3_u32 v103, v103, v74, v75
	v_max3_u32 v103, v103, v76, v78
	v_cmp_ne_u32_e32 vcc, v63, v102
	v_max3_u32 v103, v103, v79, v80
	v_max3_u32 v103, v103, v81, v104
	v_cndmask_b32_e32 v63, 0, v63, vcc
	v_cmp_ne_u32_e32 vcc, v62, v102
	v_max3_u32 v103, v103, v77, v105
	s_nop 0
	v_cndmask_b32_e32 v62, 0, v62, vcc
	v_max3_u32 v103, v103, v63, v62
	s_nop 1
	v_max_u32_dpp v103, v103, v103 quad_perm:[1,0,3,2] row_mask:0xf bank_mask:0xf
	s_waitcnt lgkmcnt(0)
	s_nop 1
	v_max_u32_dpp v103, v103, v103 quad_perm:[2,3,0,1] row_mask:0xf bank_mask:0xf
	s_waitcnt lgkmcnt(0)
	v_cmp_ne_u32_e32 vcc, v64, v103
	s_nop 1
	v_cndmask_b32_e32 v64, 0, v64, vcc
	v_cmp_ne_u32_e32 vcc, v65, v103
	s_nop 1
	v_cndmask_b32_e32 v65, 0, v65, vcc
	v_cmp_ne_u32_e32 vcc, v66, v103
	s_nop 1
	v_cndmask_b32_e32 v66, 0, v66, vcc
	v_cmp_ne_u32_e32 vcc, v67, v103
	s_nop 1
	v_cndmask_b32_e32 v67, 0, v67, vcc
	v_cmp_ne_u32_e32 vcc, v68, v103
	s_nop 1
	v_cndmask_b32_e32 v68, 0, v68, vcc
	v_cmp_ne_u32_e32 vcc, v69, v103
	s_nop 1
	v_cndmask_b32_e32 v69, 0, v69, vcc
	v_cmp_ne_u32_e32 vcc, v70, v103
	s_nop 1
	v_cndmask_b32_e32 v70, 0, v70, vcc
	v_cmp_ne_u32_e32 vcc, v72, v103
	s_nop 1
	v_cndmask_b32_e32 v72, 0, v72, vcc
	v_cmp_ne_u32_e32 vcc, v73, v103
	s_nop 1
	v_cndmask_b32_e32 v73, 0, v73, vcc
	v_cmp_ne_u32_e32 vcc, v74, v103
	s_nop 1
	v_cndmask_b32_e32 v74, 0, v74, vcc
	v_cmp_ne_u32_e32 vcc, v75, v103
	s_nop 1
	v_cndmask_b32_e32 v75, 0, v75, vcc
	v_cmp_ne_u32_e32 vcc, v76, v103
	s_nop 1
	v_cndmask_b32_e32 v106, 0, v76, vcc
	v_cmp_ne_u32_e32 vcc, v78, v103
	v_max3_u32 v76, v64, v65, v66
	v_max3_u32 v76, v76, v67, v68
	v_cndmask_b32_e32 v78, 0, v78, vcc
	v_cmp_ne_u32_e32 vcc, v79, v103
	v_max3_u32 v76, v76, v69, v70
	v_max3_u32 v76, v76, v72, v73
	v_cndmask_b32_e32 v79, 0, v79, vcc
	v_cmp_ne_u32_e32 vcc, v80, v103
	v_max3_u32 v76, v76, v74, v75
	v_max3_u32 v76, v76, v106, v78
	v_cndmask_b32_e32 v80, 0, v80, vcc
	v_cmp_ne_u32_e32 vcc, v81, v103
	v_max3_u32 v76, v76, v79, v80
	s_nop 0
	v_cndmask_b32_e32 v81, 0, v81, vcc
	v_cmp_ne_u32_e32 vcc, v104, v103
	s_nop 1
	v_cndmask_b32_e32 v104, 0, v104, vcc
	v_cmp_ne_u32_e32 vcc, v77, v103
	v_max3_u32 v76, v76, v81, v104
	s_nop 0
	v_cndmask_b32_e32 v77, 0, v77, vcc
	v_cmp_ne_u32_e32 vcc, v105, v103
	s_nop 1
	v_cndmask_b32_e32 v105, 0, v105, vcc
	v_cmp_ne_u32_e32 vcc, v63, v103
	v_max3_u32 v76, v76, v77, v105
	s_nop 0
	v_cndmask_b32_e32 v63, 0, v63, vcc
	v_cmp_ne_u32_e32 vcc, v62, v103
	s_nop 1
	v_cndmask_b32_e32 v62, 0, v62, vcc
	v_max3_u32 v76, v76, v63, v62
	s_nop 1
	v_max_u32_dpp v76, v76, v76 quad_perm:[1,0,3,2] row_mask:0xf bank_mask:0xf
	s_waitcnt lgkmcnt(0)
	s_nop 1
	v_max_u32_dpp v76, v76, v76 quad_perm:[2,3,0,1] row_mask:0xf bank_mask:0xf
	s_waitcnt lgkmcnt(0)
	v_cmp_ne_u32_e32 vcc, v64, v76
	s_nop 1
	v_cndmask_b32_e32 v64, 0, v64, vcc
	v_cmp_ne_u32_e32 vcc, v65, v76
	s_nop 1
	v_cndmask_b32_e32 v65, 0, v65, vcc
	v_cmp_ne_u32_e32 vcc, v66, v76
	s_nop 1
	v_cndmask_b32_e32 v66, 0, v66, vcc
	v_cmp_ne_u32_e32 vcc, v67, v76
	s_nop 1
	v_cndmask_b32_e32 v67, 0, v67, vcc
	v_cmp_ne_u32_e32 vcc, v68, v76
	s_nop 1
	v_cndmask_b32_e32 v68, 0, v68, vcc
	v_cmp_ne_u32_e32 vcc, v69, v76
	s_nop 1
	v_cndmask_b32_e32 v69, 0, v69, vcc
	v_cmp_ne_u32_e32 vcc, v70, v76
	s_nop 1
	v_cndmask_b32_e32 v70, 0, v70, vcc
	v_cmp_ne_u32_e32 vcc, v72, v76
	s_nop 1
	v_cndmask_b32_e32 v72, 0, v72, vcc
	v_cmp_ne_u32_e32 vcc, v73, v76
	s_nop 1
	v_cndmask_b32_e32 v73, 0, v73, vcc
	v_cmp_ne_u32_e32 vcc, v74, v76
	s_nop 1
	v_cndmask_b32_e32 v74, 0, v74, vcc
	v_cmp_ne_u32_e32 vcc, v75, v76
	s_nop 1
	v_cndmask_b32_e32 v75, 0, v75, vcc
	v_cmp_ne_u32_e32 vcc, v106, v76
	s_nop 1
	v_cndmask_b32_e32 v106, 0, v106, vcc
	v_cmp_ne_u32_e32 vcc, v78, v76
	s_nop 1
	v_cndmask_b32_e32 v78, 0, v78, vcc
	v_cmp_ne_u32_e32 vcc, v79, v76
	s_nop 1
	v_cndmask_b32_e32 v79, 0, v79, vcc
	v_cmp_ne_u32_e32 vcc, v80, v76
	s_nop 1
	v_cndmask_b32_e32 v80, 0, v80, vcc
	v_cmp_ne_u32_e32 vcc, v81, v76
	s_nop 1
	v_cndmask_b32_e32 v81, 0, v81, vcc
	v_cmp_ne_u32_e32 vcc, v104, v76
	s_nop 1
	v_cndmask_b32_e32 v104, 0, v104, vcc
	v_cmp_ne_u32_e32 vcc, v77, v76
	s_nop 1
	v_cndmask_b32_e32 v107, 0, v77, vcc
	v_max3_u32 v77, v64, v65, v66
	v_max3_u32 v77, v77, v67, v68
	v_max3_u32 v77, v77, v69, v70
	v_max3_u32 v77, v77, v72, v73
	v_max3_u32 v77, v77, v74, v75
	v_cmp_ne_u32_e32 vcc, v105, v76
	v_max3_u32 v77, v77, v106, v78
	v_max3_u32 v77, v77, v79, v80
	v_cndmask_b32_e32 v105, 0, v105, vcc
	v_cmp_ne_u32_e32 vcc, v63, v76
	v_max3_u32 v77, v77, v81, v104
	v_max3_u32 v77, v77, v107, v105
	v_cndmask_b32_e32 v63, 0, v63, vcc
	v_cmp_ne_u32_e32 vcc, v62, v76
	s_nop 1
	v_cndmask_b32_e32 v62, 0, v62, vcc
	v_max3_u32 v77, v77, v63, v62
	s_nop 1
	v_max_u32_dpp v77, v77, v77 quad_perm:[1,0,3,2] row_mask:0xf bank_mask:0xf
	s_waitcnt lgkmcnt(0)
	s_nop 1
	v_max_u32_dpp v77, v77, v77 quad_perm:[2,3,0,1] row_mask:0xf bank_mask:0xf
	s_waitcnt lgkmcnt(0)
	v_cmp_ne_u32_e32 vcc, v64, v77
	s_nop 1
	v_cndmask_b32_e32 v64, 0, v64, vcc
	v_cmp_ne_u32_e32 vcc, v65, v77
	s_nop 1
	v_cndmask_b32_e32 v65, 0, v65, vcc
	v_cmp_ne_u32_e32 vcc, v66, v77
	s_nop 1
	v_cndmask_b32_e32 v66, 0, v66, vcc
	v_cmp_ne_u32_e32 vcc, v67, v77
	s_nop 1
	v_cndmask_b32_e32 v67, 0, v67, vcc
	v_cmp_ne_u32_e32 vcc, v68, v77
	s_nop 1
	v_cndmask_b32_e32 v68, 0, v68, vcc
	v_cmp_ne_u32_e32 vcc, v69, v77
	s_nop 1
	v_cndmask_b32_e32 v69, 0, v69, vcc
	v_cmp_ne_u32_e32 vcc, v70, v77
	s_nop 1
	v_cndmask_b32_e32 v70, 0, v70, vcc
	v_cmp_ne_u32_e32 vcc, v72, v77
	s_nop 1
	v_cndmask_b32_e32 v72, 0, v72, vcc
	v_cmp_ne_u32_e32 vcc, v73, v77
	s_nop 1
	v_cndmask_b32_e32 v73, 0, v73, vcc
	v_cmp_ne_u32_e32 vcc, v74, v77
	s_nop 1
	v_cndmask_b32_e32 v74, 0, v74, vcc
	v_cmp_ne_u32_e32 vcc, v75, v77
	s_nop 1
	v_cndmask_b32_e32 v75, 0, v75, vcc
	v_cmp_ne_u32_e32 vcc, v106, v77
	s_nop 1
	v_cndmask_b32_e32 v106, 0, v106, vcc
	v_cmp_ne_u32_e32 vcc, v78, v77
	s_nop 1
	v_cndmask_b32_e32 v108, 0, v78, vcc
	v_cmp_ne_u32_e32 vcc, v79, v77
	v_max3_u32 v78, v64, v65, v66
	v_max3_u32 v78, v78, v67, v68
	v_cndmask_b32_e32 v79, 0, v79, vcc
	v_cmp_ne_u32_e32 vcc, v80, v77
	v_max3_u32 v78, v78, v69, v70
	v_max3_u32 v78, v78, v72, v73
	v_cndmask_b32_e32 v80, 0, v80, vcc
	v_cmp_ne_u32_e32 vcc, v81, v77
	v_max3_u32 v78, v78, v74, v75
	v_max3_u32 v78, v78, v106, v108
	v_cndmask_b32_e32 v81, 0, v81, vcc
	v_cmp_ne_u32_e32 vcc, v104, v77
	v_max3_u32 v78, v78, v79, v80
	s_nop 0
	v_cndmask_b32_e32 v104, 0, v104, vcc
	v_cmp_ne_u32_e32 vcc, v107, v77
	v_max3_u32 v78, v78, v81, v104
	s_nop 0
	v_cndmask_b32_e32 v107, 0, v107, vcc
	v_cmp_ne_u32_e32 vcc, v105, v77
	s_nop 1
	v_cndmask_b32_e32 v105, 0, v105, vcc
	v_cmp_ne_u32_e32 vcc, v63, v77
	v_max3_u32 v78, v78, v107, v105
	s_nop 0
	v_cndmask_b32_e32 v63, 0, v63, vcc
	v_cmp_ne_u32_e32 vcc, v62, v77
	s_nop 1
	v_cndmask_b32_e32 v62, 0, v62, vcc
	v_max3_u32 v78, v78, v63, v62
	s_nop 1
	v_max_u32_dpp v78, v78, v78 quad_perm:[1,0,3,2] row_mask:0xf bank_mask:0xf
	s_waitcnt lgkmcnt(0)
	s_nop 1
	v_max_u32_dpp v78, v78, v78 quad_perm:[2,3,0,1] row_mask:0xf bank_mask:0xf
	s_waitcnt lgkmcnt(0)
	v_cmp_ne_u32_e32 vcc, v64, v78
	s_nop 1
	v_cndmask_b32_e32 v64, 0, v64, vcc
	v_cmp_ne_u32_e32 vcc, v65, v78
	s_nop 1
	v_cndmask_b32_e32 v65, 0, v65, vcc
	v_cmp_ne_u32_e32 vcc, v66, v78
	s_nop 1
	v_cndmask_b32_e32 v66, 0, v66, vcc
	v_cmp_ne_u32_e32 vcc, v67, v78
	s_nop 1
	v_cndmask_b32_e32 v67, 0, v67, vcc
	v_cmp_ne_u32_e32 vcc, v68, v78
	s_nop 1
	v_cndmask_b32_e32 v68, 0, v68, vcc
	v_cmp_ne_u32_e32 vcc, v69, v78
	s_nop 1
	v_cndmask_b32_e32 v69, 0, v69, vcc
	v_cmp_ne_u32_e32 vcc, v70, v78
	s_nop 1
	v_cndmask_b32_e32 v70, 0, v70, vcc
	v_cmp_ne_u32_e32 vcc, v72, v78
	s_nop 1
	v_cndmask_b32_e32 v72, 0, v72, vcc
	v_cmp_ne_u32_e32 vcc, v73, v78
	s_nop 1
	v_cndmask_b32_e32 v73, 0, v73, vcc
	v_cmp_ne_u32_e32 vcc, v74, v78
	s_nop 1
	v_cndmask_b32_e32 v74, 0, v74, vcc
	v_cmp_ne_u32_e32 vcc, v75, v78
	s_nop 1
	v_cndmask_b32_e32 v75, 0, v75, vcc
	v_cmp_ne_u32_e32 vcc, v106, v78
	s_nop 1
	v_cndmask_b32_e32 v106, 0, v106, vcc
	v_cmp_ne_u32_e32 vcc, v108, v78
	s_nop 1
	v_cndmask_b32_e32 v108, 0, v108, vcc
	v_cmp_ne_u32_e32 vcc, v79, v78
	s_nop 1
	v_cndmask_b32_e32 v109, 0, v79, vcc
	v_max3_u32 v79, v64, v65, v66
	v_cmp_ne_u32_e32 vcc, v80, v78
	v_max3_u32 v79, v79, v67, v68
	v_max3_u32 v79, v79, v69, v70
	v_cndmask_b32_e32 v80, 0, v80, vcc
	v_cmp_ne_u32_e32 vcc, v81, v78
	v_max3_u32 v79, v79, v72, v73
	v_max3_u32 v79, v79, v74, v75
	v_cndmask_b32_e32 v81, 0, v81, vcc
	v_cmp_ne_u32_e32 vcc, v104, v78
	v_max3_u32 v79, v79, v106, v108
	v_max3_u32 v79, v79, v109, v80
	v_cndmask_b32_e32 v104, 0, v104, vcc
	v_cmp_ne_u32_e32 vcc, v107, v78
	v_max3_u32 v79, v79, v81, v104
	s_nop 0
	v_cndmask_b32_e32 v107, 0, v107, vcc
	v_cmp_ne_u32_e32 vcc, v105, v78
	s_nop 1
	v_cndmask_b32_e32 v105, 0, v105, vcc
	v_cmp_ne_u32_e32 vcc, v63, v78
	v_max3_u32 v79, v79, v107, v105
	s_nop 0
	v_cndmask_b32_e32 v63, 0, v63, vcc
	v_cmp_ne_u32_e32 vcc, v62, v78
	s_nop 1
	v_cndmask_b32_e32 v62, 0, v62, vcc
	v_max3_u32 v79, v79, v63, v62
	s_nop 1
	v_max_u32_dpp v79, v79, v79 quad_perm:[1,0,3,2] row_mask:0xf bank_mask:0xf
	s_waitcnt lgkmcnt(0)
	s_nop 1
	v_max_u32_dpp v79, v79, v79 quad_perm:[2,3,0,1] row_mask:0xf bank_mask:0xf
	s_waitcnt lgkmcnt(0)
	v_cmp_ne_u32_e32 vcc, v64, v79
	s_nop 1
	v_cndmask_b32_e32 v64, 0, v64, vcc
	v_cmp_ne_u32_e32 vcc, v65, v79
	s_nop 1
	v_cndmask_b32_e32 v65, 0, v65, vcc
	v_cmp_ne_u32_e32 vcc, v66, v79
	s_nop 1
	v_cndmask_b32_e32 v66, 0, v66, vcc
	v_cmp_ne_u32_e32 vcc, v67, v79
	s_nop 1
	v_cndmask_b32_e32 v67, 0, v67, vcc
	v_cmp_ne_u32_e32 vcc, v68, v79
	s_nop 1
	v_cndmask_b32_e32 v68, 0, v68, vcc
	v_cmp_ne_u32_e32 vcc, v69, v79
	s_nop 1
	v_cndmask_b32_e32 v69, 0, v69, vcc
	v_cmp_ne_u32_e32 vcc, v70, v79
	s_nop 1
	v_cndmask_b32_e32 v70, 0, v70, vcc
	v_cmp_ne_u32_e32 vcc, v72, v79
	s_nop 1
	v_cndmask_b32_e32 v72, 0, v72, vcc
	v_cmp_ne_u32_e32 vcc, v73, v79
	s_nop 1
	v_cndmask_b32_e32 v73, 0, v73, vcc
	v_cmp_ne_u32_e32 vcc, v74, v79
	s_nop 1
	v_cndmask_b32_e32 v74, 0, v74, vcc
	v_cmp_ne_u32_e32 vcc, v75, v79
	s_nop 1
	v_cndmask_b32_e32 v75, 0, v75, vcc
	v_cmp_ne_u32_e32 vcc, v106, v79
	s_nop 1
	v_cndmask_b32_e32 v106, 0, v106, vcc
	v_cmp_ne_u32_e32 vcc, v108, v79
	s_nop 1
	v_cndmask_b32_e32 v108, 0, v108, vcc
	v_cmp_ne_u32_e32 vcc, v109, v79
	s_nop 1
	v_cndmask_b32_e32 v109, 0, v109, vcc
	v_cmp_ne_u32_e32 vcc, v80, v79
	s_nop 1
	v_cndmask_b32_e32 v80, 0, v80, vcc
	v_cmp_ne_u32_e32 vcc, v81, v79
	s_nop 1
	v_cndmask_b32_e32 v81, 0, v81, vcc
	v_cmp_ne_u32_e32 vcc, v104, v79
	s_nop 1
	v_cndmask_b32_e32 v104, 0, v104, vcc
	v_cmp_ne_u32_e32 vcc, v107, v79
	s_nop 1
	v_cndmask_b32_e32 v107, 0, v107, vcc
	v_cmp_ne_u32_e32 vcc, v105, v79
	s_nop 1
	v_cndmask_b32_e32 v105, 0, v105, vcc
	v_cmp_ne_u32_e32 vcc, v63, v79
	s_nop 1
	v_cndmask_b32_e32 v63, 0, v63, vcc
	v_cmp_ne_u32_e32 vcc, v62, v79
	s_nop 1
	v_cndmask_b32_e32 v110, 0, v62, vcc
	v_max3_u32 v62, v64, v65, v66
	v_max3_u32 v62, v62, v67, v68
	v_max3_u32 v62, v62, v69, v70
	v_max3_u32 v62, v62, v72, v73
	v_max3_u32 v62, v62, v74, v75
	v_max3_u32 v62, v62, v106, v108
	v_max3_u32 v62, v62, v109, v80
	v_max3_u32 v62, v62, v81, v104
	v_max3_u32 v62, v62, v107, v105
	v_max3_u32 v62, v62, v63, v110
	s_nop 1
	v_max_u32_dpp v62, v62, v62 quad_perm:[1,0,3,2] row_mask:0xf bank_mask:0xf
	s_waitcnt lgkmcnt(0)
	s_nop 1
	v_max_u32_dpp v62, v62, v62 quad_perm:[2,3,0,1] row_mask:0xf bank_mask:0xf
	s_waitcnt lgkmcnt(0)
	v_cmp_ne_u32_e32 vcc, v64, v62
	s_nop 1
	v_cndmask_b32_e32 v64, 0, v64, vcc
	v_cmp_ne_u32_e32 vcc, v65, v62
	s_nop 1
	v_cndmask_b32_e32 v65, 0, v65, vcc
	v_cmp_ne_u32_e32 vcc, v66, v62
	s_nop 1
	v_cndmask_b32_e32 v66, 0, v66, vcc
	v_cmp_ne_u32_e32 vcc, v67, v62
	s_nop 1
	v_cndmask_b32_e32 v67, 0, v67, vcc
	v_cmp_ne_u32_e32 vcc, v68, v62
	s_nop 1
	v_cndmask_b32_e32 v68, 0, v68, vcc
	v_cmp_ne_u32_e32 vcc, v69, v62
	s_nop 1
	v_cndmask_b32_e32 v69, 0, v69, vcc
	v_cmp_ne_u32_e32 vcc, v70, v62
	s_nop 1
	v_cndmask_b32_e32 v70, 0, v70, vcc
	v_cmp_ne_u32_e32 vcc, v72, v62
	s_nop 1
	v_cndmask_b32_e32 v72, 0, v72, vcc
	v_cmp_ne_u32_e32 vcc, v73, v62
	s_nop 1
	v_cndmask_b32_e32 v73, 0, v73, vcc
	v_cmp_ne_u32_e32 vcc, v74, v62
	s_nop 1
	v_cndmask_b32_e32 v74, 0, v74, vcc
	v_cmp_ne_u32_e32 vcc, v75, v62
	s_nop 1
	v_cndmask_b32_e32 v75, 0, v75, vcc
	v_cmp_ne_u32_e32 vcc, v106, v62
	s_nop 1
	v_cndmask_b32_e32 v106, 0, v106, vcc
	v_cmp_ne_u32_e32 vcc, v108, v62
	s_nop 1
	v_cndmask_b32_e32 v108, 0, v108, vcc
	v_cmp_ne_u32_e32 vcc, v109, v62
	s_nop 1
	v_cndmask_b32_e32 v109, 0, v109, vcc
	v_cmp_ne_u32_e32 vcc, v80, v62
	s_nop 1
	v_cndmask_b32_e32 v80, 0, v80, vcc
	v_cmp_ne_u32_e32 vcc, v81, v62
	s_nop 1
	v_cndmask_b32_e32 v81, 0, v81, vcc
	v_cmp_ne_u32_e32 vcc, v104, v62
	s_nop 1
	v_cndmask_b32_e32 v104, 0, v104, vcc
	v_cmp_ne_u32_e32 vcc, v107, v62
	s_nop 1
	v_cndmask_b32_e32 v107, 0, v107, vcc
	v_cmp_ne_u32_e32 vcc, v105, v62
	s_nop 1
	v_cndmask_b32_e32 v105, 0, v105, vcc
	v_cmp_ne_u32_e32 vcc, v63, v62
	s_nop 1
	v_cndmask_b32_e32 v111, 0, v63, vcc
	v_max3_u32 v63, v64, v65, v66
	v_max3_u32 v63, v63, v67, v68
	v_max3_u32 v63, v63, v69, v70
	v_max3_u32 v63, v63, v72, v73
	v_max3_u32 v63, v63, v74, v75
	v_max3_u32 v63, v63, v106, v108
	v_max3_u32 v63, v63, v109, v80
	v_cmp_ne_u32_e32 vcc, v110, v62
	v_max3_u32 v63, v63, v81, v104
	v_max3_u32 v63, v63, v107, v105
	v_cndmask_b32_e32 v110, 0, v110, vcc
	v_max3_u32 v63, v63, v111, v110
	s_nop 1
	v_max_u32_dpp v63, v63, v63 quad_perm:[1,0,3,2] row_mask:0xf bank_mask:0xf
	s_waitcnt lgkmcnt(0)
	s_nop 1
	v_max_u32_dpp v63, v63, v63 quad_perm:[2,3,0,1] row_mask:0xf bank_mask:0xf
	s_waitcnt lgkmcnt(0)
	v_cmp_ne_u32_e32 vcc, v64, v63
	s_nop 1
	v_cndmask_b32_e32 v112, 0, v64, vcc
	v_cmp_ne_u32_e32 vcc, v65, v63
	s_nop 1
	v_cndmask_b32_e32 v65, 0, v65, vcc
	v_cmp_ne_u32_e32 vcc, v66, v63
	s_nop 1
	v_cndmask_b32_e32 v66, 0, v66, vcc
	v_cmp_ne_u32_e32 vcc, v67, v63
	v_max3_u32 v64, v112, v65, v66
	s_nop 0
	v_cndmask_b32_e32 v67, 0, v67, vcc
	v_cmp_ne_u32_e32 vcc, v68, v63
	s_nop 1
	v_cndmask_b32_e32 v68, 0, v68, vcc
	v_cmp_ne_u32_e32 vcc, v69, v63
	v_max3_u32 v64, v64, v67, v68
	s_nop 0
	v_cndmask_b32_e32 v69, 0, v69, vcc
	v_cmp_ne_u32_e32 vcc, v70, v63
	s_nop 1
	v_cndmask_b32_e32 v70, 0, v70, vcc
	v_cmp_ne_u32_e32 vcc, v72, v63
	v_max3_u32 v64, v64, v69, v70
	s_nop 0
	v_cndmask_b32_e32 v72, 0, v72, vcc
	v_cmp_ne_u32_e32 vcc, v73, v63
	s_nop 1
	v_cndmask_b32_e32 v73, 0, v73, vcc
	v_cmp_ne_u32_e32 vcc, v74, v63
	v_max3_u32 v64, v64, v72, v73
	s_nop 0
	v_cndmask_b32_e32 v74, 0, v74, vcc
	v_cmp_ne_u32_e32 vcc, v75, v63
	s_nop 1
	v_cndmask_b32_e32 v75, 0, v75, vcc
	v_cmp_ne_u32_e32 vcc, v106, v63
	v_max3_u32 v64, v64, v74, v75
	s_nop 0
	v_cndmask_b32_e32 v106, 0, v106, vcc
	v_cmp_ne_u32_e32 vcc, v108, v63
	s_nop 1
	v_cndmask_b32_e32 v108, 0, v108, vcc
	v_cmp_ne_u32_e32 vcc, v109, v63
	v_max3_u32 v64, v64, v106, v108
	s_nop 0
	v_cndmask_b32_e32 v109, 0, v109, vcc
	v_cmp_ne_u32_e32 vcc, v80, v63
	s_nop 1
	v_cndmask_b32_e32 v80, 0, v80, vcc
	v_cmp_ne_u32_e32 vcc, v81, v63
	v_max3_u32 v64, v64, v109, v80
	s_nop 0
	v_cndmask_b32_e32 v81, 0, v81, vcc
	v_cmp_ne_u32_e32 vcc, v104, v63
	s_nop 1
	v_cndmask_b32_e32 v104, 0, v104, vcc
	v_cmp_ne_u32_e32 vcc, v107, v63
	v_max3_u32 v64, v64, v81, v104
	s_nop 0
	v_cndmask_b32_e32 v107, 0, v107, vcc
	v_cmp_ne_u32_e32 vcc, v105, v63
	s_nop 1
	v_cndmask_b32_e32 v105, 0, v105, vcc
	v_cmp_ne_u32_e32 vcc, v111, v63
	v_max3_u32 v64, v64, v107, v105
	s_nop 0
	v_cndmask_b32_e32 v111, 0, v111, vcc
	v_cmp_ne_u32_e32 vcc, v110, v63
	s_nop 1
	v_cndmask_b32_e32 v110, 0, v110, vcc
	v_max3_u32 v64, v64, v111, v110
	s_nop 1
	v_max_u32_dpp v64, v64, v64 quad_perm:[1,0,3,2] row_mask:0xf bank_mask:0xf
	s_waitcnt lgkmcnt(0)
	s_nop 1
	v_max_u32_dpp v64, v64, v64 quad_perm:[2,3,0,1] row_mask:0xf bank_mask:0xf
	s_waitcnt lgkmcnt(0)
	v_cmp_ne_u32_e32 vcc, v112, v64
	s_nop 1
	v_cndmask_b32_e32 v112, 0, v112, vcc
	v_cmp_ne_u32_e32 vcc, v65, v64
	s_nop 1
	v_cndmask_b32_e32 v113, 0, v65, vcc
	v_cmp_ne_u32_e32 vcc, v66, v64
	s_nop 1
	v_cndmask_b32_e32 v66, 0, v66, vcc
	v_cmp_ne_u32_e32 vcc, v67, v64
	v_max3_u32 v65, v112, v113, v66
	s_nop 0
	v_cndmask_b32_e32 v67, 0, v67, vcc
	v_cmp_ne_u32_e32 vcc, v68, v64
	s_nop 1
	v_cndmask_b32_e32 v68, 0, v68, vcc
	v_cmp_ne_u32_e32 vcc, v69, v64
	v_max3_u32 v65, v65, v67, v68
	s_nop 0
	v_cndmask_b32_e32 v69, 0, v69, vcc
	v_cmp_ne_u32_e32 vcc, v70, v64
	s_nop 1
	v_cndmask_b32_e32 v70, 0, v70, vcc
	v_cmp_ne_u32_e32 vcc, v72, v64
	v_max3_u32 v65, v65, v69, v70
	s_nop 0
	v_cndmask_b32_e32 v72, 0, v72, vcc
	v_cmp_ne_u32_e32 vcc, v73, v64
	s_nop 1
	v_cndmask_b32_e32 v73, 0, v73, vcc
	v_cmp_ne_u32_e32 vcc, v74, v64
	v_max3_u32 v65, v65, v72, v73
	s_nop 0
	v_cndmask_b32_e32 v74, 0, v74, vcc
	v_cmp_ne_u32_e32 vcc, v75, v64
	s_nop 1
	v_cndmask_b32_e32 v75, 0, v75, vcc
	v_cmp_ne_u32_e32 vcc, v106, v64
	v_max3_u32 v65, v65, v74, v75
	s_nop 0
	v_cndmask_b32_e32 v106, 0, v106, vcc
	v_cmp_ne_u32_e32 vcc, v108, v64
	s_nop 1
	v_cndmask_b32_e32 v108, 0, v108, vcc
	v_cmp_ne_u32_e32 vcc, v109, v64
	v_max3_u32 v65, v65, v106, v108
	s_nop 0
	v_cndmask_b32_e32 v109, 0, v109, vcc
	v_cmp_ne_u32_e32 vcc, v80, v64
	s_nop 1
	v_cndmask_b32_e32 v80, 0, v80, vcc
	v_cmp_ne_u32_e32 vcc, v81, v64
	v_max3_u32 v65, v65, v109, v80
	s_nop 0
	v_cndmask_b32_e32 v81, 0, v81, vcc
	v_cmp_ne_u32_e32 vcc, v104, v64
	s_nop 1
	v_cndmask_b32_e32 v104, 0, v104, vcc
	v_cmp_ne_u32_e32 vcc, v107, v64
	v_max3_u32 v65, v65, v81, v104
	s_nop 0
	v_cndmask_b32_e32 v107, 0, v107, vcc
	v_cmp_ne_u32_e32 vcc, v105, v64
	s_nop 1
	v_cndmask_b32_e32 v105, 0, v105, vcc
	v_cmp_ne_u32_e32 vcc, v111, v64
	v_max3_u32 v65, v65, v107, v105
	s_nop 0
	v_cndmask_b32_e32 v111, 0, v111, vcc
	v_cmp_ne_u32_e32 vcc, v110, v64
	s_nop 1
	v_cndmask_b32_e32 v110, 0, v110, vcc
	v_max3_u32 v65, v65, v111, v110
	s_nop 1
	v_max_u32_dpp v65, v65, v65 quad_perm:[1,0,3,2] row_mask:0xf bank_mask:0xf
	s_waitcnt lgkmcnt(0)
	s_nop 1
	v_max_u32_dpp v65, v65, v65 quad_perm:[2,3,0,1] row_mask:0xf bank_mask:0xf
	s_waitcnt lgkmcnt(0)
	v_cmp_ne_u32_e32 vcc, v112, v65
	s_nop 1
	v_cndmask_b32_e32 v112, 0, v112, vcc
	v_cmp_ne_u32_e32 vcc, v113, v65
	s_nop 1
	v_cndmask_b32_e32 v113, 0, v113, vcc
	v_cmp_ne_u32_e32 vcc, v66, v65
	s_nop 1
	v_cndmask_b32_e32 v114, 0, v66, vcc
	v_cmp_ne_u32_e32 vcc, v67, v65
	v_max3_u32 v66, v112, v113, v114
	s_nop 0
	v_cndmask_b32_e32 v67, 0, v67, vcc
	v_cmp_ne_u32_e32 vcc, v68, v65
	s_nop 1
	v_cndmask_b32_e32 v68, 0, v68, vcc
	v_cmp_ne_u32_e32 vcc, v69, v65
	v_max3_u32 v66, v66, v67, v68
	s_nop 0
	v_cndmask_b32_e32 v69, 0, v69, vcc
	v_cmp_ne_u32_e32 vcc, v70, v65
	s_nop 1
	v_cndmask_b32_e32 v70, 0, v70, vcc
	v_cmp_ne_u32_e32 vcc, v72, v65
	v_max3_u32 v66, v66, v69, v70
	s_nop 0
	v_cndmask_b32_e32 v72, 0, v72, vcc
	v_cmp_ne_u32_e32 vcc, v73, v65
	s_nop 1
	v_cndmask_b32_e32 v73, 0, v73, vcc
	v_cmp_ne_u32_e32 vcc, v74, v65
	v_max3_u32 v66, v66, v72, v73
	s_nop 0
	v_cndmask_b32_e32 v74, 0, v74, vcc
	v_cmp_ne_u32_e32 vcc, v75, v65
	s_nop 1
	v_cndmask_b32_e32 v75, 0, v75, vcc
	v_cmp_ne_u32_e32 vcc, v106, v65
	v_max3_u32 v66, v66, v74, v75
	s_nop 0
	v_cndmask_b32_e32 v106, 0, v106, vcc
	v_cmp_ne_u32_e32 vcc, v108, v65
	s_nop 1
	v_cndmask_b32_e32 v108, 0, v108, vcc
	v_cmp_ne_u32_e32 vcc, v109, v65
	v_max3_u32 v66, v66, v106, v108
	s_nop 0
	v_cndmask_b32_e32 v109, 0, v109, vcc
	v_cmp_ne_u32_e32 vcc, v80, v65
	s_nop 1
	v_cndmask_b32_e32 v80, 0, v80, vcc
	v_cmp_ne_u32_e32 vcc, v81, v65
	v_max3_u32 v66, v66, v109, v80
	s_nop 0
	v_cndmask_b32_e32 v81, 0, v81, vcc
	v_cmp_ne_u32_e32 vcc, v104, v65
	s_nop 1
	v_cndmask_b32_e32 v104, 0, v104, vcc
	v_cmp_ne_u32_e32 vcc, v107, v65
	v_max3_u32 v66, v66, v81, v104
	s_nop 0
	v_cndmask_b32_e32 v107, 0, v107, vcc
	v_cmp_ne_u32_e32 vcc, v105, v65
	s_nop 1
	v_cndmask_b32_e32 v105, 0, v105, vcc
	v_cmp_ne_u32_e32 vcc, v111, v65
	v_max3_u32 v66, v66, v107, v105
	s_nop 0
	v_cndmask_b32_e32 v111, 0, v111, vcc
	v_cmp_ne_u32_e32 vcc, v110, v65
	s_nop 1
	v_cndmask_b32_e32 v110, 0, v110, vcc
	v_max3_u32 v66, v66, v111, v110
	s_nop 1
	v_max_u32_dpp v66, v66, v66 quad_perm:[1,0,3,2] row_mask:0xf bank_mask:0xf
	s_waitcnt lgkmcnt(0)
	s_nop 1
	v_max_u32_dpp v66, v66, v66 quad_perm:[2,3,0,1] row_mask:0xf bank_mask:0xf
	s_waitcnt lgkmcnt(0)
	v_cmp_ne_u32_e32 vcc, v112, v66
	s_nop 1
	v_cndmask_b32_e32 v112, 0, v112, vcc
	v_cmp_ne_u32_e32 vcc, v113, v66
	s_nop 1
	v_cndmask_b32_e32 v113, 0, v113, vcc
	v_cmp_ne_u32_e32 vcc, v114, v66
	s_nop 1
	v_cndmask_b32_e32 v114, 0, v114, vcc
	v_cmp_ne_u32_e32 vcc, v67, v66
	s_nop 1
	v_cndmask_b32_e32 v115, 0, v67, vcc
	v_cmp_ne_u32_e32 vcc, v68, v66
	v_max3_u32 v67, v112, v113, v114
	s_nop 0
	v_cndmask_b32_e32 v68, 0, v68, vcc
	v_cmp_ne_u32_e32 vcc, v69, v66
	v_max3_u32 v67, v67, v115, v68
	s_nop 0
	v_cndmask_b32_e32 v69, 0, v69, vcc
	v_cmp_ne_u32_e32 vcc, v70, v66
	s_nop 1
	v_cndmask_b32_e32 v70, 0, v70, vcc
	v_cmp_ne_u32_e32 vcc, v72, v66
	v_max3_u32 v67, v67, v69, v70
	s_nop 0
	v_cndmask_b32_e32 v72, 0, v72, vcc
	v_cmp_ne_u32_e32 vcc, v73, v66
	s_nop 1
	v_cndmask_b32_e32 v73, 0, v73, vcc
	v_cmp_ne_u32_e32 vcc, v74, v66
	v_max3_u32 v67, v67, v72, v73
	s_nop 0
	v_cndmask_b32_e32 v74, 0, v74, vcc
	v_cmp_ne_u32_e32 vcc, v75, v66
	s_nop 1
	v_cndmask_b32_e32 v75, 0, v75, vcc
	v_cmp_ne_u32_e32 vcc, v106, v66
	v_max3_u32 v67, v67, v74, v75
	s_nop 0
	v_cndmask_b32_e32 v106, 0, v106, vcc
	v_cmp_ne_u32_e32 vcc, v108, v66
	s_nop 1
	v_cndmask_b32_e32 v108, 0, v108, vcc
	v_cmp_ne_u32_e32 vcc, v109, v66
	v_max3_u32 v67, v67, v106, v108
	s_nop 0
	v_cndmask_b32_e32 v109, 0, v109, vcc
	v_cmp_ne_u32_e32 vcc, v80, v66
	s_nop 1
	v_cndmask_b32_e32 v80, 0, v80, vcc
	v_cmp_ne_u32_e32 vcc, v81, v66
	v_max3_u32 v67, v67, v109, v80
	s_nop 0
	v_cndmask_b32_e32 v81, 0, v81, vcc
	v_cmp_ne_u32_e32 vcc, v104, v66
	s_nop 1
	v_cndmask_b32_e32 v104, 0, v104, vcc
	v_cmp_ne_u32_e32 vcc, v107, v66
	v_max3_u32 v67, v67, v81, v104
	s_nop 0
	v_cndmask_b32_e32 v107, 0, v107, vcc
	v_cmp_ne_u32_e32 vcc, v105, v66
	s_nop 1
	v_cndmask_b32_e32 v105, 0, v105, vcc
	v_cmp_ne_u32_e32 vcc, v111, v66
	v_max3_u32 v67, v67, v107, v105
	s_nop 0
	v_cndmask_b32_e32 v111, 0, v111, vcc
	v_cmp_ne_u32_e32 vcc, v110, v66
	s_nop 1
	v_cndmask_b32_e32 v110, 0, v110, vcc
	v_max3_u32 v67, v67, v111, v110
	s_nop 1
	v_max_u32_dpp v67, v67, v67 quad_perm:[1,0,3,2] row_mask:0xf bank_mask:0xf
	s_waitcnt lgkmcnt(0)
	s_nop 1
	v_max_u32_dpp v67, v67, v67 quad_perm:[2,3,0,1] row_mask:0xf bank_mask:0xf
	s_waitcnt lgkmcnt(0)
	v_cmp_ne_u32_e32 vcc, v112, v67
	s_nop 1
	v_cndmask_b32_e32 v112, 0, v112, vcc
	v_cmp_ne_u32_e32 vcc, v113, v67
	s_nop 1
	v_cndmask_b32_e32 v113, 0, v113, vcc
	v_cmp_ne_u32_e32 vcc, v114, v67
	s_nop 1
	v_cndmask_b32_e32 v114, 0, v114, vcc
	v_cmp_ne_u32_e32 vcc, v115, v67
	s_nop 1
	v_cndmask_b32_e32 v115, 0, v115, vcc
	v_cmp_ne_u32_e32 vcc, v68, v67
	s_nop 1
	v_cndmask_b32_e32 v116, 0, v68, vcc
	v_cmp_ne_u32_e32 vcc, v69, v67
	v_max3_u32 v68, v112, v113, v114
	v_max3_u32 v68, v68, v115, v116
	v_cndmask_b32_e32 v69, 0, v69, vcc
	v_cmp_ne_u32_e32 vcc, v70, v67
	s_nop 1
	v_cndmask_b32_e32 v70, 0, v70, vcc
	v_cmp_ne_u32_e32 vcc, v72, v67
	v_max3_u32 v68, v68, v69, v70
	s_nop 0
	v_cndmask_b32_e32 v72, 0, v72, vcc
	v_cmp_ne_u32_e32 vcc, v73, v67
	s_nop 1
	v_cndmask_b32_e32 v73, 0, v73, vcc
	v_cmp_ne_u32_e32 vcc, v74, v67
	v_max3_u32 v68, v68, v72, v73
	s_nop 0
	v_cndmask_b32_e32 v74, 0, v74, vcc
	v_cmp_ne_u32_e32 vcc, v75, v67
	s_nop 1
	v_cndmask_b32_e32 v75, 0, v75, vcc
	v_cmp_ne_u32_e32 vcc, v106, v67
	v_max3_u32 v68, v68, v74, v75
	s_nop 0
	v_cndmask_b32_e32 v106, 0, v106, vcc
	v_cmp_ne_u32_e32 vcc, v108, v67
	s_nop 1
	v_cndmask_b32_e32 v108, 0, v108, vcc
	v_cmp_ne_u32_e32 vcc, v109, v67
	v_max3_u32 v68, v68, v106, v108
	s_nop 0
	v_cndmask_b32_e32 v109, 0, v109, vcc
	v_cmp_ne_u32_e32 vcc, v80, v67
	s_nop 1
	v_cndmask_b32_e32 v80, 0, v80, vcc
	v_cmp_ne_u32_e32 vcc, v81, v67
	v_max3_u32 v68, v68, v109, v80
	s_nop 0
	v_cndmask_b32_e32 v81, 0, v81, vcc
	v_cmp_ne_u32_e32 vcc, v104, v67
	s_nop 1
	v_cndmask_b32_e32 v104, 0, v104, vcc
	v_cmp_ne_u32_e32 vcc, v107, v67
	v_max3_u32 v68, v68, v81, v104
	s_nop 0
	v_cndmask_b32_e32 v107, 0, v107, vcc
	v_cmp_ne_u32_e32 vcc, v105, v67
	s_nop 1
	v_cndmask_b32_e32 v105, 0, v105, vcc
	v_cmp_ne_u32_e32 vcc, v111, v67
	v_max3_u32 v68, v68, v107, v105
	s_nop 0
	v_cndmask_b32_e32 v111, 0, v111, vcc
	v_cmp_ne_u32_e32 vcc, v110, v67
	s_nop 1
	v_cndmask_b32_e32 v110, 0, v110, vcc
	v_max3_u32 v68, v68, v111, v110
	s_nop 1
	v_max_u32_dpp v68, v68, v68 quad_perm:[1,0,3,2] row_mask:0xf bank_mask:0xf
	s_waitcnt lgkmcnt(0)
	s_nop 1
	v_max_u32_dpp v68, v68, v68 quad_perm:[2,3,0,1] row_mask:0xf bank_mask:0xf
	s_waitcnt lgkmcnt(0)
	v_cmp_ne_u32_e32 vcc, v113, v68
	s_nop 1
	v_cndmask_b32_e32 v113, 0, v113, vcc
	v_max_u32_e32 v117, v112, v113
	v_cmp_eq_u32_e32 vcc, v112, v68
	s_nop 1
	v_cndmask_b32_e32 v112, v117, v113, vcc
	v_max_u32_e32 v113, v112, v114
	v_cmp_eq_u32_e32 vcc, v114, v68
	s_nop 1
	v_cndmask_b32_e32 v112, v113, v112, vcc
	v_max_u32_e32 v113, v112, v115
	v_cmp_eq_u32_e32 vcc, v115, v68
	s_nop 1
	v_cndmask_b32_e32 v112, v113, v112, vcc
	v_max_u32_e32 v113, v112, v116
	v_cmp_eq_u32_e32 vcc, v116, v68
	s_nop 1
	v_cndmask_b32_e32 v112, v113, v112, vcc
	v_max_u32_e32 v113, v112, v69
	v_cmp_eq_u32_e32 vcc, v69, v68
	s_nop 1
	v_cndmask_b32_e32 v69, v113, v112, vcc
	v_max_u32_e32 v112, v69, v70
	v_cmp_eq_u32_e32 vcc, v70, v68
	s_nop 1
	v_cndmask_b32_e32 v69, v112, v69, vcc
	v_max_u32_e32 v70, v69, v72
	v_cmp_eq_u32_e32 vcc, v72, v68
	s_nop 1
	v_cndmask_b32_e32 v69, v70, v69, vcc
	v_max_u32_e32 v70, v69, v73
	v_cmp_eq_u32_e32 vcc, v73, v68
	s_nop 1
	v_cndmask_b32_e32 v69, v70, v69, vcc
	v_max_u32_e32 v70, v69, v74
	v_cmp_eq_u32_e32 vcc, v74, v68
	s_nop 1
	v_cndmask_b32_e32 v69, v70, v69, vcc
	v_max_u32_e32 v70, v69, v75
	v_cmp_eq_u32_e32 vcc, v75, v68
	s_nop 1
	v_cndmask_b32_e32 v69, v70, v69, vcc
	v_max_u32_e32 v70, v69, v106
	v_cmp_eq_u32_e32 vcc, v106, v68
	s_nop 1
	v_cndmask_b32_e32 v69, v70, v69, vcc
	v_max_u32_e32 v70, v69, v108
	v_cmp_eq_u32_e32 vcc, v108, v68
	s_nop 1
	v_cndmask_b32_e32 v69, v70, v69, vcc
	v_max_u32_e32 v70, v69, v109
	v_cmp_eq_u32_e32 vcc, v109, v68
	s_nop 1
	v_cndmask_b32_e32 v69, v70, v69, vcc
	v_max_u32_e32 v70, v69, v80
	v_cmp_eq_u32_e32 vcc, v80, v68
	s_nop 1
	v_cndmask_b32_e32 v69, v70, v69, vcc
	v_max_u32_e32 v70, v69, v81
	v_cmp_eq_u32_e32 vcc, v81, v68
	s_nop 1
	v_cndmask_b32_e32 v69, v70, v69, vcc
	v_max_u32_e32 v70, v69, v104
	v_cmp_eq_u32_e32 vcc, v104, v68
	s_nop 1
	v_cndmask_b32_e32 v69, v70, v69, vcc
	v_max_u32_e32 v70, v69, v107
	v_cmp_eq_u32_e32 vcc, v107, v68
	v_bitop3_b32 v107, v63, 15, v63 bitop3:0xc
	v_add_u32_e32 v107, v86, v107
	v_cndmask_b32_e32 v69, v70, v69, vcc
	v_max_u32_e32 v70, v69, v105
	v_cmp_eq_u32_e32 vcc, v105, v68
	v_bitop3_b32 v105, v62, 15, v62 bitop3:0xc
	v_add_u32_e32 v105, v86, v105
	v_cndmask_b32_e32 v69, v70, v69, vcc
	v_max_u32_e32 v70, v69, v111
	v_cmp_eq_u32_e32 vcc, v111, v68
	s_nop 1
	v_cndmask_b32_e32 v69, v70, v69, vcc
	v_max_u32_e32 v70, v69, v110
	v_cmp_eq_u32_e32 vcc, v110, v68
	s_nop 1
	v_cndmask_b32_e32 v69, v70, v69, vcc
	v_cmp_lt_i32_e32 vcc, -1, v59
	s_nop 1
	v_max_u32_dpp v69, v69, v69 quad_perm:[1,0,3,2] row_mask:0xf bank_mask:0xf
	s_waitcnt lgkmcnt(0)
	v_cndmask_b32_e64 v72, v101, -1, vcc
	v_cmp_lt_i32_e32 vcc, -1, v61
	s_nop 1
	v_mov_b32_dpp v70, v69 quad_perm:[2,3,0,1] row_mask:0xf bank_mask:0xf
	v_bitop3_b32 v72, v72, v59, s58 bitop3:0x78
	v_cndmask_b32_e64 v73, v101, -1, vcc
	v_cmp_lt_i32_e32 vcc, -1, v102
	v_bitop3_b32 v73, v73, v61, s58 bitop3:0x78
	s_nop 0
	v_cndmask_b32_e64 v74, v101, -1, vcc
	v_cmp_lt_i32_e32 vcc, -1, v103
	v_bitop3_b32 v74, v74, v102, s58 bitop3:0x78
	s_nop 0
	v_cndmask_b32_e64 v75, v101, -1, vcc
	v_cmp_lt_i32_e32 vcc, -1, v76
	v_bitop3_b32 v75, v75, v103, s58 bitop3:0x78
	s_nop 0
	v_cndmask_b32_e64 v80, v101, -1, vcc
	v_cmp_lt_i32_e32 vcc, -1, v77
	v_bitop3_b32 v80, v80, v76, s58 bitop3:0x78
	s_nop 0
	v_cndmask_b32_e64 v81, v101, -1, vcc
	v_cmp_lt_i32_e32 vcc, -1, v78
	v_bitop3_b32 v81, v81, v77, s58 bitop3:0x78
	s_nop 0
	v_cndmask_b32_e64 v104, v101, -1, vcc
	v_cmp_lt_i32_e32 vcc, -1, v79
	v_bitop3_b32 v112, v104, v78, s58 bitop3:0x78
	s_nop 0
	v_cndmask_b32_e64 v104, v101, -1, vcc
	v_cmp_lt_i32_e32 vcc, -1, v62
	v_bitop3_b32 v113, v104, v79, s58 bitop3:0x78
	v_not_b32_e32 v104, v62
	v_cndmask_b32_e64 v106, v101, -1, vcc
	v_cmp_lt_i32_e32 vcc, -1, v63
	v_bitop3_b32 v62, v106, v62, s58 bitop3:0x78
	v_not_b32_e32 v106, v63
	v_cndmask_b32_e64 v108, v101, -1, vcc
	v_bitop3_b32 v63, v108, v63, s58 bitop3:0x78
	v_not_b32_e32 v108, v64
	v_bfe_u32 v108, v108, 4, 4
	v_add_u32_e32 v114, v86, v108
	v_bitop3_b32 v108, v64, 15, v64 bitop3:0xc
	v_cmp_lt_i32_e32 vcc, -1, v64
	v_add_u32_e32 v115, v86, v108
	v_bfe_u32 v104, v104, 4, 4
	v_cndmask_b32_e64 v108, v101, -1, vcc
	v_bitop3_b32 v64, v108, v64, s58 bitop3:0x78
	v_not_b32_e32 v108, v65
	v_bfe_u32 v106, v106, 4, 4
	v_bfe_u32 v108, v108, 4, 4
	v_add_u32_e32 v104, v86, v104
	v_add_u32_e32 v106, v86, v106
	v_add_u32_e32 v116, v86, v108
	v_bitop3_b32 v108, v65, 15, v65 bitop3:0xc
	v_cmp_lt_i32_e32 vcc, -1, v65
	v_add_u32_e32 v117, v86, v108
	ds_read_u8 v110, v104
	ds_read_u8 v111, v105 offset:16
	ds_read_u8 v108, v106
	ds_read_u8 v109, v107 offset:16
	ds_read_u8 v106, v114
	ds_read_u8 v107, v115 offset:16
	ds_read_u8 v104, v116
	ds_read_u8 v105, v117 offset:16
	v_cndmask_b32_e64 v114, v101, -1, vcc
	v_cmp_lt_i32_e32 vcc, -1, v66
	v_bitop3_b32 v65, v114, v65, s58 bitop3:0x78
	v_not_b32_e32 v114, v66
	v_cndmask_b32_e64 v116, v101, -1, vcc
	v_bitop3_b32 v115, v66, 15, v66 bitop3:0xc
	v_bitop3_b32 v116, v116, v66, s58 bitop3:0x78
	v_not_b32_e32 v66, v67
	v_bfe_u32 v66, v66, 4, 4
	v_add_u32_e32 v117, v86, v66
	v_bitop3_b32 v66, v67, 15, v67 bitop3:0xc
	v_cmp_lt_i32_e32 vcc, -1, v67
	v_add_u32_e32 v127, v86, v66
	v_sub_f32_e32 v62, v62, v72
	v_cndmask_b32_e64 v66, v101, -1, vcc
	v_bitop3_b32 v118, v66, v67, s58 bitop3:0x78
	v_not_b32_e32 v66, v68
	v_bfe_u32 v66, v66, 4, 4
	v_add_u32_e32 v128, v86, v66
	v_bitop3_b32 v66, v68, 15, v68 bitop3:0xc
	v_cmp_lt_i32_e32 vcc, -1, v68
	v_add_u32_e32 v129, v86, v66
	v_mul_f32_e32 v62, 0x3fb8aa3b, v62
	v_cndmask_b32_e64 v66, v101, -1, vcc
	v_bitop3_b32 v119, v66, v68, s58 bitop3:0x78
	s_waitcnt lgkmcnt(8)
	v_max_u32_e32 v66, v69, v70
	v_not_b32_e32 v67, v66
	v_bfe_u32 v67, v67, 4, 4
	v_add_u32_e32 v70, v86, v67
	v_bitop3_b32 v67, v66, 15, v66 bitop3:0xc
	v_cmp_lt_i32_e32 vcc, -1, v66
	v_add_u32_e32 v130, v86, v67
	v_bfe_u32 v114, v114, 4, 4
	v_cndmask_b32_e64 v67, v101, -1, vcc
	v_bitop3_b32 v131, v67, v66, s58 bitop3:0x78
	v_sub_f32_e32 v66, v72, v72
	v_mul_f32_e32 v66, 0x3fb8aa3b, v66
	v_exp_f32_e32 v124, v66
	v_sub_f32_e32 v66, v73, v72
	v_mul_f32_e32 v66, 0x3fb8aa3b, v66
	v_exp_f32_e32 v123, v66
	v_sub_f32_e32 v66, v74, v72
	v_sub_f32_e32 v67, v80, v72
	v_mul_f32_e32 v66, 0x3fb8aa3b, v66
	v_mul_f32_e32 v67, 0x3fb8aa3b, v67
	v_exp_f32_e32 v125, v66
	v_sub_f32_e32 v66, v75, v72
	v_exp_f32_e32 v80, v67
	v_sub_f32_e32 v67, v81, v72
	v_mul_f32_e32 v66, 0x3fb8aa3b, v66
	v_mul_f32_e32 v67, 0x3fb8aa3b, v67
	v_exp_f32_e32 v126, v66
	v_exp_f32_e32 v120, v67
	v_sub_f32_e32 v67, v112, v72
	v_add_f32_e32 v66, 0, v124
	v_mul_f32_e32 v67, 0x3fb8aa3b, v67
	v_add_f32_e32 v66, v66, v123
	v_exp_f32_e32 v121, v67
	v_sub_f32_e32 v67, v113, v72
	v_add_f32_e32 v66, v66, v125
	v_mul_f32_e32 v67, 0x3fb8aa3b, v67
	v_add_f32_e32 v66, v66, v126
	v_exp_f32_e32 v122, v67
	v_add_f32_e32 v66, v66, v80
	v_add_f32_e32 v66, v66, v120
	v_add_f32_e32 v66, v66, v121
	v_add_f32_e32 v73, v66, v122
	v_exp_f32_e32 v66, v62
	v_sub_f32_e32 v62, v63, v72
	v_mul_f32_e32 v62, 0x3fb8aa3b, v62
	v_exp_f32_e32 v67, v62
	v_sub_f32_e32 v62, v64, v72
	v_mul_f32_e32 v62, 0x3fb8aa3b, v62
	v_exp_f32_e32 v68, v62
	v_sub_f32_e32 v62, v65, v72
	v_mul_f32_e32 v62, 0x3fb8aa3b, v62
	v_exp_f32_e32 v69, v62
	v_add_f32_e32 v62, v73, v66
	v_add_f32_e32 v62, v62, v67
	v_add_f32_e32 v62, v62, v68
	v_add_f32_e32 v73, v62, v69
	v_sub_f32_e32 v62, v116, v72
	v_mul_f32_e32 v62, 0x3fb8aa3b, v62
	v_sub_f32_e32 v63, v118, v72
	v_exp_f32_e32 v62, v62
	v_mul_f32_e32 v63, 0x3fb8aa3b, v63
	v_sub_f32_e32 v64, v119, v72
	v_exp_f32_e32 v63, v63
	v_mul_f32_e32 v64, 0x3fb8aa3b, v64
	v_sub_f32_e32 v65, v131, v72
	v_exp_f32_e32 v64, v64
	v_mul_f32_e32 v65, 0x3fb8aa3b, v65
	v_exp_f32_e32 v65, v65
	v_add_f32_e32 v72, v73, v62
	v_add_f32_e32 v72, v72, v63
	v_add_f32_e32 v72, v72, v64
	v_add_f32_e32 v73, v72, v65
	v_div_scale_f32 v74, s[28:29], v73, v73, 1.0
	v_rcp_f32_e32 v75, v74
	v_add_u32_e32 v114, v86, v114
	v_add_u32_e32 v115, v86, v115
	ds_read_u8 v118, v114
	ds_read_u8 v119, v115 offset:16
	ds_read_u8 v116, v117
	ds_read_u8 v117, v127 offset:16
	ds_read_u8 v114, v128
	ds_read_u8 v115, v129 offset:16
	ds_read_u8 v112, v70
	ds_read_u8 v113, v130 offset:16
	v_fma_f32 v70, -v74, v75, 1.0
	v_fmac_f32_e32 v75, v70, v75
	v_div_scale_f32 v70, vcc, 1.0, v73, 1.0
	v_mul_f32_e32 v81, v70, v75
	v_fma_f32 v127, -v74, v81, v70
	v_fmac_f32_e32 v81, v127, v75
	v_fma_f32 v70, -v74, v81, v70
	v_add_u32_e32 v72, s34, v82
	v_div_fmas_f32 v70, v70, v75, v81
	v_div_fixup_f32 v70, v70, v73, 1.0
	v_ashrrev_i32_e32 v73, 31, v72
	v_lshlrev_b64 v[72:73], 9, v[72:73]
	v_lshl_add_u64 v[74:75], s[20:21], 0, v[72:73]
	v_lshl_add_u64 v[72:73], s[22:23], 0, v[72:73]
	v_lshl_add_u64 v[74:75], v[74:75], 0, s[24:25]
	v_lshl_add_u64 v[72:73], v[72:73], 0, s[24:25]
	v_cmp_lt_i32_e32 vcc, 0, v83
	s_mov_b64 s[28:29], 0
	s_and_saveexec_b64 s[30:31], vcc
	s_xor_b64 s[30:31], exec, s[30:31]
	s_cbranch_execz .LBB0_847
	v_cmp_eq_u32_e32 vcc, 1, v83
	s_and_saveexec_b64 s[34:35], vcc
	s_cbranch_execz .LBB0_846
	v_not_b32_e32 v59, v79
	v_not_b32_e32 v81, v77
	v_not_b32_e32 v102, v76
	v_bfe_u32 v59, v59, 4, 4
	v_bitop3_b32 v61, v79, 15, v79 bitop3:0xc
	v_not_b32_e32 v79, v78
	v_bitop3_b32 v78, v78, 15, v78 bitop3:0xc
	v_bfe_u32 v81, v81, 4, 4
	v_bitop3_b32 v77, v77, 15, v77 bitop3:0xc
	v_bfe_u32 v102, v102, 4, 4
	v_bitop3_b32 v76, v76, 15, v76 bitop3:0xc
	v_add_u32_e32 v59, v86, v59
	v_add_u32_e32 v61, v86, v61
	v_bfe_u32 v79, v79, 4, 4
	v_add_u32_e32 v78, v86, v78
	v_add_u32_e32 v81, v86, v81
	v_add_u32_e32 v77, v86, v77
	v_add_u32_e32 v102, v86, v102
	v_add_u32_e32 v76, v86, v76
	v_add_u32_e32 v79, v86, v79
	ds_read_u8 v59, v59
	ds_read_u8 v61, v61 offset:16
	ds_read_u8 v103, v79
	ds_read_u8 v78, v78 offset:16
	ds_read_u8 v81, v81
	ds_read_u8 v77, v77 offset:16
	ds_read_u8 v102, v102
	ds_read_u8 v76, v76 offset:16
	s_waitcnt lgkmcnt(6)
	v_lshl_add_u32 v79, v59, 7, v61
	s_waitcnt lgkmcnt(4)
	v_lshl_add_u32 v78, v103, 7, v78
	s_waitcnt lgkmcnt(2)
	v_lshl_add_u32 v77, v81, 7, v77
	v_mul_f32_e32 v59, v80, v70
	s_waitcnt lgkmcnt(0)
	v_lshl_add_u32 v76, v102, 7, v76
	s_mov_b64 s[28:29], exec
	global_store_dwordx4 v[74:75], v[76:79], off offset:16
	global_store_dword v[72:73], v59, off offset:16
